# retention decay (gamma^-(t+1) on v, gamma^(t+1) on q) and the GLA 128^-0.5 scale folded into the LDS producers; consumers run plain S += v(x)k, o = S.q
# speedup vs baseline: 1.0111x; 1.0029x over previous
.Lret2_item:
	s_lshr_b32 s0, s23, 5
	s_and_b32 s1, s23, 31
	s_lshr_b32 s2, s0, 2
	s_and_b32 s3, s0, 3
	s_lshl_b32 s4, s1, 4
	v_lshl_add_u32 v46, v5, 2, s4
	s_and_b32 s4, s1, 3
	s_lshl_b32 s4, s4, 5
	s_add_u32 s4, s4, 128
	v_lshl_add_u32 v3, v5, 3, s4
	s_lshl_b32 s4, s3, 8
	s_add_u32 s4, s4, 1024
	v_lshl_add_u32 v32, v198, 2, s4
	s_add_u32 s4, s4, 4096
	v_lshl_add_u32 v33, v198, 2, s4
	s_lshl_b32 s4, s3, 9
	s_and_b32 s5, s1, 28
	s_lshl_b32 s5, s5, 4
	s_add_u32 s4, s4, s5
	s_add_u32 s4, s4, 2048
	v_min_u32_e32 v42, 31, v198
	v_lshl_add_u32 v34, v42, 2, s4
	v_cmp_lt_u32_e32 vcc, 15, v198
	v_add_u32_e32 v44, 4032, v34
	s_nop 1
	v_cndmask_b32_e32 v34, v34, v44, vcc
	v_readlane_b32 s5, v255, 15
	s_mul_i32 s4, s2, 0x1800000
	s_mul_i32 s1, s5, 0x3000
	s_add_u32 s4, s4, s1
	s_add_u32 s4, s4, 0x3bc0400
	s_add_u32 s10, s8, s4
	s_addc_u32 s11, s9, 0
	s_lshl_b32 s4, s2, 22
	s_lshl_b32 s1, s5, 11
	s_add_u32 s4, s4, s1
	s_lshl_b32 s1, s3, 9
	s_add_u32 s4, s4, s1
	s_add_u32 s4, s4, 0xfd40400
	s_add_u32 s12, s8, s4
	s_addc_u32 s13, s9, 0
	s_lshl_b32 s4, s2, 23
	s_add_u32 s4, s4, s1
	s_add_u32 s4, s4, 333188096
	s_add_u32 s14, s8, s4
	s_addc_u32 s15, s9, 0
	s_lshr_b32 s4, 0x80000, s3
	s_sub_u32 s4, 0x3f800000, s4
	v_mov_b32_e32 v28, s4
	v_mul_f32_e32 v27, v28, v28
	v_mul_f32_e32 v25, v27, v27
	v_mul_f32_e32 v26, v25, v25
	v_mov_b32_e32 v24, v28
	s_bitcmp0_b32 s5, 0
	s_cbranch_scc1 .Lret2_gw0
	v_mul_f32_e32 v24, v24, v28
.Lret2_gw0:
	s_bitcmp0_b32 s5, 1
	s_cbranch_scc1 .Lret2_gw1
	v_mul_f32_e32 v24, v24, v27
.Lret2_gw1:
	s_bitcmp0_b32 s5, 2
	s_cbranch_scc1 .Lret2_gw2
	v_mul_f32_e32 v24, v24, v25
.Lret2_gw2:
	s_mov_b32 s20, 0xffff0000
	s_mov_b32 s21, -1
	v_mov_b32_e32 v41, v26
	v_mul_f32_e32 v41, v41, v41
	v_mul_f32_e32 v41, v41, v41
	v_mul_f32_e32 v41, v41, v41
	v_mul_f32_e32 v41, v41, v41
	v_mul_f32_e32 v41, v41, v41
	v_mul_f32_e32 v41, v41, v41
	v_mul_f32_e32 v41, v41, v41
	v_mul_f32_e32 v41, v41, v41
	global_load_dword v84, v32, s[10:11]
	global_load_dword v85, v32, s[10:11] offset:-1024
	global_load_dword v86, v33, s[10:11]
	global_load_dword v87, v33, s[10:11] offset:-1024
	global_load_dword v88, v34, s[10:11]
	global_load_dword v90, v35, s[12:13]
	global_load_dword v91, v35, s[12:13] offset:4
	s_add_u32 s10, s10, 0x18000
	s_addc_u32 s11, s11, 0
	s_add_u32 s12, s12, 0x4000
	s_addc_u32 s13, s13, 0
	s_waitcnt vmcnt(0)
	v_lshlrev_b32_e32 v108, 16, v84
	v_lshlrev_b32_e32 v109, 16, v85
	v_and_b32_e32 v110, s17, v84
	v_and_b32_e32 v111, s17, v85
	v_lshlrev_b32_e32 v112, 16, v86
	v_lshlrev_b32_e32 v113, 16, v87
	v_and_b32_e32 v114, s17, v86
	v_and_b32_e32 v115, s17, v87
	v_lshlrev_b32_e32 v116, 16, v88
	v_and_b32_e32 v117, s17, v88
	v_rcp_f32_e32 v25, v24
	v_mul_f32_e32 v113, v24, v113
	v_mul_f32_e32 v115, v24, v115
	v_mul_f32_e32 v109, 0x3db504f3, v109
	v_mul_f32_e32 v111, 0x3db504f3, v111
	v_cndmask_b32_e64 v27, 1.0, v25, s[20:21]
	v_mul_f32_e32 v24, v24, v26
	v_mul_f32_e32 v116, v27, v116
	v_mul_f32_e32 v117, v27, v117
	ds_write_b128 v29, v[108:111] offset:256
	ds_write_b128 v29, v[112:115] offset:8448
	ds_write_b64 v30, v[90:91] offset:256
	ds_write_b64 v31, v[116:117] offset:256
	global_load_dword v84, v32, s[10:11]
	global_load_dword v85, v32, s[10:11] offset:-1024
	global_load_dword v86, v33, s[10:11]
	global_load_dword v87, v33, s[10:11] offset:-1024
	global_load_dword v88, v34, s[10:11]
	global_load_dword v90, v35, s[12:13]
	global_load_dword v91, v35, s[12:13] offset:4
	s_add_u32 s10, s10, 0x18000
	s_addc_u32 s11, s11, 0
	s_add_u32 s12, s12, 0x4000
	s_addc_u32 s13, s13, 0
	s_waitcnt vmcnt(0)
	v_lshlrev_b32_e32 v108, 16, v84
	v_lshlrev_b32_e32 v109, 16, v85
	v_and_b32_e32 v110, s17, v84
	v_and_b32_e32 v111, s17, v85
	v_lshlrev_b32_e32 v112, 16, v86
	v_lshlrev_b32_e32 v113, 16, v87
	v_and_b32_e32 v114, s17, v86
	v_and_b32_e32 v115, s17, v87
	v_lshlrev_b32_e32 v116, 16, v88
	v_and_b32_e32 v117, s17, v88
	v_rcp_f32_e32 v25, v24
	v_mul_f32_e32 v113, v24, v113
	v_mul_f32_e32 v115, v24, v115
	v_mul_f32_e32 v109, 0x3db504f3, v109
	v_mul_f32_e32 v111, 0x3db504f3, v111
	v_cndmask_b32_e64 v27, 1.0, v25, s[20:21]
	v_mul_f32_e32 v24, v24, v26
	v_mul_f32_e32 v116, v27, v116
	v_mul_f32_e32 v117, v27, v117
	ds_write_b128 v29, v[108:111] offset:24832
	ds_write_b128 v29, v[112:115] offset:33024
	ds_write_b64 v30, v[90:91] offset:24832
	ds_write_b64 v31, v[116:117] offset:24832
	v_add_u32_e32 v22, 0x8000, v2
	v_add_u32_e32 v23, 0x8000, v3
	v_mov_b32_e32 v6, 0
	v_mov_b32_e32 v7, 0
	v_mov_b32_e32 v8, 0
	v_mov_b32_e32 v9, 0
	v_mov_b32_e32 v10, 0
	v_mov_b32_e32 v11, 0
	v_mov_b32_e32 v12, 0
	v_mov_b32_e32 v13, 0
	v_mov_b32_e32 v14, 0
	v_mov_b32_e32 v15, 0
	v_mov_b32_e32 v16, 0
	v_mov_b32_e32 v17, 0
	v_mov_b32_e32 v18, 0
	v_mov_b32_e32 v19, 0
	v_mov_b32_e32 v20, 0
	v_mov_b32_e32 v21, 0
	s_mov_b32 s16, 0
	s_mov_b32 s2, 0x10001
	s_mov_b32 s3, 0x10001
	s_waitcnt vmcnt(0) lgkmcnt(0)
	s_barrier
	ds_read_b64 v[64:65], v3 offset:20736
	ds_read_b128 v[48:51], v2 offset:8448
	ds_read_b128 v[52:55], v2 offset:8704
	ds_read_b128 v[56:59], v2 offset:8960
	ds_read_b128 v[60:63], v2 offset:9216
.Lret2_loop:
	global_load_dword v84, v32, s[10:11]
	global_load_dword v85, v32, s[10:11] offset:-1024
	global_load_dword v86, v33, s[10:11]
	global_load_dword v87, v33, s[10:11] offset:-1024
	global_load_dword v88, v34, s[10:11]
	global_load_dword v90, v35, s[12:13]
	global_load_dword v91, v35, s[12:13] offset:4
	s_add_u32 s10, s10, 0x18000
	s_addc_u32 s11, s11, 0
	s_add_u32 s12, s12, 0x4000
	s_addc_u32 s13, s13, 0
	s_waitcnt lgkmcnt(3)
	v_pk_fma_f32 v[6:7], v[64:65], v[48:49], v[6:7] op_sel_hi:[1,0,1]
	v_pk_mul_f32 v[38:39], v[6:7], v[48:49] op_sel:[0,1] op_sel_hi:[1,1]
	v_pk_fma_f32 v[8:9], v[64:65], v[50:51], v[8:9] op_sel_hi:[1,0,1]
	v_pk_fma_f32 v[38:39], v[8:9], v[50:51], v[38:39] op_sel:[0,1,0] op_sel_hi:[1,1,1]
	s_waitcnt lgkmcnt(2)
	v_pk_fma_f32 v[10:11], v[64:65], v[52:53], v[10:11] op_sel_hi:[1,0,1]
	v_pk_fma_f32 v[38:39], v[10:11], v[52:53], v[38:39] op_sel:[0,1,0] op_sel_hi:[1,1,1]
	v_pk_fma_f32 v[12:13], v[64:65], v[54:55], v[12:13] op_sel_hi:[1,0,1]
	v_pk_fma_f32 v[38:39], v[12:13], v[54:55], v[38:39] op_sel:[0,1,0] op_sel_hi:[1,1,1]
	s_waitcnt lgkmcnt(1)
	v_pk_fma_f32 v[14:15], v[64:65], v[56:57], v[14:15] op_sel_hi:[1,0,1]
	v_pk_fma_f32 v[38:39], v[14:15], v[56:57], v[38:39] op_sel:[0,1,0] op_sel_hi:[1,1,1]
	v_pk_fma_f32 v[16:17], v[64:65], v[58:59], v[16:17] op_sel_hi:[1,0,1]
	v_pk_fma_f32 v[38:39], v[16:17], v[58:59], v[38:39] op_sel:[0,1,0] op_sel_hi:[1,1,1]
	s_waitcnt lgkmcnt(0)
	v_pk_fma_f32 v[18:19], v[64:65], v[60:61], v[18:19] op_sel_hi:[1,0,1]
	v_pk_fma_f32 v[38:39], v[18:19], v[60:61], v[38:39] op_sel:[0,1,0] op_sel_hi:[1,1,1]
	v_pk_fma_f32 v[20:21], v[64:65], v[62:63], v[20:21] op_sel_hi:[1,0,1]
	v_pk_fma_f32 v[38:39], v[20:21], v[62:63], v[38:39] op_sel:[0,1,0] op_sel_hi:[1,1,1]
	s_add_u32 s14, s14, 0x1000
	s_addc_u32 s15, s15, 0
	v_add_f32_dpp v38, v38, v38 row_ror:8 row_mask:0xf bank_mask:0x3 bound_ctrl:1
	v_add_f32_dpp v38, v39, v39 row_ror:8 row_mask:0xf bank_mask:0xc bound_ctrl:1
	ds_read_b64 v[82:83], v3 offset:20992
	ds_read_b128 v[66:69], v2 offset:9472
	v_add_f32_dpp v38, v38, v38 row_half_mirror row_mask:0xf bank_mask:0xf bound_ctrl:1
	ds_read_b128 v[70:73], v2 offset:9728
	ds_read_b128 v[74:77], v2 offset:9984
	v_add_f32_dpp v38, v38, v38 quad_perm:[1,0,3,2] row_mask:0xf bank_mask:0xf bound_ctrl:1
	ds_read_b128 v[78:81], v2 offset:10240
	s_nop 0
	v_add_f32_dpp v38, v38, v38 quad_perm:[2,3,0,1] row_mask:0xf bank_mask:0xf bound_ctrl:1
	s_nop 1
	v_mov_b32_dpp v39, v38 row_ror:8 row_mask:0xf bank_mask:0xf bound_ctrl:1
	v_cvt_pk_bf16_f32 v47, v38, v39
	s_mov_b64 exec, s[2:3]
	global_store_dword v46, v47, s[14:15] offset:-4096
	s_mov_b64 exec, -1
	s_waitcnt lgkmcnt(3)
	v_pk_fma_f32 v[6:7], v[82:83], v[66:67], v[6:7] op_sel_hi:[1,0,1]
	v_pk_mul_f32 v[38:39], v[6:7], v[66:67] op_sel:[0,1] op_sel_hi:[1,1]
	v_pk_fma_f32 v[8:9], v[82:83], v[68:69], v[8:9] op_sel_hi:[1,0,1]
	v_pk_fma_f32 v[38:39], v[8:9], v[68:69], v[38:39] op_sel:[0,1,0] op_sel_hi:[1,1,1]
	s_waitcnt lgkmcnt(2)
	v_pk_fma_f32 v[10:11], v[82:83], v[70:71], v[10:11] op_sel_hi:[1,0,1]
	v_pk_fma_f32 v[38:39], v[10:11], v[70:71], v[38:39] op_sel:[0,1,0] op_sel_hi:[1,1,1]
	v_pk_fma_f32 v[12:13], v[82:83], v[72:73], v[12:13] op_sel_hi:[1,0,1]
	v_pk_fma_f32 v[38:39], v[12:13], v[72:73], v[38:39] op_sel:[0,1,0] op_sel_hi:[1,1,1]
	s_waitcnt lgkmcnt(1)
	v_pk_fma_f32 v[14:15], v[82:83], v[74:75], v[14:15] op_sel_hi:[1,0,1]
	v_pk_fma_f32 v[38:39], v[14:15], v[74:75], v[38:39] op_sel:[0,1,0] op_sel_hi:[1,1,1]
	v_pk_fma_f32 v[16:17], v[82:83], v[76:77], v[16:17] op_sel_hi:[1,0,1]
	v_pk_fma_f32 v[38:39], v[16:17], v[76:77], v[38:39] op_sel:[0,1,0] op_sel_hi:[1,1,1]
	s_waitcnt lgkmcnt(0)
	v_pk_fma_f32 v[18:19], v[82:83], v[78:79], v[18:19] op_sel_hi:[1,0,1]
	v_pk_fma_f32 v[38:39], v[18:19], v[78:79], v[38:39] op_sel:[0,1,0] op_sel_hi:[1,1,1]
	v_pk_fma_f32 v[20:21], v[82:83], v[80:81], v[20:21] op_sel_hi:[1,0,1]
	v_pk_fma_f32 v[38:39], v[20:21], v[80:81], v[38:39] op_sel:[0,1,0] op_sel_hi:[1,1,1]
	s_add_u32 s14, s14, 0x1000
	s_addc_u32 s15, s15, 0
	v_add_f32_dpp v38, v38, v38 row_ror:8 row_mask:0xf bank_mask:0x3 bound_ctrl:1
	v_add_f32_dpp v38, v39, v39 row_ror:8 row_mask:0xf bank_mask:0xc bound_ctrl:1
	ds_read_b64 v[64:65], v3 offset:21248
	ds_read_b128 v[48:51], v2 offset:10496
	v_add_f32_dpp v38, v38, v38 row_half_mirror row_mask:0xf bank_mask:0xf bound_ctrl:1
	ds_read_b128 v[52:55], v2 offset:10752
	ds_read_b128 v[56:59], v2 offset:11008
	v_add_f32_dpp v38, v38, v38 quad_perm:[1,0,3,2] row_mask:0xf bank_mask:0xf bound_ctrl:1
	ds_read_b128 v[60:63], v2 offset:11264
	s_nop 0
	v_add_f32_dpp v38, v38, v38 quad_perm:[2,3,0,1] row_mask:0xf bank_mask:0xf bound_ctrl:1
	s_nop 1
	v_mov_b32_dpp v39, v38 row_ror:8 row_mask:0xf bank_mask:0xf bound_ctrl:1
	v_cvt_pk_bf16_f32 v47, v38, v39
	s_mov_b64 exec, s[2:3]
	global_store_dword v46, v47, s[14:15] offset:-4096
	s_mov_b64 exec, -1
	s_waitcnt lgkmcnt(3)
	v_pk_fma_f32 v[6:7], v[64:65], v[48:49], v[6:7] op_sel_hi:[1,0,1]
	v_pk_mul_f32 v[38:39], v[6:7], v[48:49] op_sel:[0,1] op_sel_hi:[1,1]
	v_pk_fma_f32 v[8:9], v[64:65], v[50:51], v[8:9] op_sel_hi:[1,0,1]
	v_pk_fma_f32 v[38:39], v[8:9], v[50:51], v[38:39] op_sel:[0,1,0] op_sel_hi:[1,1,1]
	s_waitcnt lgkmcnt(2)
	v_pk_fma_f32 v[10:11], v[64:65], v[52:53], v[10:11] op_sel_hi:[1,0,1]
	v_pk_fma_f32 v[38:39], v[10:11], v[52:53], v[38:39] op_sel:[0,1,0] op_sel_hi:[1,1,1]
	v_pk_fma_f32 v[12:13], v[64:65], v[54:55], v[12:13] op_sel_hi:[1,0,1]
	v_pk_fma_f32 v[38:39], v[12:13], v[54:55], v[38:39] op_sel:[0,1,0] op_sel_hi:[1,1,1]
	s_waitcnt lgkmcnt(1)
	v_pk_fma_f32 v[14:15], v[64:65], v[56:57], v[14:15] op_sel_hi:[1,0,1]
	v_pk_fma_f32 v[38:39], v[14:15], v[56:57], v[38:39] op_sel:[0,1,0] op_sel_hi:[1,1,1]
	v_pk_fma_f32 v[16:17], v[64:65], v[58:59], v[16:17] op_sel_hi:[1,0,1]
	v_pk_fma_f32 v[38:39], v[16:17], v[58:59], v[38:39] op_sel:[0,1,0] op_sel_hi:[1,1,1]
	s_waitcnt lgkmcnt(0)
	v_pk_fma_f32 v[18:19], v[64:65], v[60:61], v[18:19] op_sel_hi:[1,0,1]
	v_pk_fma_f32 v[38:39], v[18:19], v[60:61], v[38:39] op_sel:[0,1,0] op_sel_hi:[1,1,1]
	v_pk_fma_f32 v[20:21], v[64:65], v[62:63], v[20:21] op_sel_hi:[1,0,1]
	v_pk_fma_f32 v[38:39], v[20:21], v[62:63], v[38:39] op_sel:[0,1,0] op_sel_hi:[1,1,1]
	s_add_u32 s14, s14, 0x1000
	s_addc_u32 s15, s15, 0
	v_add_f32_dpp v38, v38, v38 row_ror:8 row_mask:0xf bank_mask:0x3 bound_ctrl:1
	v_add_f32_dpp v38, v39, v39 row_ror:8 row_mask:0xf bank_mask:0xc bound_ctrl:1
	ds_read_b64 v[82:83], v3 offset:21504
	ds_read_b128 v[66:69], v2 offset:11520
	v_add_f32_dpp v38, v38, v38 row_half_mirror row_mask:0xf bank_mask:0xf bound_ctrl:1
	ds_read_b128 v[70:73], v2 offset:11776
	ds_read_b128 v[74:77], v2 offset:12032
	v_add_f32_dpp v38, v38, v38 quad_perm:[1,0,3,2] row_mask:0xf bank_mask:0xf bound_ctrl:1
	ds_read_b128 v[78:81], v2 offset:12288
	s_nop 0
	v_add_f32_dpp v38, v38, v38 quad_perm:[2,3,0,1] row_mask:0xf bank_mask:0xf bound_ctrl:1
	s_nop 1
	v_mov_b32_dpp v39, v38 row_ror:8 row_mask:0xf bank_mask:0xf bound_ctrl:1
	v_cvt_pk_bf16_f32 v47, v38, v39
	s_mov_b64 exec, s[2:3]
	global_store_dword v46, v47, s[14:15] offset:-4096
	s_mov_b64 exec, -1
	s_waitcnt lgkmcnt(3)
	v_pk_fma_f32 v[6:7], v[82:83], v[66:67], v[6:7] op_sel_hi:[1,0,1]
	v_pk_mul_f32 v[38:39], v[6:7], v[66:67] op_sel:[0,1] op_sel_hi:[1,1]
	v_pk_fma_f32 v[8:9], v[82:83], v[68:69], v[8:9] op_sel_hi:[1,0,1]
	v_pk_fma_f32 v[38:39], v[8:9], v[68:69], v[38:39] op_sel:[0,1,0] op_sel_hi:[1,1,1]
	s_waitcnt lgkmcnt(2)
	v_pk_fma_f32 v[10:11], v[82:83], v[70:71], v[10:11] op_sel_hi:[1,0,1]
	v_pk_fma_f32 v[38:39], v[10:11], v[70:71], v[38:39] op_sel:[0,1,0] op_sel_hi:[1,1,1]
	v_pk_fma_f32 v[12:13], v[82:83], v[72:73], v[12:13] op_sel_hi:[1,0,1]
	v_pk_fma_f32 v[38:39], v[12:13], v[72:73], v[38:39] op_sel:[0,1,0] op_sel_hi:[1,1,1]
	s_waitcnt lgkmcnt(1)
	v_pk_fma_f32 v[14:15], v[82:83], v[74:75], v[14:15] op_sel_hi:[1,0,1]
	v_pk_fma_f32 v[38:39], v[14:15], v[74:75], v[38:39] op_sel:[0,1,0] op_sel_hi:[1,1,1]
	v_pk_fma_f32 v[16:17], v[82:83], v[76:77], v[16:17] op_sel_hi:[1,0,1]
	v_pk_fma_f32 v[38:39], v[16:17], v[76:77], v[38:39] op_sel:[0,1,0] op_sel_hi:[1,1,1]
	s_waitcnt lgkmcnt(0)
	v_pk_fma_f32 v[18:19], v[82:83], v[78:79], v[18:19] op_sel_hi:[1,0,1]
	v_pk_fma_f32 v[38:39], v[18:19], v[78:79], v[38:39] op_sel:[0,1,0] op_sel_hi:[1,1,1]
	v_pk_fma_f32 v[20:21], v[82:83], v[80:81], v[20:21] op_sel_hi:[1,0,1]
	v_pk_fma_f32 v[38:39], v[20:21], v[80:81], v[38:39] op_sel:[0,1,0] op_sel_hi:[1,1,1]
	s_add_u32 s14, s14, 0x1000
	s_addc_u32 s15, s15, 0
	v_add_f32_dpp v38, v38, v38 row_ror:8 row_mask:0xf bank_mask:0x3 bound_ctrl:1
	v_add_f32_dpp v38, v39, v39 row_ror:8 row_mask:0xf bank_mask:0xc bound_ctrl:1
	ds_read_b64 v[64:65], v3 offset:21760
	ds_read_b128 v[48:51], v2 offset:12544
	v_add_f32_dpp v38, v38, v38 row_half_mirror row_mask:0xf bank_mask:0xf bound_ctrl:1
	ds_read_b128 v[52:55], v2 offset:12800
	ds_read_b128 v[56:59], v2 offset:13056
	v_add_f32_dpp v38, v38, v38 quad_perm:[1,0,3,2] row_mask:0xf bank_mask:0xf bound_ctrl:1
	ds_read_b128 v[60:63], v2 offset:13312
	s_nop 0
	v_add_f32_dpp v38, v38, v38 quad_perm:[2,3,0,1] row_mask:0xf bank_mask:0xf bound_ctrl:1
	s_nop 1
	v_mov_b32_dpp v39, v38 row_ror:8 row_mask:0xf bank_mask:0xf bound_ctrl:1
	v_cvt_pk_bf16_f32 v47, v38, v39
	s_mov_b64 exec, s[2:3]
	global_store_dword v46, v47, s[14:15] offset:-4096
	s_mov_b64 exec, -1
	s_waitcnt lgkmcnt(3)
	v_pk_fma_f32 v[6:7], v[64:65], v[48:49], v[6:7] op_sel_hi:[1,0,1]
	v_pk_mul_f32 v[38:39], v[6:7], v[48:49] op_sel:[0,1] op_sel_hi:[1,1]
	v_pk_fma_f32 v[8:9], v[64:65], v[50:51], v[8:9] op_sel_hi:[1,0,1]
	v_pk_fma_f32 v[38:39], v[8:9], v[50:51], v[38:39] op_sel:[0,1,0] op_sel_hi:[1,1,1]
	s_waitcnt lgkmcnt(2)
	v_pk_fma_f32 v[10:11], v[64:65], v[52:53], v[10:11] op_sel_hi:[1,0,1]
	v_pk_fma_f32 v[38:39], v[10:11], v[52:53], v[38:39] op_sel:[0,1,0] op_sel_hi:[1,1,1]
	v_pk_fma_f32 v[12:13], v[64:65], v[54:55], v[12:13] op_sel_hi:[1,0,1]
	v_pk_fma_f32 v[38:39], v[12:13], v[54:55], v[38:39] op_sel:[0,1,0] op_sel_hi:[1,1,1]
	s_waitcnt lgkmcnt(1)
	v_pk_fma_f32 v[14:15], v[64:65], v[56:57], v[14:15] op_sel_hi:[1,0,1]
	v_pk_fma_f32 v[38:39], v[14:15], v[56:57], v[38:39] op_sel:[0,1,0] op_sel_hi:[1,1,1]
	v_pk_fma_f32 v[16:17], v[64:65], v[58:59], v[16:17] op_sel_hi:[1,0,1]
	v_pk_fma_f32 v[38:39], v[16:17], v[58:59], v[38:39] op_sel:[0,1,0] op_sel_hi:[1,1,1]
	s_waitcnt lgkmcnt(0)
	v_pk_fma_f32 v[18:19], v[64:65], v[60:61], v[18:19] op_sel_hi:[1,0,1]
	v_pk_fma_f32 v[38:39], v[18:19], v[60:61], v[38:39] op_sel:[0,1,0] op_sel_hi:[1,1,1]
	v_pk_fma_f32 v[20:21], v[64:65], v[62:63], v[20:21] op_sel_hi:[1,0,1]
	v_pk_fma_f32 v[38:39], v[20:21], v[62:63], v[38:39] op_sel:[0,1,0] op_sel_hi:[1,1,1]
	s_add_u32 s14, s14, 0x1000
	s_addc_u32 s15, s15, 0
	v_add_f32_dpp v38, v38, v38 row_ror:8 row_mask:0xf bank_mask:0x3 bound_ctrl:1
	v_add_f32_dpp v38, v39, v39 row_ror:8 row_mask:0xf bank_mask:0xc bound_ctrl:1
	ds_read_b64 v[82:83], v3 offset:22016
	ds_read_b128 v[66:69], v2 offset:13568
	v_add_f32_dpp v38, v38, v38 row_half_mirror row_mask:0xf bank_mask:0xf bound_ctrl:1
	ds_read_b128 v[70:73], v2 offset:13824
	ds_read_b128 v[74:77], v2 offset:14080
	v_add_f32_dpp v38, v38, v38 quad_perm:[1,0,3,2] row_mask:0xf bank_mask:0xf bound_ctrl:1
	ds_read_b128 v[78:81], v2 offset:14336
	s_nop 0
	v_add_f32_dpp v38, v38, v38 quad_perm:[2,3,0,1] row_mask:0xf bank_mask:0xf bound_ctrl:1
	s_nop 1
	v_mov_b32_dpp v39, v38 row_ror:8 row_mask:0xf bank_mask:0xf bound_ctrl:1
	v_cvt_pk_bf16_f32 v47, v38, v39
	s_mov_b64 exec, s[2:3]
	global_store_dword v46, v47, s[14:15] offset:-4096
	s_mov_b64 exec, -1
	s_waitcnt lgkmcnt(3)
	v_pk_fma_f32 v[6:7], v[82:83], v[66:67], v[6:7] op_sel_hi:[1,0,1]
	v_pk_mul_f32 v[38:39], v[6:7], v[66:67] op_sel:[0,1] op_sel_hi:[1,1]
	v_pk_fma_f32 v[8:9], v[82:83], v[68:69], v[8:9] op_sel_hi:[1,0,1]
	v_pk_fma_f32 v[38:39], v[8:9], v[68:69], v[38:39] op_sel:[0,1,0] op_sel_hi:[1,1,1]
	s_waitcnt lgkmcnt(2)
	v_pk_fma_f32 v[10:11], v[82:83], v[70:71], v[10:11] op_sel_hi:[1,0,1]
	v_pk_fma_f32 v[38:39], v[10:11], v[70:71], v[38:39] op_sel:[0,1,0] op_sel_hi:[1,1,1]
	v_pk_fma_f32 v[12:13], v[82:83], v[72:73], v[12:13] op_sel_hi:[1,0,1]
	v_pk_fma_f32 v[38:39], v[12:13], v[72:73], v[38:39] op_sel:[0,1,0] op_sel_hi:[1,1,1]
	s_waitcnt lgkmcnt(1)
	v_pk_fma_f32 v[14:15], v[82:83], v[74:75], v[14:15] op_sel_hi:[1,0,1]
	v_pk_fma_f32 v[38:39], v[14:15], v[74:75], v[38:39] op_sel:[0,1,0] op_sel_hi:[1,1,1]
	v_pk_fma_f32 v[16:17], v[82:83], v[76:77], v[16:17] op_sel_hi:[1,0,1]
	v_pk_fma_f32 v[38:39], v[16:17], v[76:77], v[38:39] op_sel:[0,1,0] op_sel_hi:[1,1,1]
	s_waitcnt lgkmcnt(0)
	v_pk_fma_f32 v[18:19], v[82:83], v[78:79], v[18:19] op_sel_hi:[1,0,1]
	v_pk_fma_f32 v[38:39], v[18:19], v[78:79], v[38:39] op_sel:[0,1,0] op_sel_hi:[1,1,1]
	v_pk_fma_f32 v[20:21], v[82:83], v[80:81], v[20:21] op_sel_hi:[1,0,1]
	v_pk_fma_f32 v[38:39], v[20:21], v[80:81], v[38:39] op_sel:[0,1,0] op_sel_hi:[1,1,1]
	s_add_u32 s14, s14, 0x1000
	s_addc_u32 s15, s15, 0
	v_add_f32_dpp v38, v38, v38 row_ror:8 row_mask:0xf bank_mask:0x3 bound_ctrl:1
	v_add_f32_dpp v38, v39, v39 row_ror:8 row_mask:0xf bank_mask:0xc bound_ctrl:1
	ds_read_b64 v[64:65], v3 offset:22272
	ds_read_b128 v[48:51], v2 offset:14592
	v_add_f32_dpp v38, v38, v38 row_half_mirror row_mask:0xf bank_mask:0xf bound_ctrl:1
	ds_read_b128 v[52:55], v2 offset:14848
	ds_read_b128 v[56:59], v2 offset:15104
	v_add_f32_dpp v38, v38, v38 quad_perm:[1,0,3,2] row_mask:0xf bank_mask:0xf bound_ctrl:1
	ds_read_b128 v[60:63], v2 offset:15360
	s_nop 0
	v_add_f32_dpp v38, v38, v38 quad_perm:[2,3,0,1] row_mask:0xf bank_mask:0xf bound_ctrl:1
	s_nop 1
	v_mov_b32_dpp v39, v38 row_ror:8 row_mask:0xf bank_mask:0xf bound_ctrl:1
	v_cvt_pk_bf16_f32 v47, v38, v39
	s_mov_b64 exec, s[2:3]
	global_store_dword v46, v47, s[14:15] offset:-4096
	s_mov_b64 exec, -1
	s_waitcnt lgkmcnt(3)
	v_pk_fma_f32 v[6:7], v[64:65], v[48:49], v[6:7] op_sel_hi:[1,0,1]
	v_pk_mul_f32 v[38:39], v[6:7], v[48:49] op_sel:[0,1] op_sel_hi:[1,1]
	v_pk_fma_f32 v[8:9], v[64:65], v[50:51], v[8:9] op_sel_hi:[1,0,1]
	v_pk_fma_f32 v[38:39], v[8:9], v[50:51], v[38:39] op_sel:[0,1,0] op_sel_hi:[1,1,1]
	s_waitcnt lgkmcnt(2)
	v_pk_fma_f32 v[10:11], v[64:65], v[52:53], v[10:11] op_sel_hi:[1,0,1]
	v_pk_fma_f32 v[38:39], v[10:11], v[52:53], v[38:39] op_sel:[0,1,0] op_sel_hi:[1,1,1]
	v_pk_fma_f32 v[12:13], v[64:65], v[54:55], v[12:13] op_sel_hi:[1,0,1]
	v_pk_fma_f32 v[38:39], v[12:13], v[54:55], v[38:39] op_sel:[0,1,0] op_sel_hi:[1,1,1]
	s_waitcnt lgkmcnt(1)
	v_pk_fma_f32 v[14:15], v[64:65], v[56:57], v[14:15] op_sel_hi:[1,0,1]
	v_pk_fma_f32 v[38:39], v[14:15], v[56:57], v[38:39] op_sel:[0,1,0] op_sel_hi:[1,1,1]
	v_pk_fma_f32 v[16:17], v[64:65], v[58:59], v[16:17] op_sel_hi:[1,0,1]
	v_pk_fma_f32 v[38:39], v[16:17], v[58:59], v[38:39] op_sel:[0,1,0] op_sel_hi:[1,1,1]
	s_waitcnt lgkmcnt(0)
	v_pk_fma_f32 v[18:19], v[64:65], v[60:61], v[18:19] op_sel_hi:[1,0,1]
	v_pk_fma_f32 v[38:39], v[18:19], v[60:61], v[38:39] op_sel:[0,1,0] op_sel_hi:[1,1,1]
	v_pk_fma_f32 v[20:21], v[64:65], v[62:63], v[20:21] op_sel_hi:[1,0,1]
	v_pk_fma_f32 v[38:39], v[20:21], v[62:63], v[38:39] op_sel:[0,1,0] op_sel_hi:[1,1,1]
	s_add_u32 s14, s14, 0x1000
	s_addc_u32 s15, s15, 0
	v_add_f32_dpp v38, v38, v38 row_ror:8 row_mask:0xf bank_mask:0x3 bound_ctrl:1
	v_add_f32_dpp v38, v39, v39 row_ror:8 row_mask:0xf bank_mask:0xc bound_ctrl:1
	ds_read_b64 v[82:83], v3 offset:22528
	ds_read_b128 v[66:69], v2 offset:15616
	v_add_f32_dpp v38, v38, v38 row_half_mirror row_mask:0xf bank_mask:0xf bound_ctrl:1
	ds_read_b128 v[70:73], v2 offset:15872
	ds_read_b128 v[74:77], v2 offset:16128
	v_add_f32_dpp v38, v38, v38 quad_perm:[1,0,3,2] row_mask:0xf bank_mask:0xf bound_ctrl:1
	ds_read_b128 v[78:81], v2 offset:16384
	s_nop 0
	v_add_f32_dpp v38, v38, v38 quad_perm:[2,3,0,1] row_mask:0xf bank_mask:0xf bound_ctrl:1
	s_nop 1
	v_mov_b32_dpp v39, v38 row_ror:8 row_mask:0xf bank_mask:0xf bound_ctrl:1
	v_cvt_pk_bf16_f32 v47, v38, v39
	s_mov_b64 exec, s[2:3]
	global_store_dword v46, v47, s[14:15] offset:-4096
	s_mov_b64 exec, -1
	s_waitcnt lgkmcnt(3)
	v_pk_fma_f32 v[6:7], v[82:83], v[66:67], v[6:7] op_sel_hi:[1,0,1]
	v_pk_mul_f32 v[38:39], v[6:7], v[66:67] op_sel:[0,1] op_sel_hi:[1,1]
	v_pk_fma_f32 v[8:9], v[82:83], v[68:69], v[8:9] op_sel_hi:[1,0,1]
	v_pk_fma_f32 v[38:39], v[8:9], v[68:69], v[38:39] op_sel:[0,1,0] op_sel_hi:[1,1,1]
	s_waitcnt lgkmcnt(2)
	v_pk_fma_f32 v[10:11], v[82:83], v[70:71], v[10:11] op_sel_hi:[1,0,1]
	v_pk_fma_f32 v[38:39], v[10:11], v[70:71], v[38:39] op_sel:[0,1,0] op_sel_hi:[1,1,1]
	v_pk_fma_f32 v[12:13], v[82:83], v[72:73], v[12:13] op_sel_hi:[1,0,1]
	v_pk_fma_f32 v[38:39], v[12:13], v[72:73], v[38:39] op_sel:[0,1,0] op_sel_hi:[1,1,1]
	s_waitcnt lgkmcnt(1)
	v_pk_fma_f32 v[14:15], v[82:83], v[74:75], v[14:15] op_sel_hi:[1,0,1]
	v_pk_fma_f32 v[38:39], v[14:15], v[74:75], v[38:39] op_sel:[0,1,0] op_sel_hi:[1,1,1]
	v_pk_fma_f32 v[16:17], v[82:83], v[76:77], v[16:17] op_sel_hi:[1,0,1]
	v_pk_fma_f32 v[38:39], v[16:17], v[76:77], v[38:39] op_sel:[0,1,0] op_sel_hi:[1,1,1]
	s_waitcnt lgkmcnt(0)
	v_pk_fma_f32 v[18:19], v[82:83], v[78:79], v[18:19] op_sel_hi:[1,0,1]
	v_pk_fma_f32 v[38:39], v[18:19], v[78:79], v[38:39] op_sel:[0,1,0] op_sel_hi:[1,1,1]
	v_pk_fma_f32 v[20:21], v[82:83], v[80:81], v[20:21] op_sel_hi:[1,0,1]
	v_pk_fma_f32 v[38:39], v[20:21], v[80:81], v[38:39] op_sel:[0,1,0] op_sel_hi:[1,1,1]
	s_add_u32 s14, s14, 0x1000
	s_addc_u32 s15, s15, 0
	v_add_f32_dpp v38, v38, v38 row_ror:8 row_mask:0xf bank_mask:0x3 bound_ctrl:1
	v_add_f32_dpp v38, v39, v39 row_ror:8 row_mask:0xf bank_mask:0xc bound_ctrl:1
	ds_read_b64 v[64:65], v3 offset:45312
	ds_read_b128 v[48:51], v2 offset:33024
	v_add_f32_dpp v38, v38, v38 row_half_mirror row_mask:0xf bank_mask:0xf bound_ctrl:1
	ds_read_b128 v[52:55], v2 offset:33280
	ds_read_b128 v[56:59], v2 offset:33536
	v_add_f32_dpp v38, v38, v38 quad_perm:[1,0,3,2] row_mask:0xf bank_mask:0xf bound_ctrl:1
	ds_read_b128 v[60:63], v2 offset:33792
	s_nop 0
	v_add_f32_dpp v38, v38, v38 quad_perm:[2,3,0,1] row_mask:0xf bank_mask:0xf bound_ctrl:1
	s_nop 1
	v_mov_b32_dpp v39, v38 row_ror:8 row_mask:0xf bank_mask:0xf bound_ctrl:1
	v_cvt_pk_bf16_f32 v47, v38, v39
	s_mov_b64 exec, s[2:3]
	global_store_dword v46, v47, s[14:15] offset:-4096
	s_mov_b64 exec, -1
	s_waitcnt vmcnt(8)
	v_lshlrev_b32_e32 v108, 16, v84
	v_lshlrev_b32_e32 v109, 16, v85
	v_and_b32_e32 v110, s17, v84
	v_and_b32_e32 v111, s17, v85
	v_lshlrev_b32_e32 v112, 16, v86
	v_lshlrev_b32_e32 v113, 16, v87
	v_and_b32_e32 v114, s17, v86
	v_and_b32_e32 v115, s17, v87
	v_lshlrev_b32_e32 v116, 16, v88
	v_and_b32_e32 v117, s17, v88
	v_rcp_f32_e32 v25, v24
	v_mul_f32_e32 v113, v24, v113
	v_mul_f32_e32 v115, v24, v115
	v_mul_f32_e32 v109, 0x3db504f3, v109
	v_mul_f32_e32 v111, 0x3db504f3, v111
	v_cndmask_b32_e64 v27, 1.0, v25, s[20:21]
	v_mul_f32_e32 v24, v24, v26
	v_mul_f32_e32 v116, v27, v116
	v_mul_f32_e32 v117, v27, v117
	ds_write_b128 v29, v[108:111] offset:49408
	ds_write_b128 v29, v[112:115] offset:57600
	ds_write_b64 v30, v[90:91] offset:49408
	ds_write_b64 v31, v[116:117] offset:49408
	s_add_i32 s16, s16, 8
	s_waitcnt lgkmcnt(0)
	s_barrier
	s_cmpk_lt_u32 s16, 0x800
	s_cbranch_scc0 .Lret2_done
	global_load_dword v84, v32, s[10:11]
	global_load_dword v85, v32, s[10:11] offset:-1024
	global_load_dword v86, v33, s[10:11]
	global_load_dword v87, v33, s[10:11] offset:-1024
	global_load_dword v88, v34, s[10:11]
	global_load_dword v90, v35, s[12:13]
	global_load_dword v91, v35, s[12:13] offset:4
	s_add_u32 s10, s10, 0x18000
	s_addc_u32 s11, s11, 0
	s_add_u32 s12, s12, 0x4000
	s_addc_u32 s13, s13, 0
	s_waitcnt lgkmcnt(3)
	v_pk_fma_f32 v[6:7], v[64:65], v[48:49], v[6:7] op_sel_hi:[1,0,1]
	v_pk_mul_f32 v[38:39], v[6:7], v[48:49] op_sel:[0,1] op_sel_hi:[1,1]
	v_pk_fma_f32 v[8:9], v[64:65], v[50:51], v[8:9] op_sel_hi:[1,0,1]
	v_pk_fma_f32 v[38:39], v[8:9], v[50:51], v[38:39] op_sel:[0,1,0] op_sel_hi:[1,1,1]
	s_waitcnt lgkmcnt(2)
	v_pk_fma_f32 v[10:11], v[64:65], v[52:53], v[10:11] op_sel_hi:[1,0,1]
	v_pk_fma_f32 v[38:39], v[10:11], v[52:53], v[38:39] op_sel:[0,1,0] op_sel_hi:[1,1,1]
	v_pk_fma_f32 v[12:13], v[64:65], v[54:55], v[12:13] op_sel_hi:[1,0,1]
	v_pk_fma_f32 v[38:39], v[12:13], v[54:55], v[38:39] op_sel:[0,1,0] op_sel_hi:[1,1,1]
	s_waitcnt lgkmcnt(1)
	v_pk_fma_f32 v[14:15], v[64:65], v[56:57], v[14:15] op_sel_hi:[1,0,1]
	v_pk_fma_f32 v[38:39], v[14:15], v[56:57], v[38:39] op_sel:[0,1,0] op_sel_hi:[1,1,1]
	v_pk_fma_f32 v[16:17], v[64:65], v[58:59], v[16:17] op_sel_hi:[1,0,1]
	v_pk_fma_f32 v[38:39], v[16:17], v[58:59], v[38:39] op_sel:[0,1,0] op_sel_hi:[1,1,1]
	s_waitcnt lgkmcnt(0)
	v_pk_fma_f32 v[18:19], v[64:65], v[60:61], v[18:19] op_sel_hi:[1,0,1]
	v_pk_fma_f32 v[38:39], v[18:19], v[60:61], v[38:39] op_sel:[0,1,0] op_sel_hi:[1,1,1]
	v_pk_fma_f32 v[20:21], v[64:65], v[62:63], v[20:21] op_sel_hi:[1,0,1]
	v_pk_fma_f32 v[38:39], v[20:21], v[62:63], v[38:39] op_sel:[0,1,0] op_sel_hi:[1,1,1]
	s_add_u32 s14, s14, 0x1000
	s_addc_u32 s15, s15, 0
	v_add_f32_dpp v38, v38, v38 row_ror:8 row_mask:0xf bank_mask:0x3 bound_ctrl:1
	v_add_f32_dpp v38, v39, v39 row_ror:8 row_mask:0xf bank_mask:0xc bound_ctrl:1
	ds_read_b64 v[82:83], v3 offset:45568
	ds_read_b128 v[66:69], v2 offset:34048
	v_add_f32_dpp v38, v38, v38 row_half_mirror row_mask:0xf bank_mask:0xf bound_ctrl:1
	ds_read_b128 v[70:73], v2 offset:34304
	ds_read_b128 v[74:77], v2 offset:34560
	v_add_f32_dpp v38, v38, v38 quad_perm:[1,0,3,2] row_mask:0xf bank_mask:0xf bound_ctrl:1
	ds_read_b128 v[78:81], v2 offset:34816
	s_nop 0
	v_add_f32_dpp v38, v38, v38 quad_perm:[2,3,0,1] row_mask:0xf bank_mask:0xf bound_ctrl:1
	s_nop 1
	v_mov_b32_dpp v39, v38 row_ror:8 row_mask:0xf bank_mask:0xf bound_ctrl:1
	v_cvt_pk_bf16_f32 v47, v38, v39
	s_mov_b64 exec, s[2:3]
	global_store_dword v46, v47, s[14:15] offset:-4096
	s_mov_b64 exec, -1
	s_waitcnt lgkmcnt(3)
	v_pk_fma_f32 v[6:7], v[82:83], v[66:67], v[6:7] op_sel_hi:[1,0,1]
	v_pk_mul_f32 v[38:39], v[6:7], v[66:67] op_sel:[0,1] op_sel_hi:[1,1]
	v_pk_fma_f32 v[8:9], v[82:83], v[68:69], v[8:9] op_sel_hi:[1,0,1]
	v_pk_fma_f32 v[38:39], v[8:9], v[68:69], v[38:39] op_sel:[0,1,0] op_sel_hi:[1,1,1]
	s_waitcnt lgkmcnt(2)
	v_pk_fma_f32 v[10:11], v[82:83], v[70:71], v[10:11] op_sel_hi:[1,0,1]
	v_pk_fma_f32 v[38:39], v[10:11], v[70:71], v[38:39] op_sel:[0,1,0] op_sel_hi:[1,1,1]
	v_pk_fma_f32 v[12:13], v[82:83], v[72:73], v[12:13] op_sel_hi:[1,0,1]
	v_pk_fma_f32 v[38:39], v[12:13], v[72:73], v[38:39] op_sel:[0,1,0] op_sel_hi:[1,1,1]
	s_waitcnt lgkmcnt(1)
	v_pk_fma_f32 v[14:15], v[82:83], v[74:75], v[14:15] op_sel_hi:[1,0,1]
	v_pk_fma_f32 v[38:39], v[14:15], v[74:75], v[38:39] op_sel:[0,1,0] op_sel_hi:[1,1,1]
	v_pk_fma_f32 v[16:17], v[82:83], v[76:77], v[16:17] op_sel_hi:[1,0,1]
	v_pk_fma_f32 v[38:39], v[16:17], v[76:77], v[38:39] op_sel:[0,1,0] op_sel_hi:[1,1,1]
	s_waitcnt lgkmcnt(0)
	v_pk_fma_f32 v[18:19], v[82:83], v[78:79], v[18:19] op_sel_hi:[1,0,1]
	v_pk_fma_f32 v[38:39], v[18:19], v[78:79], v[38:39] op_sel:[0,1,0] op_sel_hi:[1,1,1]
	v_pk_fma_f32 v[20:21], v[82:83], v[80:81], v[20:21] op_sel_hi:[1,0,1]
	v_pk_fma_f32 v[38:39], v[20:21], v[80:81], v[38:39] op_sel:[0,1,0] op_sel_hi:[1,1,1]
	s_add_u32 s14, s14, 0x1000
	s_addc_u32 s15, s15, 0
	v_add_f32_dpp v38, v38, v38 row_ror:8 row_mask:0xf bank_mask:0x3 bound_ctrl:1
	v_add_f32_dpp v38, v39, v39 row_ror:8 row_mask:0xf bank_mask:0xc bound_ctrl:1
	ds_read_b64 v[64:65], v3 offset:45824
	ds_read_b128 v[48:51], v2 offset:35072
	v_add_f32_dpp v38, v38, v38 row_half_mirror row_mask:0xf bank_mask:0xf bound_ctrl:1
	ds_read_b128 v[52:55], v2 offset:35328
	ds_read_b128 v[56:59], v2 offset:35584
	v_add_f32_dpp v38, v38, v38 quad_perm:[1,0,3,2] row_mask:0xf bank_mask:0xf bound_ctrl:1
	ds_read_b128 v[60:63], v2 offset:35840
	s_nop 0
	v_add_f32_dpp v38, v38, v38 quad_perm:[2,3,0,1] row_mask:0xf bank_mask:0xf bound_ctrl:1
	s_nop 1
	v_mov_b32_dpp v39, v38 row_ror:8 row_mask:0xf bank_mask:0xf bound_ctrl:1
	v_cvt_pk_bf16_f32 v47, v38, v39
	s_mov_b64 exec, s[2:3]
	global_store_dword v46, v47, s[14:15] offset:-4096
	s_mov_b64 exec, -1
	s_waitcnt lgkmcnt(3)
	v_pk_fma_f32 v[6:7], v[64:65], v[48:49], v[6:7] op_sel_hi:[1,0,1]
	v_pk_mul_f32 v[38:39], v[6:7], v[48:49] op_sel:[0,1] op_sel_hi:[1,1]
	v_pk_fma_f32 v[8:9], v[64:65], v[50:51], v[8:9] op_sel_hi:[1,0,1]
	v_pk_fma_f32 v[38:39], v[8:9], v[50:51], v[38:39] op_sel:[0,1,0] op_sel_hi:[1,1,1]
	s_waitcnt lgkmcnt(2)
	v_pk_fma_f32 v[10:11], v[64:65], v[52:53], v[10:11] op_sel_hi:[1,0,1]
	v_pk_fma_f32 v[38:39], v[10:11], v[52:53], v[38:39] op_sel:[0,1,0] op_sel_hi:[1,1,1]
	v_pk_fma_f32 v[12:13], v[64:65], v[54:55], v[12:13] op_sel_hi:[1,0,1]
	v_pk_fma_f32 v[38:39], v[12:13], v[54:55], v[38:39] op_sel:[0,1,0] op_sel_hi:[1,1,1]
	s_waitcnt lgkmcnt(1)
	v_pk_fma_f32 v[14:15], v[64:65], v[56:57], v[14:15] op_sel_hi:[1,0,1]
	v_pk_fma_f32 v[38:39], v[14:15], v[56:57], v[38:39] op_sel:[0,1,0] op_sel_hi:[1,1,1]
	v_pk_fma_f32 v[16:17], v[64:65], v[58:59], v[16:17] op_sel_hi:[1,0,1]
	v_pk_fma_f32 v[38:39], v[16:17], v[58:59], v[38:39] op_sel:[0,1,0] op_sel_hi:[1,1,1]
	s_waitcnt lgkmcnt(0)
	v_pk_fma_f32 v[18:19], v[64:65], v[60:61], v[18:19] op_sel_hi:[1,0,1]
	v_pk_fma_f32 v[38:39], v[18:19], v[60:61], v[38:39] op_sel:[0,1,0] op_sel_hi:[1,1,1]
	v_pk_fma_f32 v[20:21], v[64:65], v[62:63], v[20:21] op_sel_hi:[1,0,1]
	v_pk_fma_f32 v[38:39], v[20:21], v[62:63], v[38:39] op_sel:[0,1,0] op_sel_hi:[1,1,1]
	s_add_u32 s14, s14, 0x1000
	s_addc_u32 s15, s15, 0
	v_add_f32_dpp v38, v38, v38 row_ror:8 row_mask:0xf bank_mask:0x3 bound_ctrl:1
	v_add_f32_dpp v38, v39, v39 row_ror:8 row_mask:0xf bank_mask:0xc bound_ctrl:1
	ds_read_b64 v[82:83], v3 offset:46080
	ds_read_b128 v[66:69], v2 offset:36096
	v_add_f32_dpp v38, v38, v38 row_half_mirror row_mask:0xf bank_mask:0xf bound_ctrl:1
	ds_read_b128 v[70:73], v2 offset:36352
	ds_read_b128 v[74:77], v2 offset:36608
	v_add_f32_dpp v38, v38, v38 quad_perm:[1,0,3,2] row_mask:0xf bank_mask:0xf bound_ctrl:1
	ds_read_b128 v[78:81], v2 offset:36864
	s_nop 0
	v_add_f32_dpp v38, v38, v38 quad_perm:[2,3,0,1] row_mask:0xf bank_mask:0xf bound_ctrl:1
	s_nop 1
	v_mov_b32_dpp v39, v38 row_ror:8 row_mask:0xf bank_mask:0xf bound_ctrl:1
	v_cvt_pk_bf16_f32 v47, v38, v39
	s_mov_b64 exec, s[2:3]
	global_store_dword v46, v47, s[14:15] offset:-4096
	s_mov_b64 exec, -1
	s_waitcnt lgkmcnt(3)
	v_pk_fma_f32 v[6:7], v[82:83], v[66:67], v[6:7] op_sel_hi:[1,0,1]
	v_pk_mul_f32 v[38:39], v[6:7], v[66:67] op_sel:[0,1] op_sel_hi:[1,1]
	v_pk_fma_f32 v[8:9], v[82:83], v[68:69], v[8:9] op_sel_hi:[1,0,1]
	v_pk_fma_f32 v[38:39], v[8:9], v[68:69], v[38:39] op_sel:[0,1,0] op_sel_hi:[1,1,1]
	s_waitcnt lgkmcnt(2)
	v_pk_fma_f32 v[10:11], v[82:83], v[70:71], v[10:11] op_sel_hi:[1,0,1]
	v_pk_fma_f32 v[38:39], v[10:11], v[70:71], v[38:39] op_sel:[0,1,0] op_sel_hi:[1,1,1]
	v_pk_fma_f32 v[12:13], v[82:83], v[72:73], v[12:13] op_sel_hi:[1,0,1]
	v_pk_fma_f32 v[38:39], v[12:13], v[72:73], v[38:39] op_sel:[0,1,0] op_sel_hi:[1,1,1]
	s_waitcnt lgkmcnt(1)
	v_pk_fma_f32 v[14:15], v[82:83], v[74:75], v[14:15] op_sel_hi:[1,0,1]
	v_pk_fma_f32 v[38:39], v[14:15], v[74:75], v[38:39] op_sel:[0,1,0] op_sel_hi:[1,1,1]
	v_pk_fma_f32 v[16:17], v[82:83], v[76:77], v[16:17] op_sel_hi:[1,0,1]
	v_pk_fma_f32 v[38:39], v[16:17], v[76:77], v[38:39] op_sel:[0,1,0] op_sel_hi:[1,1,1]
	s_waitcnt lgkmcnt(0)
	v_pk_fma_f32 v[18:19], v[82:83], v[78:79], v[18:19] op_sel_hi:[1,0,1]
	v_pk_fma_f32 v[38:39], v[18:19], v[78:79], v[38:39] op_sel:[0,1,0] op_sel_hi:[1,1,1]
	v_pk_fma_f32 v[20:21], v[82:83], v[80:81], v[20:21] op_sel_hi:[1,0,1]
	v_pk_fma_f32 v[38:39], v[20:21], v[80:81], v[38:39] op_sel:[0,1,0] op_sel_hi:[1,1,1]
	s_add_u32 s14, s14, 0x1000
	s_addc_u32 s15, s15, 0
	v_add_f32_dpp v38, v38, v38 row_ror:8 row_mask:0xf bank_mask:0x3 bound_ctrl:1
	v_add_f32_dpp v38, v39, v39 row_ror:8 row_mask:0xf bank_mask:0xc bound_ctrl:1
	ds_read_b64 v[64:65], v3 offset:46336
	ds_read_b128 v[48:51], v2 offset:37120
	v_add_f32_dpp v38, v38, v38 row_half_mirror row_mask:0xf bank_mask:0xf bound_ctrl:1
	ds_read_b128 v[52:55], v2 offset:37376
	ds_read_b128 v[56:59], v2 offset:37632
	v_add_f32_dpp v38, v38, v38 quad_perm:[1,0,3,2] row_mask:0xf bank_mask:0xf bound_ctrl:1
	ds_read_b128 v[60:63], v2 offset:37888
	s_nop 0
	v_add_f32_dpp v38, v38, v38 quad_perm:[2,3,0,1] row_mask:0xf bank_mask:0xf bound_ctrl:1
	s_nop 1
	v_mov_b32_dpp v39, v38 row_ror:8 row_mask:0xf bank_mask:0xf bound_ctrl:1
	v_cvt_pk_bf16_f32 v47, v38, v39
	s_mov_b64 exec, s[2:3]
	global_store_dword v46, v47, s[14:15] offset:-4096
	s_mov_b64 exec, -1
	s_waitcnt lgkmcnt(3)
	v_pk_fma_f32 v[6:7], v[64:65], v[48:49], v[6:7] op_sel_hi:[1,0,1]
	v_pk_mul_f32 v[38:39], v[6:7], v[48:49] op_sel:[0,1] op_sel_hi:[1,1]
	v_pk_fma_f32 v[8:9], v[64:65], v[50:51], v[8:9] op_sel_hi:[1,0,1]
	v_pk_fma_f32 v[38:39], v[8:9], v[50:51], v[38:39] op_sel:[0,1,0] op_sel_hi:[1,1,1]
	s_waitcnt lgkmcnt(2)
	v_pk_fma_f32 v[10:11], v[64:65], v[52:53], v[10:11] op_sel_hi:[1,0,1]
	v_pk_fma_f32 v[38:39], v[10:11], v[52:53], v[38:39] op_sel:[0,1,0] op_sel_hi:[1,1,1]
	v_pk_fma_f32 v[12:13], v[64:65], v[54:55], v[12:13] op_sel_hi:[1,0,1]
	v_pk_fma_f32 v[38:39], v[12:13], v[54:55], v[38:39] op_sel:[0,1,0] op_sel_hi:[1,1,1]
	s_waitcnt lgkmcnt(1)
	v_pk_fma_f32 v[14:15], v[64:65], v[56:57], v[14:15] op_sel_hi:[1,0,1]
	v_pk_fma_f32 v[38:39], v[14:15], v[56:57], v[38:39] op_sel:[0,1,0] op_sel_hi:[1,1,1]
	v_pk_fma_f32 v[16:17], v[64:65], v[58:59], v[16:17] op_sel_hi:[1,0,1]
	v_pk_fma_f32 v[38:39], v[16:17], v[58:59], v[38:39] op_sel:[0,1,0] op_sel_hi:[1,1,1]
	s_waitcnt lgkmcnt(0)
	v_pk_fma_f32 v[18:19], v[64:65], v[60:61], v[18:19] op_sel_hi:[1,0,1]
	v_pk_fma_f32 v[38:39], v[18:19], v[60:61], v[38:39] op_sel:[0,1,0] op_sel_hi:[1,1,1]
	v_pk_fma_f32 v[20:21], v[64:65], v[62:63], v[20:21] op_sel_hi:[1,0,1]
	v_pk_fma_f32 v[38:39], v[20:21], v[62:63], v[38:39] op_sel:[0,1,0] op_sel_hi:[1,1,1]
	s_add_u32 s14, s14, 0x1000
	s_addc_u32 s15, s15, 0
	v_add_f32_dpp v38, v38, v38 row_ror:8 row_mask:0xf bank_mask:0x3 bound_ctrl:1
	v_add_f32_dpp v38, v39, v39 row_ror:8 row_mask:0xf bank_mask:0xc bound_ctrl:1
	ds_read_b64 v[82:83], v3 offset:46592
	ds_read_b128 v[66:69], v2 offset:38144
	v_add_f32_dpp v38, v38, v38 row_half_mirror row_mask:0xf bank_mask:0xf bound_ctrl:1
	ds_read_b128 v[70:73], v2 offset:38400
	ds_read_b128 v[74:77], v2 offset:38656
	v_add_f32_dpp v38, v38, v38 quad_perm:[1,0,3,2] row_mask:0xf bank_mask:0xf bound_ctrl:1
	ds_read_b128 v[78:81], v2 offset:38912
	s_nop 0
	v_add_f32_dpp v38, v38, v38 quad_perm:[2,3,0,1] row_mask:0xf bank_mask:0xf bound_ctrl:1
	s_nop 1
	v_mov_b32_dpp v39, v38 row_ror:8 row_mask:0xf bank_mask:0xf bound_ctrl:1
	v_cvt_pk_bf16_f32 v47, v38, v39
	s_mov_b64 exec, s[2:3]
	global_store_dword v46, v47, s[14:15] offset:-4096
	s_mov_b64 exec, -1
	s_waitcnt lgkmcnt(3)
	v_pk_fma_f32 v[6:7], v[82:83], v[66:67], v[6:7] op_sel_hi:[1,0,1]
	v_pk_mul_f32 v[38:39], v[6:7], v[66:67] op_sel:[0,1] op_sel_hi:[1,1]
	v_pk_fma_f32 v[8:9], v[82:83], v[68:69], v[8:9] op_sel_hi:[1,0,1]
	v_pk_fma_f32 v[38:39], v[8:9], v[68:69], v[38:39] op_sel:[0,1,0] op_sel_hi:[1,1,1]
	s_waitcnt lgkmcnt(2)
	v_pk_fma_f32 v[10:11], v[82:83], v[70:71], v[10:11] op_sel_hi:[1,0,1]
	v_pk_fma_f32 v[38:39], v[10:11], v[70:71], v[38:39] op_sel:[0,1,0] op_sel_hi:[1,1,1]
	v_pk_fma_f32 v[12:13], v[82:83], v[72:73], v[12:13] op_sel_hi:[1,0,1]
	v_pk_fma_f32 v[38:39], v[12:13], v[72:73], v[38:39] op_sel:[0,1,0] op_sel_hi:[1,1,1]
	s_waitcnt lgkmcnt(1)
	v_pk_fma_f32 v[14:15], v[82:83], v[74:75], v[14:15] op_sel_hi:[1,0,1]
	v_pk_fma_f32 v[38:39], v[14:15], v[74:75], v[38:39] op_sel:[0,1,0] op_sel_hi:[1,1,1]
	v_pk_fma_f32 v[16:17], v[82:83], v[76:77], v[16:17] op_sel_hi:[1,0,1]
	v_pk_fma_f32 v[38:39], v[16:17], v[76:77], v[38:39] op_sel:[0,1,0] op_sel_hi:[1,1,1]
	s_waitcnt lgkmcnt(0)
	v_pk_fma_f32 v[18:19], v[82:83], v[78:79], v[18:19] op_sel_hi:[1,0,1]
	v_pk_fma_f32 v[38:39], v[18:19], v[78:79], v[38:39] op_sel:[0,1,0] op_sel_hi:[1,1,1]
	v_pk_fma_f32 v[20:21], v[82:83], v[80:81], v[20:21] op_sel_hi:[1,0,1]
	v_pk_fma_f32 v[38:39], v[20:21], v[80:81], v[38:39] op_sel:[0,1,0] op_sel_hi:[1,1,1]
	s_add_u32 s14, s14, 0x1000
	s_addc_u32 s15, s15, 0
	v_add_f32_dpp v38, v38, v38 row_ror:8 row_mask:0xf bank_mask:0x3 bound_ctrl:1
	v_add_f32_dpp v38, v39, v39 row_ror:8 row_mask:0xf bank_mask:0xc bound_ctrl:1
	ds_read_b64 v[64:65], v3 offset:46848
	ds_read_b128 v[48:51], v2 offset:39168
	v_add_f32_dpp v38, v38, v38 row_half_mirror row_mask:0xf bank_mask:0xf bound_ctrl:1
	ds_read_b128 v[52:55], v2 offset:39424
	ds_read_b128 v[56:59], v2 offset:39680
	v_add_f32_dpp v38, v38, v38 quad_perm:[1,0,3,2] row_mask:0xf bank_mask:0xf bound_ctrl:1
	ds_read_b128 v[60:63], v2 offset:39936
	s_nop 0
	v_add_f32_dpp v38, v38, v38 quad_perm:[2,3,0,1] row_mask:0xf bank_mask:0xf bound_ctrl:1
	s_nop 1
	v_mov_b32_dpp v39, v38 row_ror:8 row_mask:0xf bank_mask:0xf bound_ctrl:1
	v_cvt_pk_bf16_f32 v47, v38, v39
	s_mov_b64 exec, s[2:3]
	global_store_dword v46, v47, s[14:15] offset:-4096
	s_mov_b64 exec, -1
	s_waitcnt lgkmcnt(3)
	v_pk_fma_f32 v[6:7], v[64:65], v[48:49], v[6:7] op_sel_hi:[1,0,1]
	v_pk_mul_f32 v[38:39], v[6:7], v[48:49] op_sel:[0,1] op_sel_hi:[1,1]
	v_pk_fma_f32 v[8:9], v[64:65], v[50:51], v[8:9] op_sel_hi:[1,0,1]
	v_pk_fma_f32 v[38:39], v[8:9], v[50:51], v[38:39] op_sel:[0,1,0] op_sel_hi:[1,1,1]
	s_waitcnt lgkmcnt(2)
	v_pk_fma_f32 v[10:11], v[64:65], v[52:53], v[10:11] op_sel_hi:[1,0,1]
	v_pk_fma_f32 v[38:39], v[10:11], v[52:53], v[38:39] op_sel:[0,1,0] op_sel_hi:[1,1,1]
	v_pk_fma_f32 v[12:13], v[64:65], v[54:55], v[12:13] op_sel_hi:[1,0,1]
	v_pk_fma_f32 v[38:39], v[12:13], v[54:55], v[38:39] op_sel:[0,1,0] op_sel_hi:[1,1,1]
	s_waitcnt lgkmcnt(1)
	v_pk_fma_f32 v[14:15], v[64:65], v[56:57], v[14:15] op_sel_hi:[1,0,1]
	v_pk_fma_f32 v[38:39], v[14:15], v[56:57], v[38:39] op_sel:[0,1,0] op_sel_hi:[1,1,1]
	v_pk_fma_f32 v[16:17], v[64:65], v[58:59], v[16:17] op_sel_hi:[1,0,1]
	v_pk_fma_f32 v[38:39], v[16:17], v[58:59], v[38:39] op_sel:[0,1,0] op_sel_hi:[1,1,1]
	s_waitcnt lgkmcnt(0)
	v_pk_fma_f32 v[18:19], v[64:65], v[60:61], v[18:19] op_sel_hi:[1,0,1]
	v_pk_fma_f32 v[38:39], v[18:19], v[60:61], v[38:39] op_sel:[0,1,0] op_sel_hi:[1,1,1]
	v_pk_fma_f32 v[20:21], v[64:65], v[62:63], v[20:21] op_sel_hi:[1,0,1]
	v_pk_fma_f32 v[38:39], v[20:21], v[62:63], v[38:39] op_sel:[0,1,0] op_sel_hi:[1,1,1]
	s_add_u32 s14, s14, 0x1000
	s_addc_u32 s15, s15, 0
	v_add_f32_dpp v38, v38, v38 row_ror:8 row_mask:0xf bank_mask:0x3 bound_ctrl:1
	v_add_f32_dpp v38, v39, v39 row_ror:8 row_mask:0xf bank_mask:0xc bound_ctrl:1
	ds_read_b64 v[82:83], v3 offset:47104
	ds_read_b128 v[66:69], v2 offset:40192
	v_add_f32_dpp v38, v38, v38 row_half_mirror row_mask:0xf bank_mask:0xf bound_ctrl:1
	ds_read_b128 v[70:73], v2 offset:40448
	ds_read_b128 v[74:77], v2 offset:40704
	v_add_f32_dpp v38, v38, v38 quad_perm:[1,0,3,2] row_mask:0xf bank_mask:0xf bound_ctrl:1
	ds_read_b128 v[78:81], v2 offset:40960
	s_nop 0
	v_add_f32_dpp v38, v38, v38 quad_perm:[2,3,0,1] row_mask:0xf bank_mask:0xf bound_ctrl:1
	s_nop 1
	v_mov_b32_dpp v39, v38 row_ror:8 row_mask:0xf bank_mask:0xf bound_ctrl:1
	v_cvt_pk_bf16_f32 v47, v38, v39
	s_mov_b64 exec, s[2:3]
	global_store_dword v46, v47, s[14:15] offset:-4096
	s_mov_b64 exec, -1
	s_waitcnt lgkmcnt(3)
	v_pk_fma_f32 v[6:7], v[82:83], v[66:67], v[6:7] op_sel_hi:[1,0,1]
	v_pk_mul_f32 v[38:39], v[6:7], v[66:67] op_sel:[0,1] op_sel_hi:[1,1]
	v_pk_fma_f32 v[8:9], v[82:83], v[68:69], v[8:9] op_sel_hi:[1,0,1]
	v_pk_fma_f32 v[38:39], v[8:9], v[68:69], v[38:39] op_sel:[0,1,0] op_sel_hi:[1,1,1]
	s_waitcnt lgkmcnt(2)
	v_pk_fma_f32 v[10:11], v[82:83], v[70:71], v[10:11] op_sel_hi:[1,0,1]
	v_pk_fma_f32 v[38:39], v[10:11], v[70:71], v[38:39] op_sel:[0,1,0] op_sel_hi:[1,1,1]
	v_pk_fma_f32 v[12:13], v[82:83], v[72:73], v[12:13] op_sel_hi:[1,0,1]
	v_pk_fma_f32 v[38:39], v[12:13], v[72:73], v[38:39] op_sel:[0,1,0] op_sel_hi:[1,1,1]
	s_waitcnt lgkmcnt(1)
	v_pk_fma_f32 v[14:15], v[82:83], v[74:75], v[14:15] op_sel_hi:[1,0,1]
	v_pk_fma_f32 v[38:39], v[14:15], v[74:75], v[38:39] op_sel:[0,1,0] op_sel_hi:[1,1,1]
	v_pk_fma_f32 v[16:17], v[82:83], v[76:77], v[16:17] op_sel_hi:[1,0,1]
	v_pk_fma_f32 v[38:39], v[16:17], v[76:77], v[38:39] op_sel:[0,1,0] op_sel_hi:[1,1,1]
	s_waitcnt lgkmcnt(0)
	v_pk_fma_f32 v[18:19], v[82:83], v[78:79], v[18:19] op_sel_hi:[1,0,1]
	v_pk_fma_f32 v[38:39], v[18:19], v[78:79], v[38:39] op_sel:[0,1,0] op_sel_hi:[1,1,1]
	v_pk_fma_f32 v[20:21], v[82:83], v[80:81], v[20:21] op_sel_hi:[1,0,1]
	v_pk_fma_f32 v[38:39], v[20:21], v[80:81], v[38:39] op_sel:[0,1,0] op_sel_hi:[1,1,1]
	s_add_u32 s14, s14, 0x1000
	s_addc_u32 s15, s15, 0
	v_add_f32_dpp v38, v38, v38 row_ror:8 row_mask:0xf bank_mask:0x3 bound_ctrl:1
	v_add_f32_dpp v38, v39, v39 row_ror:8 row_mask:0xf bank_mask:0xc bound_ctrl:1
	ds_read_b64 v[64:65], v23 offset:37120
	ds_read_b128 v[48:51], v2 offset:57600
	v_add_f32_dpp v38, v38, v38 row_half_mirror row_mask:0xf bank_mask:0xf bound_ctrl:1
	ds_read_b128 v[52:55], v2 offset:57856
	ds_read_b128 v[56:59], v2 offset:58112
	v_add_f32_dpp v38, v38, v38 quad_perm:[1,0,3,2] row_mask:0xf bank_mask:0xf bound_ctrl:1
	ds_read_b128 v[60:63], v2 offset:58368
	s_nop 0
	v_add_f32_dpp v38, v38, v38 quad_perm:[2,3,0,1] row_mask:0xf bank_mask:0xf bound_ctrl:1
	s_nop 1
	v_mov_b32_dpp v39, v38 row_ror:8 row_mask:0xf bank_mask:0xf bound_ctrl:1
	v_cvt_pk_bf16_f32 v47, v38, v39
	s_mov_b64 exec, s[2:3]
	global_store_dword v46, v47, s[14:15] offset:-4096
	s_mov_b64 exec, -1
	s_waitcnt vmcnt(8)
	v_lshlrev_b32_e32 v108, 16, v84
	v_lshlrev_b32_e32 v109, 16, v85
	v_and_b32_e32 v110, s17, v84
	v_and_b32_e32 v111, s17, v85
	v_lshlrev_b32_e32 v112, 16, v86
	v_lshlrev_b32_e32 v113, 16, v87
	v_and_b32_e32 v114, s17, v86
	v_and_b32_e32 v115, s17, v87
	v_lshlrev_b32_e32 v116, 16, v88
	v_and_b32_e32 v117, s17, v88
	v_rcp_f32_e32 v25, v24
	v_mul_f32_e32 v113, v24, v113
	v_mul_f32_e32 v115, v24, v115
	v_mul_f32_e32 v109, 0x3db504f3, v109
	v_mul_f32_e32 v111, 0x3db504f3, v111
	v_cndmask_b32_e64 v27, 1.0, v25, s[20:21]
	v_mul_f32_e32 v24, v24, v26
	v_mul_f32_e32 v116, v27, v116
	v_mul_f32_e32 v117, v27, v117
	ds_write_b128 v29, v[108:111] offset:256
	ds_write_b128 v29, v[112:115] offset:8448
	ds_write_b64 v30, v[90:91] offset:256
	ds_write_b64 v31, v[116:117] offset:256
	s_add_i32 s16, s16, 8
	s_waitcnt lgkmcnt(0)
	s_barrier
	s_cmpk_lt_u32 s16, 0x800
	s_cbranch_scc0 .Lret2_done
	global_load_dword v84, v32, s[10:11]
	global_load_dword v85, v32, s[10:11] offset:-1024
	global_load_dword v86, v33, s[10:11]
	global_load_dword v87, v33, s[10:11] offset:-1024
	global_load_dword v88, v34, s[10:11]
	global_load_dword v90, v35, s[12:13]
	global_load_dword v91, v35, s[12:13] offset:4
	s_add_u32 s10, s10, 0x18000
	s_addc_u32 s11, s11, 0
	s_add_u32 s12, s12, 0x4000
	s_addc_u32 s13, s13, 0
	s_waitcnt lgkmcnt(3)
	v_pk_fma_f32 v[6:7], v[64:65], v[48:49], v[6:7] op_sel_hi:[1,0,1]
	v_pk_mul_f32 v[38:39], v[6:7], v[48:49] op_sel:[0,1] op_sel_hi:[1,1]
	v_pk_fma_f32 v[8:9], v[64:65], v[50:51], v[8:9] op_sel_hi:[1,0,1]
	v_pk_fma_f32 v[38:39], v[8:9], v[50:51], v[38:39] op_sel:[0,1,0] op_sel_hi:[1,1,1]
	s_waitcnt lgkmcnt(2)
	v_pk_fma_f32 v[10:11], v[64:65], v[52:53], v[10:11] op_sel_hi:[1,0,1]
	v_pk_fma_f32 v[38:39], v[10:11], v[52:53], v[38:39] op_sel:[0,1,0] op_sel_hi:[1,1,1]
	v_pk_fma_f32 v[12:13], v[64:65], v[54:55], v[12:13] op_sel_hi:[1,0,1]
	v_pk_fma_f32 v[38:39], v[12:13], v[54:55], v[38:39] op_sel:[0,1,0] op_sel_hi:[1,1,1]
	s_waitcnt lgkmcnt(1)
	v_pk_fma_f32 v[14:15], v[64:65], v[56:57], v[14:15] op_sel_hi:[1,0,1]
	v_pk_fma_f32 v[38:39], v[14:15], v[56:57], v[38:39] op_sel:[0,1,0] op_sel_hi:[1,1,1]
	v_pk_fma_f32 v[16:17], v[64:65], v[58:59], v[16:17] op_sel_hi:[1,0,1]
	v_pk_fma_f32 v[38:39], v[16:17], v[58:59], v[38:39] op_sel:[0,1,0] op_sel_hi:[1,1,1]
	s_waitcnt lgkmcnt(0)
	v_pk_fma_f32 v[18:19], v[64:65], v[60:61], v[18:19] op_sel_hi:[1,0,1]
	v_pk_fma_f32 v[38:39], v[18:19], v[60:61], v[38:39] op_sel:[0,1,0] op_sel_hi:[1,1,1]
	v_pk_fma_f32 v[20:21], v[64:65], v[62:63], v[20:21] op_sel_hi:[1,0,1]
	v_pk_fma_f32 v[38:39], v[20:21], v[62:63], v[38:39] op_sel:[0,1,0] op_sel_hi:[1,1,1]
	s_add_u32 s14, s14, 0x1000
	s_addc_u32 s15, s15, 0
	v_add_f32_dpp v38, v38, v38 row_ror:8 row_mask:0xf bank_mask:0x3 bound_ctrl:1
	v_add_f32_dpp v38, v39, v39 row_ror:8 row_mask:0xf bank_mask:0xc bound_ctrl:1
	ds_read_b64 v[82:83], v23 offset:37376
	ds_read_b128 v[66:69], v2 offset:58624
	v_add_f32_dpp v38, v38, v38 row_half_mirror row_mask:0xf bank_mask:0xf bound_ctrl:1
	ds_read_b128 v[70:73], v2 offset:58880
	ds_read_b128 v[74:77], v2 offset:59136
	v_add_f32_dpp v38, v38, v38 quad_perm:[1,0,3,2] row_mask:0xf bank_mask:0xf bound_ctrl:1
	ds_read_b128 v[78:81], v2 offset:59392
	s_nop 0
	v_add_f32_dpp v38, v38, v38 quad_perm:[2,3,0,1] row_mask:0xf bank_mask:0xf bound_ctrl:1
	s_nop 1
	v_mov_b32_dpp v39, v38 row_ror:8 row_mask:0xf bank_mask:0xf bound_ctrl:1
	v_cvt_pk_bf16_f32 v47, v38, v39
	s_mov_b64 exec, s[2:3]
	global_store_dword v46, v47, s[14:15] offset:-4096
	s_mov_b64 exec, -1
	s_waitcnt lgkmcnt(3)
	v_pk_fma_f32 v[6:7], v[82:83], v[66:67], v[6:7] op_sel_hi:[1,0,1]
	v_pk_mul_f32 v[38:39], v[6:7], v[66:67] op_sel:[0,1] op_sel_hi:[1,1]
	v_pk_fma_f32 v[8:9], v[82:83], v[68:69], v[8:9] op_sel_hi:[1,0,1]
	v_pk_fma_f32 v[38:39], v[8:9], v[68:69], v[38:39] op_sel:[0,1,0] op_sel_hi:[1,1,1]
	s_waitcnt lgkmcnt(2)
	v_pk_fma_f32 v[10:11], v[82:83], v[70:71], v[10:11] op_sel_hi:[1,0,1]
	v_pk_fma_f32 v[38:39], v[10:11], v[70:71], v[38:39] op_sel:[0,1,0] op_sel_hi:[1,1,1]
	v_pk_fma_f32 v[12:13], v[82:83], v[72:73], v[12:13] op_sel_hi:[1,0,1]
	v_pk_fma_f32 v[38:39], v[12:13], v[72:73], v[38:39] op_sel:[0,1,0] op_sel_hi:[1,1,1]
	s_waitcnt lgkmcnt(1)
	v_pk_fma_f32 v[14:15], v[82:83], v[74:75], v[14:15] op_sel_hi:[1,0,1]
	v_pk_fma_f32 v[38:39], v[14:15], v[74:75], v[38:39] op_sel:[0,1,0] op_sel_hi:[1,1,1]
	v_pk_fma_f32 v[16:17], v[82:83], v[76:77], v[16:17] op_sel_hi:[1,0,1]
	v_pk_fma_f32 v[38:39], v[16:17], v[76:77], v[38:39] op_sel:[0,1,0] op_sel_hi:[1,1,1]
	s_waitcnt lgkmcnt(0)
	v_pk_fma_f32 v[18:19], v[82:83], v[78:79], v[18:19] op_sel_hi:[1,0,1]
	v_pk_fma_f32 v[38:39], v[18:19], v[78:79], v[38:39] op_sel:[0,1,0] op_sel_hi:[1,1,1]
	v_pk_fma_f32 v[20:21], v[82:83], v[80:81], v[20:21] op_sel_hi:[1,0,1]
	v_pk_fma_f32 v[38:39], v[20:21], v[80:81], v[38:39] op_sel:[0,1,0] op_sel_hi:[1,1,1]
	s_add_u32 s14, s14, 0x1000
	s_addc_u32 s15, s15, 0
	v_add_f32_dpp v38, v38, v38 row_ror:8 row_mask:0xf bank_mask:0x3 bound_ctrl:1
	v_add_f32_dpp v38, v39, v39 row_ror:8 row_mask:0xf bank_mask:0xc bound_ctrl:1
	ds_read_b64 v[64:65], v23 offset:37632
	ds_read_b128 v[48:51], v2 offset:59648
	v_add_f32_dpp v38, v38, v38 row_half_mirror row_mask:0xf bank_mask:0xf bound_ctrl:1
	ds_read_b128 v[52:55], v2 offset:59904
	ds_read_b128 v[56:59], v2 offset:60160
	v_add_f32_dpp v38, v38, v38 quad_perm:[1,0,3,2] row_mask:0xf bank_mask:0xf bound_ctrl:1
	ds_read_b128 v[60:63], v2 offset:60416
	s_nop 0
	v_add_f32_dpp v38, v38, v38 quad_perm:[2,3,0,1] row_mask:0xf bank_mask:0xf bound_ctrl:1
	s_nop 1
	v_mov_b32_dpp v39, v38 row_ror:8 row_mask:0xf bank_mask:0xf bound_ctrl:1
	v_cvt_pk_bf16_f32 v47, v38, v39
	s_mov_b64 exec, s[2:3]
	global_store_dword v46, v47, s[14:15] offset:-4096
	s_mov_b64 exec, -1
	s_waitcnt lgkmcnt(3)
	v_pk_fma_f32 v[6:7], v[64:65], v[48:49], v[6:7] op_sel_hi:[1,0,1]
	v_pk_mul_f32 v[38:39], v[6:7], v[48:49] op_sel:[0,1] op_sel_hi:[1,1]
	v_pk_fma_f32 v[8:9], v[64:65], v[50:51], v[8:9] op_sel_hi:[1,0,1]
	v_pk_fma_f32 v[38:39], v[8:9], v[50:51], v[38:39] op_sel:[0,1,0] op_sel_hi:[1,1,1]
	s_waitcnt lgkmcnt(2)
	v_pk_fma_f32 v[10:11], v[64:65], v[52:53], v[10:11] op_sel_hi:[1,0,1]
	v_pk_fma_f32 v[38:39], v[10:11], v[52:53], v[38:39] op_sel:[0,1,0] op_sel_hi:[1,1,1]
	v_pk_fma_f32 v[12:13], v[64:65], v[54:55], v[12:13] op_sel_hi:[1,0,1]
	v_pk_fma_f32 v[38:39], v[12:13], v[54:55], v[38:39] op_sel:[0,1,0] op_sel_hi:[1,1,1]
	s_waitcnt lgkmcnt(1)
	v_pk_fma_f32 v[14:15], v[64:65], v[56:57], v[14:15] op_sel_hi:[1,0,1]
	v_pk_fma_f32 v[38:39], v[14:15], v[56:57], v[38:39] op_sel:[0,1,0] op_sel_hi:[1,1,1]
	v_pk_fma_f32 v[16:17], v[64:65], v[58:59], v[16:17] op_sel_hi:[1,0,1]
	v_pk_fma_f32 v[38:39], v[16:17], v[58:59], v[38:39] op_sel:[0,1,0] op_sel_hi:[1,1,1]
	s_waitcnt lgkmcnt(0)
	v_pk_fma_f32 v[18:19], v[64:65], v[60:61], v[18:19] op_sel_hi:[1,0,1]
	v_pk_fma_f32 v[38:39], v[18:19], v[60:61], v[38:39] op_sel:[0,1,0] op_sel_hi:[1,1,1]
	v_pk_fma_f32 v[20:21], v[64:65], v[62:63], v[20:21] op_sel_hi:[1,0,1]
	v_pk_fma_f32 v[38:39], v[20:21], v[62:63], v[38:39] op_sel:[0,1,0] op_sel_hi:[1,1,1]
	s_add_u32 s14, s14, 0x1000
	s_addc_u32 s15, s15, 0
	v_add_f32_dpp v38, v38, v38 row_ror:8 row_mask:0xf bank_mask:0x3 bound_ctrl:1
	v_add_f32_dpp v38, v39, v39 row_ror:8 row_mask:0xf bank_mask:0xc bound_ctrl:1
	ds_read_b64 v[82:83], v23 offset:37888
	ds_read_b128 v[66:69], v2 offset:60672
	v_add_f32_dpp v38, v38, v38 row_half_mirror row_mask:0xf bank_mask:0xf bound_ctrl:1
	ds_read_b128 v[70:73], v2 offset:60928
	ds_read_b128 v[74:77], v2 offset:61184
	v_add_f32_dpp v38, v38, v38 quad_perm:[1,0,3,2] row_mask:0xf bank_mask:0xf bound_ctrl:1
	ds_read_b128 v[78:81], v2 offset:61440
	s_nop 0
	v_add_f32_dpp v38, v38, v38 quad_perm:[2,3,0,1] row_mask:0xf bank_mask:0xf bound_ctrl:1
	s_nop 1
	v_mov_b32_dpp v39, v38 row_ror:8 row_mask:0xf bank_mask:0xf bound_ctrl:1
	v_cvt_pk_bf16_f32 v47, v38, v39
	s_mov_b64 exec, s[2:3]
	global_store_dword v46, v47, s[14:15] offset:-4096
	s_mov_b64 exec, -1
	s_waitcnt lgkmcnt(3)
	v_pk_fma_f32 v[6:7], v[82:83], v[66:67], v[6:7] op_sel_hi:[1,0,1]
	v_pk_mul_f32 v[38:39], v[6:7], v[66:67] op_sel:[0,1] op_sel_hi:[1,1]
	v_pk_fma_f32 v[8:9], v[82:83], v[68:69], v[8:9] op_sel_hi:[1,0,1]
	v_pk_fma_f32 v[38:39], v[8:9], v[68:69], v[38:39] op_sel:[0,1,0] op_sel_hi:[1,1,1]
	s_waitcnt lgkmcnt(2)
	v_pk_fma_f32 v[10:11], v[82:83], v[70:71], v[10:11] op_sel_hi:[1,0,1]
	v_pk_fma_f32 v[38:39], v[10:11], v[70:71], v[38:39] op_sel:[0,1,0] op_sel_hi:[1,1,1]
	v_pk_fma_f32 v[12:13], v[82:83], v[72:73], v[12:13] op_sel_hi:[1,0,1]
	v_pk_fma_f32 v[38:39], v[12:13], v[72:73], v[38:39] op_sel:[0,1,0] op_sel_hi:[1,1,1]
	s_waitcnt lgkmcnt(1)
	v_pk_fma_f32 v[14:15], v[82:83], v[74:75], v[14:15] op_sel_hi:[1,0,1]
	v_pk_fma_f32 v[38:39], v[14:15], v[74:75], v[38:39] op_sel:[0,1,0] op_sel_hi:[1,1,1]
	v_pk_fma_f32 v[16:17], v[82:83], v[76:77], v[16:17] op_sel_hi:[1,0,1]
	v_pk_fma_f32 v[38:39], v[16:17], v[76:77], v[38:39] op_sel:[0,1,0] op_sel_hi:[1,1,1]
	s_waitcnt lgkmcnt(0)
	v_pk_fma_f32 v[18:19], v[82:83], v[78:79], v[18:19] op_sel_hi:[1,0,1]
	v_pk_fma_f32 v[38:39], v[18:19], v[78:79], v[38:39] op_sel:[0,1,0] op_sel_hi:[1,1,1]
	v_pk_fma_f32 v[20:21], v[82:83], v[80:81], v[20:21] op_sel_hi:[1,0,1]
	v_pk_fma_f32 v[38:39], v[20:21], v[80:81], v[38:39] op_sel:[0,1,0] op_sel_hi:[1,1,1]
	s_add_u32 s14, s14, 0x1000
	s_addc_u32 s15, s15, 0
	v_add_f32_dpp v38, v38, v38 row_ror:8 row_mask:0xf bank_mask:0x3 bound_ctrl:1
	v_add_f32_dpp v38, v39, v39 row_ror:8 row_mask:0xf bank_mask:0xc bound_ctrl:1
	ds_read_b64 v[64:65], v23 offset:38144
	ds_read_b128 v[48:51], v2 offset:61696
	v_add_f32_dpp v38, v38, v38 row_half_mirror row_mask:0xf bank_mask:0xf bound_ctrl:1
	ds_read_b128 v[52:55], v2 offset:61952
	ds_read_b128 v[56:59], v2 offset:62208
	v_add_f32_dpp v38, v38, v38 quad_perm:[1,0,3,2] row_mask:0xf bank_mask:0xf bound_ctrl:1
	ds_read_b128 v[60:63], v2 offset:62464
	s_nop 0
	v_add_f32_dpp v38, v38, v38 quad_perm:[2,3,0,1] row_mask:0xf bank_mask:0xf bound_ctrl:1
	s_nop 1
	v_mov_b32_dpp v39, v38 row_ror:8 row_mask:0xf bank_mask:0xf bound_ctrl:1
	v_cvt_pk_bf16_f32 v47, v38, v39
	s_mov_b64 exec, s[2:3]
	global_store_dword v46, v47, s[14:15] offset:-4096
	s_mov_b64 exec, -1
	s_waitcnt lgkmcnt(3)
	v_pk_fma_f32 v[6:7], v[64:65], v[48:49], v[6:7] op_sel_hi:[1,0,1]
	v_pk_mul_f32 v[38:39], v[6:7], v[48:49] op_sel:[0,1] op_sel_hi:[1,1]
	v_pk_fma_f32 v[8:9], v[64:65], v[50:51], v[8:9] op_sel_hi:[1,0,1]
	v_pk_fma_f32 v[38:39], v[8:9], v[50:51], v[38:39] op_sel:[0,1,0] op_sel_hi:[1,1,1]
	s_waitcnt lgkmcnt(2)
	v_pk_fma_f32 v[10:11], v[64:65], v[52:53], v[10:11] op_sel_hi:[1,0,1]
	v_pk_fma_f32 v[38:39], v[10:11], v[52:53], v[38:39] op_sel:[0,1,0] op_sel_hi:[1,1,1]
	v_pk_fma_f32 v[12:13], v[64:65], v[54:55], v[12:13] op_sel_hi:[1,0,1]
	v_pk_fma_f32 v[38:39], v[12:13], v[54:55], v[38:39] op_sel:[0,1,0] op_sel_hi:[1,1,1]
	s_waitcnt lgkmcnt(1)
	v_pk_fma_f32 v[14:15], v[64:65], v[56:57], v[14:15] op_sel_hi:[1,0,1]
	v_pk_fma_f32 v[38:39], v[14:15], v[56:57], v[38:39] op_sel:[0,1,0] op_sel_hi:[1,1,1]
	v_pk_fma_f32 v[16:17], v[64:65], v[58:59], v[16:17] op_sel_hi:[1,0,1]
	v_pk_fma_f32 v[38:39], v[16:17], v[58:59], v[38:39] op_sel:[0,1,0] op_sel_hi:[1,1,1]
	s_waitcnt lgkmcnt(0)
	v_pk_fma_f32 v[18:19], v[64:65], v[60:61], v[18:19] op_sel_hi:[1,0,1]
	v_pk_fma_f32 v[38:39], v[18:19], v[60:61], v[38:39] op_sel:[0,1,0] op_sel_hi:[1,1,1]
	v_pk_fma_f32 v[20:21], v[64:65], v[62:63], v[20:21] op_sel_hi:[1,0,1]
	v_pk_fma_f32 v[38:39], v[20:21], v[62:63], v[38:39] op_sel:[0,1,0] op_sel_hi:[1,1,1]
	s_add_u32 s14, s14, 0x1000
	s_addc_u32 s15, s15, 0
	v_add_f32_dpp v38, v38, v38 row_ror:8 row_mask:0xf bank_mask:0x3 bound_ctrl:1
	v_add_f32_dpp v38, v39, v39 row_ror:8 row_mask:0xf bank_mask:0xc bound_ctrl:1
	ds_read_b64 v[82:83], v23 offset:38400
	ds_read_b128 v[66:69], v2 offset:62720
	v_add_f32_dpp v38, v38, v38 row_half_mirror row_mask:0xf bank_mask:0xf bound_ctrl:1
	ds_read_b128 v[70:73], v2 offset:62976
	ds_read_b128 v[74:77], v2 offset:63232
	v_add_f32_dpp v38, v38, v38 quad_perm:[1,0,3,2] row_mask:0xf bank_mask:0xf bound_ctrl:1
	ds_read_b128 v[78:81], v2 offset:63488
	s_nop 0
	v_add_f32_dpp v38, v38, v38 quad_perm:[2,3,0,1] row_mask:0xf bank_mask:0xf bound_ctrl:1
	s_nop 1
	v_mov_b32_dpp v39, v38 row_ror:8 row_mask:0xf bank_mask:0xf bound_ctrl:1
	v_cvt_pk_bf16_f32 v47, v38, v39
	s_mov_b64 exec, s[2:3]
	global_store_dword v46, v47, s[14:15] offset:-4096
	s_mov_b64 exec, -1
	s_waitcnt lgkmcnt(3)
	v_pk_fma_f32 v[6:7], v[82:83], v[66:67], v[6:7] op_sel_hi:[1,0,1]
	v_pk_mul_f32 v[38:39], v[6:7], v[66:67] op_sel:[0,1] op_sel_hi:[1,1]
	v_pk_fma_f32 v[8:9], v[82:83], v[68:69], v[8:9] op_sel_hi:[1,0,1]
	v_pk_fma_f32 v[38:39], v[8:9], v[68:69], v[38:39] op_sel:[0,1,0] op_sel_hi:[1,1,1]
	s_waitcnt lgkmcnt(2)
	v_pk_fma_f32 v[10:11], v[82:83], v[70:71], v[10:11] op_sel_hi:[1,0,1]
	v_pk_fma_f32 v[38:39], v[10:11], v[70:71], v[38:39] op_sel:[0,1,0] op_sel_hi:[1,1,1]
	v_pk_fma_f32 v[12:13], v[82:83], v[72:73], v[12:13] op_sel_hi:[1,0,1]
	v_pk_fma_f32 v[38:39], v[12:13], v[72:73], v[38:39] op_sel:[0,1,0] op_sel_hi:[1,1,1]
	s_waitcnt lgkmcnt(1)
	v_pk_fma_f32 v[14:15], v[82:83], v[74:75], v[14:15] op_sel_hi:[1,0,1]
	v_pk_fma_f32 v[38:39], v[14:15], v[74:75], v[38:39] op_sel:[0,1,0] op_sel_hi:[1,1,1]
	v_pk_fma_f32 v[16:17], v[82:83], v[76:77], v[16:17] op_sel_hi:[1,0,1]
	v_pk_fma_f32 v[38:39], v[16:17], v[76:77], v[38:39] op_sel:[0,1,0] op_sel_hi:[1,1,1]
	s_waitcnt lgkmcnt(0)
	v_pk_fma_f32 v[18:19], v[82:83], v[78:79], v[18:19] op_sel_hi:[1,0,1]
	v_pk_fma_f32 v[38:39], v[18:19], v[78:79], v[38:39] op_sel:[0,1,0] op_sel_hi:[1,1,1]
	v_pk_fma_f32 v[20:21], v[82:83], v[80:81], v[20:21] op_sel_hi:[1,0,1]
	v_pk_fma_f32 v[38:39], v[20:21], v[80:81], v[38:39] op_sel:[0,1,0] op_sel_hi:[1,1,1]
	s_add_u32 s14, s14, 0x1000
	s_addc_u32 s15, s15, 0
	v_add_f32_dpp v38, v38, v38 row_ror:8 row_mask:0xf bank_mask:0x3 bound_ctrl:1
	v_add_f32_dpp v38, v39, v39 row_ror:8 row_mask:0xf bank_mask:0xc bound_ctrl:1
	ds_read_b64 v[64:65], v23 offset:38656
	ds_read_b128 v[48:51], v2 offset:63744
	v_add_f32_dpp v38, v38, v38 row_half_mirror row_mask:0xf bank_mask:0xf bound_ctrl:1
	ds_read_b128 v[52:55], v2 offset:64000
	ds_read_b128 v[56:59], v2 offset:64256
	v_add_f32_dpp v38, v38, v38 quad_perm:[1,0,3,2] row_mask:0xf bank_mask:0xf bound_ctrl:1
	ds_read_b128 v[60:63], v2 offset:64512
	s_nop 0
	v_add_f32_dpp v38, v38, v38 quad_perm:[2,3,0,1] row_mask:0xf bank_mask:0xf bound_ctrl:1
	s_nop 1
	v_mov_b32_dpp v39, v38 row_ror:8 row_mask:0xf bank_mask:0xf bound_ctrl:1
	v_cvt_pk_bf16_f32 v47, v38, v39
	s_mov_b64 exec, s[2:3]
	global_store_dword v46, v47, s[14:15] offset:-4096
	s_mov_b64 exec, -1
	s_waitcnt lgkmcnt(3)
	v_pk_fma_f32 v[6:7], v[64:65], v[48:49], v[6:7] op_sel_hi:[1,0,1]
	v_pk_mul_f32 v[38:39], v[6:7], v[48:49] op_sel:[0,1] op_sel_hi:[1,1]
	v_pk_fma_f32 v[8:9], v[64:65], v[50:51], v[8:9] op_sel_hi:[1,0,1]
	v_pk_fma_f32 v[38:39], v[8:9], v[50:51], v[38:39] op_sel:[0,1,0] op_sel_hi:[1,1,1]
	s_waitcnt lgkmcnt(2)
	v_pk_fma_f32 v[10:11], v[64:65], v[52:53], v[10:11] op_sel_hi:[1,0,1]
	v_pk_fma_f32 v[38:39], v[10:11], v[52:53], v[38:39] op_sel:[0,1,0] op_sel_hi:[1,1,1]
	v_pk_fma_f32 v[12:13], v[64:65], v[54:55], v[12:13] op_sel_hi:[1,0,1]
	v_pk_fma_f32 v[38:39], v[12:13], v[54:55], v[38:39] op_sel:[0,1,0] op_sel_hi:[1,1,1]
	s_waitcnt lgkmcnt(1)
	v_pk_fma_f32 v[14:15], v[64:65], v[56:57], v[14:15] op_sel_hi:[1,0,1]
	v_pk_fma_f32 v[38:39], v[14:15], v[56:57], v[38:39] op_sel:[0,1,0] op_sel_hi:[1,1,1]
	v_pk_fma_f32 v[16:17], v[64:65], v[58:59], v[16:17] op_sel_hi:[1,0,1]
	v_pk_fma_f32 v[38:39], v[16:17], v[58:59], v[38:39] op_sel:[0,1,0] op_sel_hi:[1,1,1]
	s_waitcnt lgkmcnt(0)
	v_pk_fma_f32 v[18:19], v[64:65], v[60:61], v[18:19] op_sel_hi:[1,0,1]
	v_pk_fma_f32 v[38:39], v[18:19], v[60:61], v[38:39] op_sel:[0,1,0] op_sel_hi:[1,1,1]
	v_pk_fma_f32 v[20:21], v[64:65], v[62:63], v[20:21] op_sel_hi:[1,0,1]
	v_pk_fma_f32 v[38:39], v[20:21], v[62:63], v[38:39] op_sel:[0,1,0] op_sel_hi:[1,1,1]
	s_add_u32 s14, s14, 0x1000
	s_addc_u32 s15, s15, 0
	v_add_f32_dpp v38, v38, v38 row_ror:8 row_mask:0xf bank_mask:0x3 bound_ctrl:1
	v_add_f32_dpp v38, v39, v39 row_ror:8 row_mask:0xf bank_mask:0xc bound_ctrl:1
	ds_read_b64 v[82:83], v23 offset:38912
	ds_read_b128 v[66:69], v2 offset:64768
	v_add_f32_dpp v38, v38, v38 row_half_mirror row_mask:0xf bank_mask:0xf bound_ctrl:1
	ds_read_b128 v[70:73], v2 offset:65024
	ds_read_b128 v[74:77], v2 offset:65280
	v_add_f32_dpp v38, v38, v38 quad_perm:[1,0,3,2] row_mask:0xf bank_mask:0xf bound_ctrl:1
	ds_read_b128 v[78:81], v22 offset:32768
	s_nop 0
	v_add_f32_dpp v38, v38, v38 quad_perm:[2,3,0,1] row_mask:0xf bank_mask:0xf bound_ctrl:1
	s_nop 1
	v_mov_b32_dpp v39, v38 row_ror:8 row_mask:0xf bank_mask:0xf bound_ctrl:1
	v_cvt_pk_bf16_f32 v47, v38, v39
	s_mov_b64 exec, s[2:3]
	global_store_dword v46, v47, s[14:15] offset:-4096
	s_mov_b64 exec, -1
	s_waitcnt lgkmcnt(3)
	v_pk_fma_f32 v[6:7], v[82:83], v[66:67], v[6:7] op_sel_hi:[1,0,1]
	v_pk_mul_f32 v[38:39], v[6:7], v[66:67] op_sel:[0,1] op_sel_hi:[1,1]
	v_pk_fma_f32 v[8:9], v[82:83], v[68:69], v[8:9] op_sel_hi:[1,0,1]
	v_pk_fma_f32 v[38:39], v[8:9], v[68:69], v[38:39] op_sel:[0,1,0] op_sel_hi:[1,1,1]
	s_waitcnt lgkmcnt(2)
	v_pk_fma_f32 v[10:11], v[82:83], v[70:71], v[10:11] op_sel_hi:[1,0,1]
	v_pk_fma_f32 v[38:39], v[10:11], v[70:71], v[38:39] op_sel:[0,1,0] op_sel_hi:[1,1,1]
	v_pk_fma_f32 v[12:13], v[82:83], v[72:73], v[12:13] op_sel_hi:[1,0,1]
	v_pk_fma_f32 v[38:39], v[12:13], v[72:73], v[38:39] op_sel:[0,1,0] op_sel_hi:[1,1,1]
	s_waitcnt lgkmcnt(1)
	v_pk_fma_f32 v[14:15], v[82:83], v[74:75], v[14:15] op_sel_hi:[1,0,1]
	v_pk_fma_f32 v[38:39], v[14:15], v[74:75], v[38:39] op_sel:[0,1,0] op_sel_hi:[1,1,1]
	v_pk_fma_f32 v[16:17], v[82:83], v[76:77], v[16:17] op_sel_hi:[1,0,1]
	v_pk_fma_f32 v[38:39], v[16:17], v[76:77], v[38:39] op_sel:[0,1,0] op_sel_hi:[1,1,1]
	s_waitcnt lgkmcnt(0)
	v_pk_fma_f32 v[18:19], v[82:83], v[78:79], v[18:19] op_sel_hi:[1,0,1]
	v_pk_fma_f32 v[38:39], v[18:19], v[78:79], v[38:39] op_sel:[0,1,0] op_sel_hi:[1,1,1]
	v_pk_fma_f32 v[20:21], v[82:83], v[80:81], v[20:21] op_sel_hi:[1,0,1]
	v_pk_fma_f32 v[38:39], v[20:21], v[80:81], v[38:39] op_sel:[0,1,0] op_sel_hi:[1,1,1]
	s_add_u32 s14, s14, 0x1000
	s_addc_u32 s15, s15, 0
	v_add_f32_dpp v38, v38, v38 row_ror:8 row_mask:0xf bank_mask:0x3 bound_ctrl:1
	v_add_f32_dpp v38, v39, v39 row_ror:8 row_mask:0xf bank_mask:0xc bound_ctrl:1
	ds_read_b64 v[64:65], v3 offset:20736
	ds_read_b128 v[48:51], v2 offset:8448
	v_add_f32_dpp v38, v38, v38 row_half_mirror row_mask:0xf bank_mask:0xf bound_ctrl:1
	ds_read_b128 v[52:55], v2 offset:8704
	ds_read_b128 v[56:59], v2 offset:8960
	v_add_f32_dpp v38, v38, v38 quad_perm:[1,0,3,2] row_mask:0xf bank_mask:0xf bound_ctrl:1
	ds_read_b128 v[60:63], v2 offset:9216
	s_nop 0
	v_add_f32_dpp v38, v38, v38 quad_perm:[2,3,0,1] row_mask:0xf bank_mask:0xf bound_ctrl:1
	s_nop 1
	v_mov_b32_dpp v39, v38 row_ror:8 row_mask:0xf bank_mask:0xf bound_ctrl:1
	v_cvt_pk_bf16_f32 v47, v38, v39
	s_mov_b64 exec, s[2:3]
	global_store_dword v46, v47, s[14:15] offset:-4096
	s_mov_b64 exec, -1
	s_waitcnt vmcnt(8)
	v_lshlrev_b32_e32 v108, 16, v84
	v_lshlrev_b32_e32 v109, 16, v85
	v_and_b32_e32 v110, s17, v84
	v_and_b32_e32 v111, s17, v85
	v_lshlrev_b32_e32 v112, 16, v86
	v_lshlrev_b32_e32 v113, 16, v87
	v_and_b32_e32 v114, s17, v86
	v_and_b32_e32 v115, s17, v87
	v_lshlrev_b32_e32 v116, 16, v88
	v_and_b32_e32 v117, s17, v88
	v_rcp_f32_e32 v25, v24
	v_mul_f32_e32 v113, v24, v113
	v_mul_f32_e32 v115, v24, v115
	v_mul_f32_e32 v109, 0x3db504f3, v109
	v_mul_f32_e32 v111, 0x3db504f3, v111
	v_cndmask_b32_e64 v27, 1.0, v25, s[20:21]
	v_mul_f32_e32 v24, v24, v26
	v_mul_f32_e32 v116, v27, v116
	v_mul_f32_e32 v117, v27, v117
	ds_write_b128 v29, v[108:111] offset:24832
	ds_write_b128 v29, v[112:115] offset:33024
	ds_write_b64 v30, v[90:91] offset:24832
	ds_write_b64 v31, v[116:117] offset:24832
	s_add_i32 s16, s16, 8
	s_waitcnt lgkmcnt(0)
	s_barrier
	s_cmpk_lt_u32 s16, 0x800
	s_cbranch_scc1 .Lret2_loop

.Lgla2_item:
	s_lshr_b32 s0, s18, 5
	s_and_b32 s1, s18, 31
	s_lshr_b32 s2, s0, 2
	s_and_b32 s3, s0, 3
	s_lshl_b32 s4, s1, 4
	v_lshl_add_u32 v46, v5, 2, s4
	s_and_b32 s4, s1, 3
	s_lshl_b32 s4, s4, 5
	v_lshl_add_u32 v3, v5, 3, s4
	s_lshl_b32 s4, s3, 8
	s_add_u32 s4, s4, 1024
	v_lshl_add_u32 v32, v198, 2, s4
	s_add_u32 s4, s4, 4096
	v_lshl_add_u32 v33, v198, 2, s4
	s_lshl_b32 s4, s3, 9
	s_and_b32 s5, s1, 28
	s_lshl_b32 s5, s5, 4
	s_add_u32 s4, s4, s5
	s_add_u32 s4, s4, 2048
	v_min_u32_e32 v42, 31, v198
	v_lshl_add_u32 v34, v42, 2, s4
	v_cmp_lt_u32_e32 vcc, 15, v198
	v_add_u32_e32 v44, 4032, v34
	s_nop 1
	v_cndmask_b32_e32 v34, v34, v44, vcc
	v_readlane_b32 s5, v255, 15
	s_mul_i32 s4, s2, 0x1800000
	s_mul_i32 s1, s5, 0x3000
	s_add_u32 s4, s4, s1
	s_add_u32 s4, s4, 0x3bc0400
	s_add_u32 s10, s8, s4
	s_addc_u32 s11, s9, 0
	s_lshl_b32 s4, s2, 22
	s_lshl_b32 s1, s5, 11
	s_add_u32 s4, s4, s1
	s_lshl_b32 s1, s3, 9
	s_add_u32 s4, s4, s1
	s_add_u32 s4, s4, 0xfd40400
	s_add_u32 s12, s8, s4
	s_addc_u32 s13, s9, 0
	s_lshl_b32 s4, s2, 23
	s_add_u32 s4, s4, s1
	s_add_u32 s4, s4, 333186048
	s_add_u32 s14, s8, s4
	s_addc_u32 s15, s9, 0
	s_lshr_b32 s4, 0x80000, s3
	s_sub_u32 s4, 0x3f800000, s4
	v_mov_b32_e32 v28, s4
	v_mul_f32_e32 v27, v28, v28
	v_mul_f32_e32 v25, v27, v27
	v_mul_f32_e32 v26, v25, v25
	v_mov_b32_e32 v24, v28
	s_bitcmp0_b32 s5, 0
	s_cbranch_scc1 .Lgla2_gw0
	v_mul_f32_e32 v24, v24, v28

.Lgla2_gw2:
	s_mov_b32 s20, 0xffff0000
	s_mov_b32 s21, -1
	global_load_dword v110, v32, s[10:11]
	global_load_dword v111, v32, s[10:11] offset:-1024
	global_load_dword v112, v33, s[10:11]
	global_load_dword v113, v33, s[10:11] offset:-1024
	global_load_dword v114, v34, s[10:11]
	global_load_dword v116, v35, s[12:13]
	global_load_dword v117, v35, s[12:13] offset:4
	s_add_u32 s10, s10, 0x18000
	s_addc_u32 s11, s11, 0
	s_add_u32 s12, s12, 0x4000
	s_addc_u32 s13, s13, 0
	s_waitcnt vmcnt(0)
	v_lshlrev_b32_e32 v144, 16, v110
	v_lshlrev_b32_e32 v145, 16, v111
	v_and_b32_e32 v146, s17, v110
	v_and_b32_e32 v147, s17, v111
	v_lshlrev_b32_e32 v148, 16, v112
	v_lshlrev_b32_e32 v149, 16, v113
	v_and_b32_e32 v150, s17, v112
	v_and_b32_e32 v151, s17, v113
	v_lshlrev_b32_e32 v152, 16, v114
	v_and_b32_e32 v153, s17, v114
	v_rcp_f32_e32 v25, v24
	v_mul_f32_e32 v149, v24, v149
	v_mul_f32_e32 v151, v24, v151
	v_mul_f32_e32 v145, 0x3db504f3, v145
	v_mul_f32_e32 v147, 0x3db504f3, v147
	v_cndmask_b32_e64 v27, 1.0, v25, s[20:21]
	v_mul_f32_e32 v24, v24, v26
	v_mul_f32_e32 v152, v27, v152
	v_mul_f32_e32 v153, v27, v153
	ds_write_b128 v29, v[144:147] offset:256
	ds_write_b128 v29, v[148:151] offset:8448
	ds_write_b64 v30, v[116:117] offset:256
	ds_write_b64 v31, v[152:153] offset:256
	global_load_dword v110, v32, s[10:11]
	global_load_dword v111, v32, s[10:11] offset:-1024
	global_load_dword v112, v33, s[10:11]
	global_load_dword v113, v33, s[10:11] offset:-1024
	global_load_dword v114, v34, s[10:11]
	global_load_dword v116, v35, s[12:13]
	global_load_dword v117, v35, s[12:13] offset:4
	s_add_u32 s10, s10, 0x18000
	s_addc_u32 s11, s11, 0
	s_add_u32 s12, s12, 0x4000
	s_addc_u32 s13, s13, 0
	s_waitcnt vmcnt(0)
	v_lshlrev_b32_e32 v144, 16, v110
	v_lshlrev_b32_e32 v145, 16, v111
	v_and_b32_e32 v146, s17, v110
	v_and_b32_e32 v147, s17, v111
	v_lshlrev_b32_e32 v148, 16, v112
	v_lshlrev_b32_e32 v149, 16, v113
	v_and_b32_e32 v150, s17, v112
	v_and_b32_e32 v151, s17, v113
	v_lshlrev_b32_e32 v152, 16, v114
	v_and_b32_e32 v153, s17, v114
	v_rcp_f32_e32 v25, v24
	v_mul_f32_e32 v149, v24, v149
	v_mul_f32_e32 v151, v24, v151
	v_mul_f32_e32 v145, 0x3db504f3, v145
	v_mul_f32_e32 v147, 0x3db504f3, v147
	v_cndmask_b32_e64 v27, 1.0, v25, s[20:21]
	v_mul_f32_e32 v24, v24, v26
	v_mul_f32_e32 v152, v27, v152
	v_mul_f32_e32 v153, v27, v153
	ds_write_b128 v29, v[144:147] offset:24832
	ds_write_b128 v29, v[148:151] offset:33024
	ds_write_b64 v30, v[116:117] offset:24832
	ds_write_b64 v31, v[152:153] offset:24832
	v_add_u32_e32 v22, 0x8000, v2
	v_add_u32_e32 v23, 0x8000, v3
	v_mov_b32_e32 v6, 0
	v_mov_b32_e32 v7, 0
	v_mov_b32_e32 v8, 0
	v_mov_b32_e32 v9, 0
	v_mov_b32_e32 v10, 0
	v_mov_b32_e32 v11, 0
	v_mov_b32_e32 v12, 0
	v_mov_b32_e32 v13, 0
	v_mov_b32_e32 v14, 0
	v_mov_b32_e32 v15, 0
	v_mov_b32_e32 v16, 0
	v_mov_b32_e32 v17, 0
	v_mov_b32_e32 v18, 0
	v_mov_b32_e32 v19, 0
	v_mov_b32_e32 v20, 0
	v_mov_b32_e32 v21, 0
	s_mov_b32 s16, 0
	s_mov_b32 s2, 0x10001
	s_mov_b32 s3, 0x10001
	s_waitcnt vmcnt(0) lgkmcnt(0)
	s_barrier
	ds_read_b64 v[72:73], v3 offset:20736
	ds_read_b128 v[48:51], v2 offset:256
	ds_read_b128 v[64:67], v2 offset:16640
	ds_read_b128 v[52:55], v2 offset:512
	ds_read_b128 v[56:59], v2 offset:768
	ds_read_b128 v[68:71], v2 offset:16896
	ds_read_b128 v[60:63], v2 offset:1024
.Lgla2_loop:
	global_load_dword v110, v32, s[10:11]
	global_load_dword v111, v32, s[10:11] offset:-1024
	global_load_dword v112, v33, s[10:11]
	global_load_dword v113, v33, s[10:11] offset:-1024
	global_load_dword v114, v34, s[10:11]
	global_load_dword v116, v35, s[12:13]
	global_load_dword v117, v35, s[12:13] offset:4
	s_add_u32 s10, s10, 0x18000
	s_addc_u32 s11, s11, 0
	s_add_u32 s12, s12, 0x4000
	s_addc_u32 s13, s13, 0
	s_waitcnt lgkmcnt(4)
	v_pk_mul_f32 v[42:43], v[72:73], v[48:49] op_sel_hi:[1,0]
	v_pk_fma_f32 v[6:7], v[6:7], v[64:65], v[42:43] op_sel:[0,0,0] op_sel_hi:[1,0,1]
	v_pk_mul_f32 v[38:39], v[6:7], v[48:49] op_sel:[0,1] op_sel_hi:[1,1]
	v_pk_mul_f32 v[44:45], v[72:73], v[50:51] op_sel_hi:[1,0]
	v_pk_fma_f32 v[8:9], v[8:9], v[64:65], v[44:45] op_sel:[0,1,0] op_sel_hi:[1,1,1]
	v_pk_fma_f32 v[38:39], v[8:9], v[50:51], v[38:39] op_sel:[0,1,0] op_sel_hi:[1,1,1]
	s_waitcnt lgkmcnt(3)
	v_pk_mul_f32 v[42:43], v[72:73], v[52:53] op_sel_hi:[1,0]
	v_pk_fma_f32 v[10:11], v[10:11], v[66:67], v[42:43] op_sel:[0,0,0] op_sel_hi:[1,0,1]
	v_pk_fma_f32 v[38:39], v[10:11], v[52:53], v[38:39] op_sel:[0,1,0] op_sel_hi:[1,1,1]
	v_pk_mul_f32 v[44:45], v[72:73], v[54:55] op_sel_hi:[1,0]
	v_pk_fma_f32 v[12:13], v[12:13], v[66:67], v[44:45] op_sel:[0,1,0] op_sel_hi:[1,1,1]
	v_pk_fma_f32 v[38:39], v[12:13], v[54:55], v[38:39] op_sel:[0,1,0] op_sel_hi:[1,1,1]
	s_waitcnt lgkmcnt(1)
	v_pk_mul_f32 v[42:43], v[72:73], v[56:57] op_sel_hi:[1,0]
	v_pk_fma_f32 v[14:15], v[14:15], v[68:69], v[42:43] op_sel:[0,0,0] op_sel_hi:[1,0,1]
	v_pk_fma_f32 v[38:39], v[14:15], v[56:57], v[38:39] op_sel:[0,1,0] op_sel_hi:[1,1,1]
	v_pk_mul_f32 v[44:45], v[72:73], v[58:59] op_sel_hi:[1,0]
	v_pk_fma_f32 v[16:17], v[16:17], v[68:69], v[44:45] op_sel:[0,1,0] op_sel_hi:[1,1,1]
	v_pk_fma_f32 v[38:39], v[16:17], v[58:59], v[38:39] op_sel:[0,1,0] op_sel_hi:[1,1,1]
	s_waitcnt lgkmcnt(0)
	v_pk_mul_f32 v[42:43], v[72:73], v[60:61] op_sel_hi:[1,0]
	v_pk_fma_f32 v[18:19], v[18:19], v[70:71], v[42:43] op_sel:[0,0,0] op_sel_hi:[1,0,1]
	v_pk_fma_f32 v[38:39], v[18:19], v[60:61], v[38:39] op_sel:[0,1,0] op_sel_hi:[1,1,1]
	v_pk_mul_f32 v[44:45], v[72:73], v[62:63] op_sel_hi:[1,0]
	v_pk_fma_f32 v[20:21], v[20:21], v[70:71], v[44:45] op_sel:[0,1,0] op_sel_hi:[1,1,1]
	v_pk_fma_f32 v[38:39], v[20:21], v[62:63], v[38:39] op_sel:[0,1,0] op_sel_hi:[1,1,1]
	s_add_u32 s14, s14, 0x1000
	s_addc_u32 s15, s15, 0
	v_add_f32_dpp v38, v38, v38 row_ror:8 row_mask:0xf bank_mask:0x3 bound_ctrl:1
	v_add_f32_dpp v38, v39, v39 row_ror:8 row_mask:0xf bank_mask:0xc bound_ctrl:1
	ds_read_b64 v[104:105], v3 offset:20992
	ds_read_b128 v[80:83], v2 offset:1280
	v_add_f32_dpp v38, v38, v38 row_half_mirror row_mask:0xf bank_mask:0xf bound_ctrl:1
	ds_read_b128 v[96:99], v2 offset:17152
	ds_read_b128 v[84:87], v2 offset:1536
	v_add_f32_dpp v38, v38, v38 quad_perm:[1,0,3,2] row_mask:0xf bank_mask:0xf bound_ctrl:1
	ds_read_b128 v[88:91], v2 offset:1792
	ds_read_b128 v[100:103], v2 offset:17408
	v_add_f32_dpp v38, v38, v38 quad_perm:[2,3,0,1] row_mask:0xf bank_mask:0xf bound_ctrl:1
	ds_read_b128 v[92:95], v2 offset:2048
	s_nop 0
	v_mov_b32_dpp v39, v38 row_ror:8 row_mask:0xf bank_mask:0xf bound_ctrl:1
	v_cvt_pk_bf16_f32 v47, v38, v39
	s_mov_b64 exec, s[2:3]
	global_store_dword v46, v47, s[14:15] offset:-4096
	s_mov_b64 exec, -1
	s_waitcnt lgkmcnt(4)
	v_pk_mul_f32 v[42:43], v[104:105], v[80:81] op_sel_hi:[1,0]
	v_pk_fma_f32 v[6:7], v[6:7], v[96:97], v[42:43] op_sel:[0,0,0] op_sel_hi:[1,0,1]
	v_pk_mul_f32 v[38:39], v[6:7], v[80:81] op_sel:[0,1] op_sel_hi:[1,1]
	v_pk_mul_f32 v[44:45], v[104:105], v[82:83] op_sel_hi:[1,0]
	v_pk_fma_f32 v[8:9], v[8:9], v[96:97], v[44:45] op_sel:[0,1,0] op_sel_hi:[1,1,1]
	v_pk_fma_f32 v[38:39], v[8:9], v[82:83], v[38:39] op_sel:[0,1,0] op_sel_hi:[1,1,1]
	s_waitcnt lgkmcnt(3)
	v_pk_mul_f32 v[42:43], v[104:105], v[84:85] op_sel_hi:[1,0]
	v_pk_fma_f32 v[10:11], v[10:11], v[98:99], v[42:43] op_sel:[0,0,0] op_sel_hi:[1,0,1]
	v_pk_fma_f32 v[38:39], v[10:11], v[84:85], v[38:39] op_sel:[0,1,0] op_sel_hi:[1,1,1]
	v_pk_mul_f32 v[44:45], v[104:105], v[86:87] op_sel_hi:[1,0]
	v_pk_fma_f32 v[12:13], v[12:13], v[98:99], v[44:45] op_sel:[0,1,0] op_sel_hi:[1,1,1]
	v_pk_fma_f32 v[38:39], v[12:13], v[86:87], v[38:39] op_sel:[0,1,0] op_sel_hi:[1,1,1]
	s_waitcnt lgkmcnt(1)
	v_pk_mul_f32 v[42:43], v[104:105], v[88:89] op_sel_hi:[1,0]
	v_pk_fma_f32 v[14:15], v[14:15], v[100:101], v[42:43] op_sel:[0,0,0] op_sel_hi:[1,0,1]
	v_pk_fma_f32 v[38:39], v[14:15], v[88:89], v[38:39] op_sel:[0,1,0] op_sel_hi:[1,1,1]
	v_pk_mul_f32 v[44:45], v[104:105], v[90:91] op_sel_hi:[1,0]
	v_pk_fma_f32 v[16:17], v[16:17], v[100:101], v[44:45] op_sel:[0,1,0] op_sel_hi:[1,1,1]
	v_pk_fma_f32 v[38:39], v[16:17], v[90:91], v[38:39] op_sel:[0,1,0] op_sel_hi:[1,1,1]
	s_waitcnt lgkmcnt(0)
	v_pk_mul_f32 v[42:43], v[104:105], v[92:93] op_sel_hi:[1,0]
	v_pk_fma_f32 v[18:19], v[18:19], v[102:103], v[42:43] op_sel:[0,0,0] op_sel_hi:[1,0,1]
	v_pk_fma_f32 v[38:39], v[18:19], v[92:93], v[38:39] op_sel:[0,1,0] op_sel_hi:[1,1,1]
	v_pk_mul_f32 v[44:45], v[104:105], v[94:95] op_sel_hi:[1,0]
	v_pk_fma_f32 v[20:21], v[20:21], v[102:103], v[44:45] op_sel:[0,1,0] op_sel_hi:[1,1,1]
	v_pk_fma_f32 v[38:39], v[20:21], v[94:95], v[38:39] op_sel:[0,1,0] op_sel_hi:[1,1,1]
	s_add_u32 s14, s14, 0x1000
	s_addc_u32 s15, s15, 0
	v_add_f32_dpp v38, v38, v38 row_ror:8 row_mask:0xf bank_mask:0x3 bound_ctrl:1
	v_add_f32_dpp v38, v39, v39 row_ror:8 row_mask:0xf bank_mask:0xc bound_ctrl:1
	ds_read_b64 v[72:73], v3 offset:21248
	ds_read_b128 v[48:51], v2 offset:2304
	v_add_f32_dpp v38, v38, v38 row_half_mirror row_mask:0xf bank_mask:0xf bound_ctrl:1
	ds_read_b128 v[64:67], v2 offset:17664
	ds_read_b128 v[52:55], v2 offset:2560
	v_add_f32_dpp v38, v38, v38 quad_perm:[1,0,3,2] row_mask:0xf bank_mask:0xf bound_ctrl:1
	ds_read_b128 v[56:59], v2 offset:2816
	ds_read_b128 v[68:71], v2 offset:17920
	v_add_f32_dpp v38, v38, v38 quad_perm:[2,3,0,1] row_mask:0xf bank_mask:0xf bound_ctrl:1
	ds_read_b128 v[60:63], v2 offset:3072
	s_nop 0
	v_mov_b32_dpp v39, v38 row_ror:8 row_mask:0xf bank_mask:0xf bound_ctrl:1
	v_cvt_pk_bf16_f32 v47, v38, v39
	s_mov_b64 exec, s[2:3]
	global_store_dword v46, v47, s[14:15] offset:-4096
	s_mov_b64 exec, -1
	s_waitcnt lgkmcnt(4)
	v_pk_mul_f32 v[42:43], v[72:73], v[48:49] op_sel_hi:[1,0]
	v_pk_fma_f32 v[6:7], v[6:7], v[64:65], v[42:43] op_sel:[0,0,0] op_sel_hi:[1,0,1]
	v_pk_mul_f32 v[38:39], v[6:7], v[48:49] op_sel:[0,1] op_sel_hi:[1,1]
	v_pk_mul_f32 v[44:45], v[72:73], v[50:51] op_sel_hi:[1,0]
	v_pk_fma_f32 v[8:9], v[8:9], v[64:65], v[44:45] op_sel:[0,1,0] op_sel_hi:[1,1,1]
	v_pk_fma_f32 v[38:39], v[8:9], v[50:51], v[38:39] op_sel:[0,1,0] op_sel_hi:[1,1,1]
	s_waitcnt lgkmcnt(3)
	v_pk_mul_f32 v[42:43], v[72:73], v[52:53] op_sel_hi:[1,0]
	v_pk_fma_f32 v[10:11], v[10:11], v[66:67], v[42:43] op_sel:[0,0,0] op_sel_hi:[1,0,1]
	v_pk_fma_f32 v[38:39], v[10:11], v[52:53], v[38:39] op_sel:[0,1,0] op_sel_hi:[1,1,1]
	v_pk_mul_f32 v[44:45], v[72:73], v[54:55] op_sel_hi:[1,0]
	v_pk_fma_f32 v[12:13], v[12:13], v[66:67], v[44:45] op_sel:[0,1,0] op_sel_hi:[1,1,1]
	v_pk_fma_f32 v[38:39], v[12:13], v[54:55], v[38:39] op_sel:[0,1,0] op_sel_hi:[1,1,1]
	s_waitcnt lgkmcnt(1)
	v_pk_mul_f32 v[42:43], v[72:73], v[56:57] op_sel_hi:[1,0]
	v_pk_fma_f32 v[14:15], v[14:15], v[68:69], v[42:43] op_sel:[0,0,0] op_sel_hi:[1,0,1]
	v_pk_fma_f32 v[38:39], v[14:15], v[56:57], v[38:39] op_sel:[0,1,0] op_sel_hi:[1,1,1]
	v_pk_mul_f32 v[44:45], v[72:73], v[58:59] op_sel_hi:[1,0]
	v_pk_fma_f32 v[16:17], v[16:17], v[68:69], v[44:45] op_sel:[0,1,0] op_sel_hi:[1,1,1]
	v_pk_fma_f32 v[38:39], v[16:17], v[58:59], v[38:39] op_sel:[0,1,0] op_sel_hi:[1,1,1]
	s_waitcnt lgkmcnt(0)
	v_pk_mul_f32 v[42:43], v[72:73], v[60:61] op_sel_hi:[1,0]
	v_pk_fma_f32 v[18:19], v[18:19], v[70:71], v[42:43] op_sel:[0,0,0] op_sel_hi:[1,0,1]
	v_pk_fma_f32 v[38:39], v[18:19], v[60:61], v[38:39] op_sel:[0,1,0] op_sel_hi:[1,1,1]
	v_pk_mul_f32 v[44:45], v[72:73], v[62:63] op_sel_hi:[1,0]
	v_pk_fma_f32 v[20:21], v[20:21], v[70:71], v[44:45] op_sel:[0,1,0] op_sel_hi:[1,1,1]
	v_pk_fma_f32 v[38:39], v[20:21], v[62:63], v[38:39] op_sel:[0,1,0] op_sel_hi:[1,1,1]
	s_add_u32 s14, s14, 0x1000
	s_addc_u32 s15, s15, 0
	v_add_f32_dpp v38, v38, v38 row_ror:8 row_mask:0xf bank_mask:0x3 bound_ctrl:1
	v_add_f32_dpp v38, v39, v39 row_ror:8 row_mask:0xf bank_mask:0xc bound_ctrl:1
	ds_read_b64 v[104:105], v3 offset:21504
	ds_read_b128 v[80:83], v2 offset:3328
	v_add_f32_dpp v38, v38, v38 row_half_mirror row_mask:0xf bank_mask:0xf bound_ctrl:1
	ds_read_b128 v[96:99], v2 offset:18176
	ds_read_b128 v[84:87], v2 offset:3584
	v_add_f32_dpp v38, v38, v38 quad_perm:[1,0,3,2] row_mask:0xf bank_mask:0xf bound_ctrl:1
	ds_read_b128 v[88:91], v2 offset:3840
	ds_read_b128 v[100:103], v2 offset:18432
	v_add_f32_dpp v38, v38, v38 quad_perm:[2,3,0,1] row_mask:0xf bank_mask:0xf bound_ctrl:1
	ds_read_b128 v[92:95], v2 offset:4096
	s_nop 0
	v_mov_b32_dpp v39, v38 row_ror:8 row_mask:0xf bank_mask:0xf bound_ctrl:1
	v_cvt_pk_bf16_f32 v47, v38, v39
	s_mov_b64 exec, s[2:3]
	global_store_dword v46, v47, s[14:15] offset:-4096
	s_mov_b64 exec, -1
	s_waitcnt lgkmcnt(4)
	v_pk_mul_f32 v[42:43], v[104:105], v[80:81] op_sel_hi:[1,0]
	v_pk_fma_f32 v[6:7], v[6:7], v[96:97], v[42:43] op_sel:[0,0,0] op_sel_hi:[1,0,1]
	v_pk_mul_f32 v[38:39], v[6:7], v[80:81] op_sel:[0,1] op_sel_hi:[1,1]
	v_pk_mul_f32 v[44:45], v[104:105], v[82:83] op_sel_hi:[1,0]
	v_pk_fma_f32 v[8:9], v[8:9], v[96:97], v[44:45] op_sel:[0,1,0] op_sel_hi:[1,1,1]
	v_pk_fma_f32 v[38:39], v[8:9], v[82:83], v[38:39] op_sel:[0,1,0] op_sel_hi:[1,1,1]
	s_waitcnt lgkmcnt(3)
	v_pk_mul_f32 v[42:43], v[104:105], v[84:85] op_sel_hi:[1,0]
	v_pk_fma_f32 v[10:11], v[10:11], v[98:99], v[42:43] op_sel:[0,0,0] op_sel_hi:[1,0,1]
	v_pk_fma_f32 v[38:39], v[10:11], v[84:85], v[38:39] op_sel:[0,1,0] op_sel_hi:[1,1,1]
	v_pk_mul_f32 v[44:45], v[104:105], v[86:87] op_sel_hi:[1,0]
	v_pk_fma_f32 v[12:13], v[12:13], v[98:99], v[44:45] op_sel:[0,1,0] op_sel_hi:[1,1,1]
	v_pk_fma_f32 v[38:39], v[12:13], v[86:87], v[38:39] op_sel:[0,1,0] op_sel_hi:[1,1,1]
	s_waitcnt lgkmcnt(1)
	v_pk_mul_f32 v[42:43], v[104:105], v[88:89] op_sel_hi:[1,0]
	v_pk_fma_f32 v[14:15], v[14:15], v[100:101], v[42:43] op_sel:[0,0,0] op_sel_hi:[1,0,1]
	v_pk_fma_f32 v[38:39], v[14:15], v[88:89], v[38:39] op_sel:[0,1,0] op_sel_hi:[1,1,1]
	v_pk_mul_f32 v[44:45], v[104:105], v[90:91] op_sel_hi:[1,0]
	v_pk_fma_f32 v[16:17], v[16:17], v[100:101], v[44:45] op_sel:[0,1,0] op_sel_hi:[1,1,1]
	v_pk_fma_f32 v[38:39], v[16:17], v[90:91], v[38:39] op_sel:[0,1,0] op_sel_hi:[1,1,1]
	s_waitcnt lgkmcnt(0)
	v_pk_mul_f32 v[42:43], v[104:105], v[92:93] op_sel_hi:[1,0]
	v_pk_fma_f32 v[18:19], v[18:19], v[102:103], v[42:43] op_sel:[0,0,0] op_sel_hi:[1,0,1]
	v_pk_fma_f32 v[38:39], v[18:19], v[92:93], v[38:39] op_sel:[0,1,0] op_sel_hi:[1,1,1]
	v_pk_mul_f32 v[44:45], v[104:105], v[94:95] op_sel_hi:[1,0]
	v_pk_fma_f32 v[20:21], v[20:21], v[102:103], v[44:45] op_sel:[0,1,0] op_sel_hi:[1,1,1]
	v_pk_fma_f32 v[38:39], v[20:21], v[94:95], v[38:39] op_sel:[0,1,0] op_sel_hi:[1,1,1]
	s_add_u32 s14, s14, 0x1000
	s_addc_u32 s15, s15, 0
	v_add_f32_dpp v38, v38, v38 row_ror:8 row_mask:0xf bank_mask:0x3 bound_ctrl:1
	v_add_f32_dpp v38, v39, v39 row_ror:8 row_mask:0xf bank_mask:0xc bound_ctrl:1
	ds_read_b64 v[72:73], v3 offset:21760
	ds_read_b128 v[48:51], v2 offset:4352
	v_add_f32_dpp v38, v38, v38 row_half_mirror row_mask:0xf bank_mask:0xf bound_ctrl:1
	ds_read_b128 v[64:67], v2 offset:18688
	ds_read_b128 v[52:55], v2 offset:4608
	v_add_f32_dpp v38, v38, v38 quad_perm:[1,0,3,2] row_mask:0xf bank_mask:0xf bound_ctrl:1
	ds_read_b128 v[56:59], v2 offset:4864
	ds_read_b128 v[68:71], v2 offset:18944
	v_add_f32_dpp v38, v38, v38 quad_perm:[2,3,0,1] row_mask:0xf bank_mask:0xf bound_ctrl:1
	ds_read_b128 v[60:63], v2 offset:5120
	s_nop 0
	v_mov_b32_dpp v39, v38 row_ror:8 row_mask:0xf bank_mask:0xf bound_ctrl:1
	v_cvt_pk_bf16_f32 v47, v38, v39
	s_mov_b64 exec, s[2:3]
	global_store_dword v46, v47, s[14:15] offset:-4096
	s_mov_b64 exec, -1
	s_waitcnt lgkmcnt(4)
	v_pk_mul_f32 v[42:43], v[72:73], v[48:49] op_sel_hi:[1,0]
	v_pk_fma_f32 v[6:7], v[6:7], v[64:65], v[42:43] op_sel:[0,0,0] op_sel_hi:[1,0,1]
	v_pk_mul_f32 v[38:39], v[6:7], v[48:49] op_sel:[0,1] op_sel_hi:[1,1]
	v_pk_mul_f32 v[44:45], v[72:73], v[50:51] op_sel_hi:[1,0]
	v_pk_fma_f32 v[8:9], v[8:9], v[64:65], v[44:45] op_sel:[0,1,0] op_sel_hi:[1,1,1]
	v_pk_fma_f32 v[38:39], v[8:9], v[50:51], v[38:39] op_sel:[0,1,0] op_sel_hi:[1,1,1]
	s_waitcnt lgkmcnt(3)
	v_pk_mul_f32 v[42:43], v[72:73], v[52:53] op_sel_hi:[1,0]
	v_pk_fma_f32 v[10:11], v[10:11], v[66:67], v[42:43] op_sel:[0,0,0] op_sel_hi:[1,0,1]
	v_pk_fma_f32 v[38:39], v[10:11], v[52:53], v[38:39] op_sel:[0,1,0] op_sel_hi:[1,1,1]
	v_pk_mul_f32 v[44:45], v[72:73], v[54:55] op_sel_hi:[1,0]
	v_pk_fma_f32 v[12:13], v[12:13], v[66:67], v[44:45] op_sel:[0,1,0] op_sel_hi:[1,1,1]
	v_pk_fma_f32 v[38:39], v[12:13], v[54:55], v[38:39] op_sel:[0,1,0] op_sel_hi:[1,1,1]
	s_waitcnt lgkmcnt(1)
	v_pk_mul_f32 v[42:43], v[72:73], v[56:57] op_sel_hi:[1,0]
	v_pk_fma_f32 v[14:15], v[14:15], v[68:69], v[42:43] op_sel:[0,0,0] op_sel_hi:[1,0,1]
	v_pk_fma_f32 v[38:39], v[14:15], v[56:57], v[38:39] op_sel:[0,1,0] op_sel_hi:[1,1,1]
	v_pk_mul_f32 v[44:45], v[72:73], v[58:59] op_sel_hi:[1,0]
	v_pk_fma_f32 v[16:17], v[16:17], v[68:69], v[44:45] op_sel:[0,1,0] op_sel_hi:[1,1,1]
	v_pk_fma_f32 v[38:39], v[16:17], v[58:59], v[38:39] op_sel:[0,1,0] op_sel_hi:[1,1,1]
	s_waitcnt lgkmcnt(0)
	v_pk_mul_f32 v[42:43], v[72:73], v[60:61] op_sel_hi:[1,0]
	v_pk_fma_f32 v[18:19], v[18:19], v[70:71], v[42:43] op_sel:[0,0,0] op_sel_hi:[1,0,1]
	v_pk_fma_f32 v[38:39], v[18:19], v[60:61], v[38:39] op_sel:[0,1,0] op_sel_hi:[1,1,1]
	v_pk_mul_f32 v[44:45], v[72:73], v[62:63] op_sel_hi:[1,0]
	v_pk_fma_f32 v[20:21], v[20:21], v[70:71], v[44:45] op_sel:[0,1,0] op_sel_hi:[1,1,1]
	v_pk_fma_f32 v[38:39], v[20:21], v[62:63], v[38:39] op_sel:[0,1,0] op_sel_hi:[1,1,1]
	s_add_u32 s14, s14, 0x1000
	s_addc_u32 s15, s15, 0
	v_add_f32_dpp v38, v38, v38 row_ror:8 row_mask:0xf bank_mask:0x3 bound_ctrl:1
	v_add_f32_dpp v38, v39, v39 row_ror:8 row_mask:0xf bank_mask:0xc bound_ctrl:1
	ds_read_b64 v[104:105], v3 offset:22016
	ds_read_b128 v[80:83], v2 offset:5376
	v_add_f32_dpp v38, v38, v38 row_half_mirror row_mask:0xf bank_mask:0xf bound_ctrl:1
	ds_read_b128 v[96:99], v2 offset:19200
	ds_read_b128 v[84:87], v2 offset:5632
	v_add_f32_dpp v38, v38, v38 quad_perm:[1,0,3,2] row_mask:0xf bank_mask:0xf bound_ctrl:1
	ds_read_b128 v[88:91], v2 offset:5888
	ds_read_b128 v[100:103], v2 offset:19456
	v_add_f32_dpp v38, v38, v38 quad_perm:[2,3,0,1] row_mask:0xf bank_mask:0xf bound_ctrl:1
	ds_read_b128 v[92:95], v2 offset:6144
	s_nop 0
	v_mov_b32_dpp v39, v38 row_ror:8 row_mask:0xf bank_mask:0xf bound_ctrl:1
	v_cvt_pk_bf16_f32 v47, v38, v39
	s_mov_b64 exec, s[2:3]
	global_store_dword v46, v47, s[14:15] offset:-4096
	s_mov_b64 exec, -1
	s_waitcnt lgkmcnt(4)
	v_pk_mul_f32 v[42:43], v[104:105], v[80:81] op_sel_hi:[1,0]
	v_pk_fma_f32 v[6:7], v[6:7], v[96:97], v[42:43] op_sel:[0,0,0] op_sel_hi:[1,0,1]
	v_pk_mul_f32 v[38:39], v[6:7], v[80:81] op_sel:[0,1] op_sel_hi:[1,1]
	v_pk_mul_f32 v[44:45], v[104:105], v[82:83] op_sel_hi:[1,0]
	v_pk_fma_f32 v[8:9], v[8:9], v[96:97], v[44:45] op_sel:[0,1,0] op_sel_hi:[1,1,1]
	v_pk_fma_f32 v[38:39], v[8:9], v[82:83], v[38:39] op_sel:[0,1,0] op_sel_hi:[1,1,1]
	s_waitcnt lgkmcnt(3)
	v_pk_mul_f32 v[42:43], v[104:105], v[84:85] op_sel_hi:[1,0]
	v_pk_fma_f32 v[10:11], v[10:11], v[98:99], v[42:43] op_sel:[0,0,0] op_sel_hi:[1,0,1]
	v_pk_fma_f32 v[38:39], v[10:11], v[84:85], v[38:39] op_sel:[0,1,0] op_sel_hi:[1,1,1]
	v_pk_mul_f32 v[44:45], v[104:105], v[86:87] op_sel_hi:[1,0]
	v_pk_fma_f32 v[12:13], v[12:13], v[98:99], v[44:45] op_sel:[0,1,0] op_sel_hi:[1,1,1]
	v_pk_fma_f32 v[38:39], v[12:13], v[86:87], v[38:39] op_sel:[0,1,0] op_sel_hi:[1,1,1]
	s_waitcnt lgkmcnt(1)
	v_pk_mul_f32 v[42:43], v[104:105], v[88:89] op_sel_hi:[1,0]
	v_pk_fma_f32 v[14:15], v[14:15], v[100:101], v[42:43] op_sel:[0,0,0] op_sel_hi:[1,0,1]
	v_pk_fma_f32 v[38:39], v[14:15], v[88:89], v[38:39] op_sel:[0,1,0] op_sel_hi:[1,1,1]
	v_pk_mul_f32 v[44:45], v[104:105], v[90:91] op_sel_hi:[1,0]
	v_pk_fma_f32 v[16:17], v[16:17], v[100:101], v[44:45] op_sel:[0,1,0] op_sel_hi:[1,1,1]
	v_pk_fma_f32 v[38:39], v[16:17], v[90:91], v[38:39] op_sel:[0,1,0] op_sel_hi:[1,1,1]
	s_waitcnt lgkmcnt(0)
	v_pk_mul_f32 v[42:43], v[104:105], v[92:93] op_sel_hi:[1,0]
	v_pk_fma_f32 v[18:19], v[18:19], v[102:103], v[42:43] op_sel:[0,0,0] op_sel_hi:[1,0,1]
	v_pk_fma_f32 v[38:39], v[18:19], v[92:93], v[38:39] op_sel:[0,1,0] op_sel_hi:[1,1,1]
	v_pk_mul_f32 v[44:45], v[104:105], v[94:95] op_sel_hi:[1,0]
	v_pk_fma_f32 v[20:21], v[20:21], v[102:103], v[44:45] op_sel:[0,1,0] op_sel_hi:[1,1,1]
	v_pk_fma_f32 v[38:39], v[20:21], v[94:95], v[38:39] op_sel:[0,1,0] op_sel_hi:[1,1,1]
	s_add_u32 s14, s14, 0x1000
	s_addc_u32 s15, s15, 0
	v_add_f32_dpp v38, v38, v38 row_ror:8 row_mask:0xf bank_mask:0x3 bound_ctrl:1
	v_add_f32_dpp v38, v39, v39 row_ror:8 row_mask:0xf bank_mask:0xc bound_ctrl:1
	ds_read_b64 v[72:73], v3 offset:22272
	ds_read_b128 v[48:51], v2 offset:6400
	v_add_f32_dpp v38, v38, v38 row_half_mirror row_mask:0xf bank_mask:0xf bound_ctrl:1
	ds_read_b128 v[64:67], v2 offset:19712
	ds_read_b128 v[52:55], v2 offset:6656
	v_add_f32_dpp v38, v38, v38 quad_perm:[1,0,3,2] row_mask:0xf bank_mask:0xf bound_ctrl:1
	ds_read_b128 v[56:59], v2 offset:6912
	ds_read_b128 v[68:71], v2 offset:19968
	v_add_f32_dpp v38, v38, v38 quad_perm:[2,3,0,1] row_mask:0xf bank_mask:0xf bound_ctrl:1
	ds_read_b128 v[60:63], v2 offset:7168
	s_nop 0
	v_mov_b32_dpp v39, v38 row_ror:8 row_mask:0xf bank_mask:0xf bound_ctrl:1
	v_cvt_pk_bf16_f32 v47, v38, v39
	s_mov_b64 exec, s[2:3]
	global_store_dword v46, v47, s[14:15] offset:-4096
	s_mov_b64 exec, -1
	s_waitcnt lgkmcnt(4)
	v_pk_mul_f32 v[42:43], v[72:73], v[48:49] op_sel_hi:[1,0]
	v_pk_fma_f32 v[6:7], v[6:7], v[64:65], v[42:43] op_sel:[0,0,0] op_sel_hi:[1,0,1]
	v_pk_mul_f32 v[38:39], v[6:7], v[48:49] op_sel:[0,1] op_sel_hi:[1,1]
	v_pk_mul_f32 v[44:45], v[72:73], v[50:51] op_sel_hi:[1,0]
	v_pk_fma_f32 v[8:9], v[8:9], v[64:65], v[44:45] op_sel:[0,1,0] op_sel_hi:[1,1,1]
	v_pk_fma_f32 v[38:39], v[8:9], v[50:51], v[38:39] op_sel:[0,1,0] op_sel_hi:[1,1,1]
	s_waitcnt lgkmcnt(3)
	v_pk_mul_f32 v[42:43], v[72:73], v[52:53] op_sel_hi:[1,0]
	v_pk_fma_f32 v[10:11], v[10:11], v[66:67], v[42:43] op_sel:[0,0,0] op_sel_hi:[1,0,1]
	v_pk_fma_f32 v[38:39], v[10:11], v[52:53], v[38:39] op_sel:[0,1,0] op_sel_hi:[1,1,1]
	v_pk_mul_f32 v[44:45], v[72:73], v[54:55] op_sel_hi:[1,0]
	v_pk_fma_f32 v[12:13], v[12:13], v[66:67], v[44:45] op_sel:[0,1,0] op_sel_hi:[1,1,1]
	v_pk_fma_f32 v[38:39], v[12:13], v[54:55], v[38:39] op_sel:[0,1,0] op_sel_hi:[1,1,1]
	s_waitcnt lgkmcnt(1)
	v_pk_mul_f32 v[42:43], v[72:73], v[56:57] op_sel_hi:[1,0]
	v_pk_fma_f32 v[14:15], v[14:15], v[68:69], v[42:43] op_sel:[0,0,0] op_sel_hi:[1,0,1]
	v_pk_fma_f32 v[38:39], v[14:15], v[56:57], v[38:39] op_sel:[0,1,0] op_sel_hi:[1,1,1]
	v_pk_mul_f32 v[44:45], v[72:73], v[58:59] op_sel_hi:[1,0]
	v_pk_fma_f32 v[16:17], v[16:17], v[68:69], v[44:45] op_sel:[0,1,0] op_sel_hi:[1,1,1]
	v_pk_fma_f32 v[38:39], v[16:17], v[58:59], v[38:39] op_sel:[0,1,0] op_sel_hi:[1,1,1]
	s_waitcnt lgkmcnt(0)
	v_pk_mul_f32 v[42:43], v[72:73], v[60:61] op_sel_hi:[1,0]
	v_pk_fma_f32 v[18:19], v[18:19], v[70:71], v[42:43] op_sel:[0,0,0] op_sel_hi:[1,0,1]
	v_pk_fma_f32 v[38:39], v[18:19], v[60:61], v[38:39] op_sel:[0,1,0] op_sel_hi:[1,1,1]
	v_pk_mul_f32 v[44:45], v[72:73], v[62:63] op_sel_hi:[1,0]
	v_pk_fma_f32 v[20:21], v[20:21], v[70:71], v[44:45] op_sel:[0,1,0] op_sel_hi:[1,1,1]
	v_pk_fma_f32 v[38:39], v[20:21], v[62:63], v[38:39] op_sel:[0,1,0] op_sel_hi:[1,1,1]
	s_add_u32 s14, s14, 0x1000
	s_addc_u32 s15, s15, 0
	v_add_f32_dpp v38, v38, v38 row_ror:8 row_mask:0xf bank_mask:0x3 bound_ctrl:1
	v_add_f32_dpp v38, v39, v39 row_ror:8 row_mask:0xf bank_mask:0xc bound_ctrl:1
	ds_read_b64 v[104:105], v3 offset:22528
	ds_read_b128 v[80:83], v2 offset:7424
	v_add_f32_dpp v38, v38, v38 row_half_mirror row_mask:0xf bank_mask:0xf bound_ctrl:1
	ds_read_b128 v[96:99], v2 offset:20224
	ds_read_b128 v[84:87], v2 offset:7680
	v_add_f32_dpp v38, v38, v38 quad_perm:[1,0,3,2] row_mask:0xf bank_mask:0xf bound_ctrl:1
	ds_read_b128 v[88:91], v2 offset:7936
	ds_read_b128 v[100:103], v2 offset:20480
	v_add_f32_dpp v38, v38, v38 quad_perm:[2,3,0,1] row_mask:0xf bank_mask:0xf bound_ctrl:1
	ds_read_b128 v[92:95], v2 offset:8192
	s_nop 0
	v_mov_b32_dpp v39, v38 row_ror:8 row_mask:0xf bank_mask:0xf bound_ctrl:1
	v_cvt_pk_bf16_f32 v47, v38, v39
	s_mov_b64 exec, s[2:3]
	global_store_dword v46, v47, s[14:15] offset:-4096
	s_mov_b64 exec, -1
	s_waitcnt lgkmcnt(4)
	v_pk_mul_f32 v[42:43], v[104:105], v[80:81] op_sel_hi:[1,0]
	v_pk_fma_f32 v[6:7], v[6:7], v[96:97], v[42:43] op_sel:[0,0,0] op_sel_hi:[1,0,1]
	v_pk_mul_f32 v[38:39], v[6:7], v[80:81] op_sel:[0,1] op_sel_hi:[1,1]
	v_pk_mul_f32 v[44:45], v[104:105], v[82:83] op_sel_hi:[1,0]
	v_pk_fma_f32 v[8:9], v[8:9], v[96:97], v[44:45] op_sel:[0,1,0] op_sel_hi:[1,1,1]
	v_pk_fma_f32 v[38:39], v[8:9], v[82:83], v[38:39] op_sel:[0,1,0] op_sel_hi:[1,1,1]
	s_waitcnt lgkmcnt(3)
	v_pk_mul_f32 v[42:43], v[104:105], v[84:85] op_sel_hi:[1,0]
	v_pk_fma_f32 v[10:11], v[10:11], v[98:99], v[42:43] op_sel:[0,0,0] op_sel_hi:[1,0,1]
	v_pk_fma_f32 v[38:39], v[10:11], v[84:85], v[38:39] op_sel:[0,1,0] op_sel_hi:[1,1,1]
	v_pk_mul_f32 v[44:45], v[104:105], v[86:87] op_sel_hi:[1,0]
	v_pk_fma_f32 v[12:13], v[12:13], v[98:99], v[44:45] op_sel:[0,1,0] op_sel_hi:[1,1,1]
	v_pk_fma_f32 v[38:39], v[12:13], v[86:87], v[38:39] op_sel:[0,1,0] op_sel_hi:[1,1,1]
	s_waitcnt lgkmcnt(1)
	v_pk_mul_f32 v[42:43], v[104:105], v[88:89] op_sel_hi:[1,0]
	v_pk_fma_f32 v[14:15], v[14:15], v[100:101], v[42:43] op_sel:[0,0,0] op_sel_hi:[1,0,1]
	v_pk_fma_f32 v[38:39], v[14:15], v[88:89], v[38:39] op_sel:[0,1,0] op_sel_hi:[1,1,1]
	v_pk_mul_f32 v[44:45], v[104:105], v[90:91] op_sel_hi:[1,0]
	v_pk_fma_f32 v[16:17], v[16:17], v[100:101], v[44:45] op_sel:[0,1,0] op_sel_hi:[1,1,1]
	v_pk_fma_f32 v[38:39], v[16:17], v[90:91], v[38:39] op_sel:[0,1,0] op_sel_hi:[1,1,1]
	s_waitcnt lgkmcnt(0)
	v_pk_mul_f32 v[42:43], v[104:105], v[92:93] op_sel_hi:[1,0]
	v_pk_fma_f32 v[18:19], v[18:19], v[102:103], v[42:43] op_sel:[0,0,0] op_sel_hi:[1,0,1]
	v_pk_fma_f32 v[38:39], v[18:19], v[92:93], v[38:39] op_sel:[0,1,0] op_sel_hi:[1,1,1]
	v_pk_mul_f32 v[44:45], v[104:105], v[94:95] op_sel_hi:[1,0]
	v_pk_fma_f32 v[20:21], v[20:21], v[102:103], v[44:45] op_sel:[0,1,0] op_sel_hi:[1,1,1]
	v_pk_fma_f32 v[38:39], v[20:21], v[94:95], v[38:39] op_sel:[0,1,0] op_sel_hi:[1,1,1]
	s_add_u32 s14, s14, 0x1000
	s_addc_u32 s15, s15, 0
	v_add_f32_dpp v38, v38, v38 row_ror:8 row_mask:0xf bank_mask:0x3 bound_ctrl:1
	v_add_f32_dpp v38, v39, v39 row_ror:8 row_mask:0xf bank_mask:0xc bound_ctrl:1
	ds_read_b64 v[72:73], v3 offset:45312
	ds_read_b128 v[48:51], v2 offset:24832
	v_add_f32_dpp v38, v38, v38 row_half_mirror row_mask:0xf bank_mask:0xf bound_ctrl:1
	ds_read_b128 v[64:67], v2 offset:41216
	ds_read_b128 v[52:55], v2 offset:25088
	v_add_f32_dpp v38, v38, v38 quad_perm:[1,0,3,2] row_mask:0xf bank_mask:0xf bound_ctrl:1
	ds_read_b128 v[56:59], v2 offset:25344
	ds_read_b128 v[68:71], v2 offset:41472
	v_add_f32_dpp v38, v38, v38 quad_perm:[2,3,0,1] row_mask:0xf bank_mask:0xf bound_ctrl:1
	ds_read_b128 v[60:63], v2 offset:25600
	s_nop 0
	v_mov_b32_dpp v39, v38 row_ror:8 row_mask:0xf bank_mask:0xf bound_ctrl:1
	v_cvt_pk_bf16_f32 v47, v38, v39
	s_mov_b64 exec, s[2:3]
	global_store_dword v46, v47, s[14:15] offset:-4096
	s_mov_b64 exec, -1
	s_waitcnt vmcnt(8)
	v_lshlrev_b32_e32 v144, 16, v110
	v_lshlrev_b32_e32 v145, 16, v111
	v_and_b32_e32 v146, s17, v110
	v_and_b32_e32 v147, s17, v111
	v_lshlrev_b32_e32 v148, 16, v112
	v_lshlrev_b32_e32 v149, 16, v113
	v_and_b32_e32 v150, s17, v112
	v_and_b32_e32 v151, s17, v113
	v_lshlrev_b32_e32 v152, 16, v114
	v_and_b32_e32 v153, s17, v114
	v_rcp_f32_e32 v25, v24
	v_mul_f32_e32 v149, v24, v149
	v_mul_f32_e32 v151, v24, v151
	v_mul_f32_e32 v145, 0x3db504f3, v145
	v_mul_f32_e32 v147, 0x3db504f3, v147
	v_cndmask_b32_e64 v27, 1.0, v25, s[20:21]
	v_mul_f32_e32 v24, v24, v26
	v_mul_f32_e32 v152, v27, v152
	v_mul_f32_e32 v153, v27, v153
	ds_write_b128 v29, v[144:147] offset:49408
	ds_write_b128 v29, v[148:151] offset:57600
	ds_write_b64 v30, v[116:117] offset:49408
	ds_write_b64 v31, v[152:153] offset:49408
	s_add_i32 s16, s16, 8
	s_waitcnt lgkmcnt(0)
	s_barrier
	s_cmpk_lt_u32 s16, 0x800
	s_cbranch_scc0 .Lgla2_done
	global_load_dword v110, v32, s[10:11]
	global_load_dword v111, v32, s[10:11] offset:-1024
	global_load_dword v112, v33, s[10:11]
	global_load_dword v113, v33, s[10:11] offset:-1024
	global_load_dword v114, v34, s[10:11]
	global_load_dword v116, v35, s[12:13]
	global_load_dword v117, v35, s[12:13] offset:4
	s_add_u32 s10, s10, 0x18000
	s_addc_u32 s11, s11, 0
	s_add_u32 s12, s12, 0x4000
	s_addc_u32 s13, s13, 0
	s_waitcnt lgkmcnt(4)
	v_pk_mul_f32 v[42:43], v[72:73], v[48:49] op_sel_hi:[1,0]
	v_pk_fma_f32 v[6:7], v[6:7], v[64:65], v[42:43] op_sel:[0,0,0] op_sel_hi:[1,0,1]
	v_pk_mul_f32 v[38:39], v[6:7], v[48:49] op_sel:[0,1] op_sel_hi:[1,1]
	v_pk_mul_f32 v[44:45], v[72:73], v[50:51] op_sel_hi:[1,0]
	v_pk_fma_f32 v[8:9], v[8:9], v[64:65], v[44:45] op_sel:[0,1,0] op_sel_hi:[1,1,1]
	v_pk_fma_f32 v[38:39], v[8:9], v[50:51], v[38:39] op_sel:[0,1,0] op_sel_hi:[1,1,1]
	s_waitcnt lgkmcnt(3)
	v_pk_mul_f32 v[42:43], v[72:73], v[52:53] op_sel_hi:[1,0]
	v_pk_fma_f32 v[10:11], v[10:11], v[66:67], v[42:43] op_sel:[0,0,0] op_sel_hi:[1,0,1]
	v_pk_fma_f32 v[38:39], v[10:11], v[52:53], v[38:39] op_sel:[0,1,0] op_sel_hi:[1,1,1]
	v_pk_mul_f32 v[44:45], v[72:73], v[54:55] op_sel_hi:[1,0]
	v_pk_fma_f32 v[12:13], v[12:13], v[66:67], v[44:45] op_sel:[0,1,0] op_sel_hi:[1,1,1]
	v_pk_fma_f32 v[38:39], v[12:13], v[54:55], v[38:39] op_sel:[0,1,0] op_sel_hi:[1,1,1]
	s_waitcnt lgkmcnt(1)
	v_pk_mul_f32 v[42:43], v[72:73], v[56:57] op_sel_hi:[1,0]
	v_pk_fma_f32 v[14:15], v[14:15], v[68:69], v[42:43] op_sel:[0,0,0] op_sel_hi:[1,0,1]
	v_pk_fma_f32 v[38:39], v[14:15], v[56:57], v[38:39] op_sel:[0,1,0] op_sel_hi:[1,1,1]
	v_pk_mul_f32 v[44:45], v[72:73], v[58:59] op_sel_hi:[1,0]
	v_pk_fma_f32 v[16:17], v[16:17], v[68:69], v[44:45] op_sel:[0,1,0] op_sel_hi:[1,1,1]
	v_pk_fma_f32 v[38:39], v[16:17], v[58:59], v[38:39] op_sel:[0,1,0] op_sel_hi:[1,1,1]
	s_waitcnt lgkmcnt(0)
	v_pk_mul_f32 v[42:43], v[72:73], v[60:61] op_sel_hi:[1,0]
	v_pk_fma_f32 v[18:19], v[18:19], v[70:71], v[42:43] op_sel:[0,0,0] op_sel_hi:[1,0,1]
	v_pk_fma_f32 v[38:39], v[18:19], v[60:61], v[38:39] op_sel:[0,1,0] op_sel_hi:[1,1,1]
	v_pk_mul_f32 v[44:45], v[72:73], v[62:63] op_sel_hi:[1,0]
	v_pk_fma_f32 v[20:21], v[20:21], v[70:71], v[44:45] op_sel:[0,1,0] op_sel_hi:[1,1,1]
	v_pk_fma_f32 v[38:39], v[20:21], v[62:63], v[38:39] op_sel:[0,1,0] op_sel_hi:[1,1,1]
	s_add_u32 s14, s14, 0x1000
	s_addc_u32 s15, s15, 0
	v_add_f32_dpp v38, v38, v38 row_ror:8 row_mask:0xf bank_mask:0x3 bound_ctrl:1
	v_add_f32_dpp v38, v39, v39 row_ror:8 row_mask:0xf bank_mask:0xc bound_ctrl:1
	ds_read_b64 v[104:105], v3 offset:45568
	ds_read_b128 v[80:83], v2 offset:25856
	v_add_f32_dpp v38, v38, v38 row_half_mirror row_mask:0xf bank_mask:0xf bound_ctrl:1
	ds_read_b128 v[96:99], v2 offset:41728
	ds_read_b128 v[84:87], v2 offset:26112
	v_add_f32_dpp v38, v38, v38 quad_perm:[1,0,3,2] row_mask:0xf bank_mask:0xf bound_ctrl:1
	ds_read_b128 v[88:91], v2 offset:26368
	ds_read_b128 v[100:103], v2 offset:41984
	v_add_f32_dpp v38, v38, v38 quad_perm:[2,3,0,1] row_mask:0xf bank_mask:0xf bound_ctrl:1
	ds_read_b128 v[92:95], v2 offset:26624
	s_nop 0
	v_mov_b32_dpp v39, v38 row_ror:8 row_mask:0xf bank_mask:0xf bound_ctrl:1
	v_cvt_pk_bf16_f32 v47, v38, v39
	s_mov_b64 exec, s[2:3]
	global_store_dword v46, v47, s[14:15] offset:-4096
	s_mov_b64 exec, -1
	s_waitcnt lgkmcnt(4)
	v_pk_mul_f32 v[42:43], v[104:105], v[80:81] op_sel_hi:[1,0]
	v_pk_fma_f32 v[6:7], v[6:7], v[96:97], v[42:43] op_sel:[0,0,0] op_sel_hi:[1,0,1]
	v_pk_mul_f32 v[38:39], v[6:7], v[80:81] op_sel:[0,1] op_sel_hi:[1,1]
	v_pk_mul_f32 v[44:45], v[104:105], v[82:83] op_sel_hi:[1,0]
	v_pk_fma_f32 v[8:9], v[8:9], v[96:97], v[44:45] op_sel:[0,1,0] op_sel_hi:[1,1,1]
	v_pk_fma_f32 v[38:39], v[8:9], v[82:83], v[38:39] op_sel:[0,1,0] op_sel_hi:[1,1,1]
	s_waitcnt lgkmcnt(3)
	v_pk_mul_f32 v[42:43], v[104:105], v[84:85] op_sel_hi:[1,0]
	v_pk_fma_f32 v[10:11], v[10:11], v[98:99], v[42:43] op_sel:[0,0,0] op_sel_hi:[1,0,1]
	v_pk_fma_f32 v[38:39], v[10:11], v[84:85], v[38:39] op_sel:[0,1,0] op_sel_hi:[1,1,1]
	v_pk_mul_f32 v[44:45], v[104:105], v[86:87] op_sel_hi:[1,0]
	v_pk_fma_f32 v[12:13], v[12:13], v[98:99], v[44:45] op_sel:[0,1,0] op_sel_hi:[1,1,1]
	v_pk_fma_f32 v[38:39], v[12:13], v[86:87], v[38:39] op_sel:[0,1,0] op_sel_hi:[1,1,1]
	s_waitcnt lgkmcnt(1)
	v_pk_mul_f32 v[42:43], v[104:105], v[88:89] op_sel_hi:[1,0]
	v_pk_fma_f32 v[14:15], v[14:15], v[100:101], v[42:43] op_sel:[0,0,0] op_sel_hi:[1,0,1]
	v_pk_fma_f32 v[38:39], v[14:15], v[88:89], v[38:39] op_sel:[0,1,0] op_sel_hi:[1,1,1]
	v_pk_mul_f32 v[44:45], v[104:105], v[90:91] op_sel_hi:[1,0]
	v_pk_fma_f32 v[16:17], v[16:17], v[100:101], v[44:45] op_sel:[0,1,0] op_sel_hi:[1,1,1]
	v_pk_fma_f32 v[38:39], v[16:17], v[90:91], v[38:39] op_sel:[0,1,0] op_sel_hi:[1,1,1]
	s_waitcnt lgkmcnt(0)
	v_pk_mul_f32 v[42:43], v[104:105], v[92:93] op_sel_hi:[1,0]
	v_pk_fma_f32 v[18:19], v[18:19], v[102:103], v[42:43] op_sel:[0,0,0] op_sel_hi:[1,0,1]
	v_pk_fma_f32 v[38:39], v[18:19], v[92:93], v[38:39] op_sel:[0,1,0] op_sel_hi:[1,1,1]
	v_pk_mul_f32 v[44:45], v[104:105], v[94:95] op_sel_hi:[1,0]
	v_pk_fma_f32 v[20:21], v[20:21], v[102:103], v[44:45] op_sel:[0,1,0] op_sel_hi:[1,1,1]
	v_pk_fma_f32 v[38:39], v[20:21], v[94:95], v[38:39] op_sel:[0,1,0] op_sel_hi:[1,1,1]
	s_add_u32 s14, s14, 0x1000
	s_addc_u32 s15, s15, 0
	v_add_f32_dpp v38, v38, v38 row_ror:8 row_mask:0xf bank_mask:0x3 bound_ctrl:1
	v_add_f32_dpp v38, v39, v39 row_ror:8 row_mask:0xf bank_mask:0xc bound_ctrl:1
	ds_read_b64 v[72:73], v3 offset:45824
	ds_read_b128 v[48:51], v2 offset:26880
	v_add_f32_dpp v38, v38, v38 row_half_mirror row_mask:0xf bank_mask:0xf bound_ctrl:1
	ds_read_b128 v[64:67], v2 offset:42240
	ds_read_b128 v[52:55], v2 offset:27136
	v_add_f32_dpp v38, v38, v38 quad_perm:[1,0,3,2] row_mask:0xf bank_mask:0xf bound_ctrl:1
	ds_read_b128 v[56:59], v2 offset:27392
	ds_read_b128 v[68:71], v2 offset:42496
	v_add_f32_dpp v38, v38, v38 quad_perm:[2,3,0,1] row_mask:0xf bank_mask:0xf bound_ctrl:1
	ds_read_b128 v[60:63], v2 offset:27648
	s_nop 0
	v_mov_b32_dpp v39, v38 row_ror:8 row_mask:0xf bank_mask:0xf bound_ctrl:1
	v_cvt_pk_bf16_f32 v47, v38, v39
	s_mov_b64 exec, s[2:3]
	global_store_dword v46, v47, s[14:15] offset:-4096
	s_mov_b64 exec, -1
	s_waitcnt lgkmcnt(4)
	v_pk_mul_f32 v[42:43], v[72:73], v[48:49] op_sel_hi:[1,0]
	v_pk_fma_f32 v[6:7], v[6:7], v[64:65], v[42:43] op_sel:[0,0,0] op_sel_hi:[1,0,1]
	v_pk_mul_f32 v[38:39], v[6:7], v[48:49] op_sel:[0,1] op_sel_hi:[1,1]
	v_pk_mul_f32 v[44:45], v[72:73], v[50:51] op_sel_hi:[1,0]
	v_pk_fma_f32 v[8:9], v[8:9], v[64:65], v[44:45] op_sel:[0,1,0] op_sel_hi:[1,1,1]
	v_pk_fma_f32 v[38:39], v[8:9], v[50:51], v[38:39] op_sel:[0,1,0] op_sel_hi:[1,1,1]
	s_waitcnt lgkmcnt(3)
	v_pk_mul_f32 v[42:43], v[72:73], v[52:53] op_sel_hi:[1,0]
	v_pk_fma_f32 v[10:11], v[10:11], v[66:67], v[42:43] op_sel:[0,0,0] op_sel_hi:[1,0,1]
	v_pk_fma_f32 v[38:39], v[10:11], v[52:53], v[38:39] op_sel:[0,1,0] op_sel_hi:[1,1,1]
	v_pk_mul_f32 v[44:45], v[72:73], v[54:55] op_sel_hi:[1,0]
	v_pk_fma_f32 v[12:13], v[12:13], v[66:67], v[44:45] op_sel:[0,1,0] op_sel_hi:[1,1,1]
	v_pk_fma_f32 v[38:39], v[12:13], v[54:55], v[38:39] op_sel:[0,1,0] op_sel_hi:[1,1,1]
	s_waitcnt lgkmcnt(1)
	v_pk_mul_f32 v[42:43], v[72:73], v[56:57] op_sel_hi:[1,0]
	v_pk_fma_f32 v[14:15], v[14:15], v[68:69], v[42:43] op_sel:[0,0,0] op_sel_hi:[1,0,1]
	v_pk_fma_f32 v[38:39], v[14:15], v[56:57], v[38:39] op_sel:[0,1,0] op_sel_hi:[1,1,1]
	v_pk_mul_f32 v[44:45], v[72:73], v[58:59] op_sel_hi:[1,0]
	v_pk_fma_f32 v[16:17], v[16:17], v[68:69], v[44:45] op_sel:[0,1,0] op_sel_hi:[1,1,1]
	v_pk_fma_f32 v[38:39], v[16:17], v[58:59], v[38:39] op_sel:[0,1,0] op_sel_hi:[1,1,1]
	s_waitcnt lgkmcnt(0)
	v_pk_mul_f32 v[42:43], v[72:73], v[60:61] op_sel_hi:[1,0]
	v_pk_fma_f32 v[18:19], v[18:19], v[70:71], v[42:43] op_sel:[0,0,0] op_sel_hi:[1,0,1]
	v_pk_fma_f32 v[38:39], v[18:19], v[60:61], v[38:39] op_sel:[0,1,0] op_sel_hi:[1,1,1]
	v_pk_mul_f32 v[44:45], v[72:73], v[62:63] op_sel_hi:[1,0]
	v_pk_fma_f32 v[20:21], v[20:21], v[70:71], v[44:45] op_sel:[0,1,0] op_sel_hi:[1,1,1]
	v_pk_fma_f32 v[38:39], v[20:21], v[62:63], v[38:39] op_sel:[0,1,0] op_sel_hi:[1,1,1]
	s_add_u32 s14, s14, 0x1000
	s_addc_u32 s15, s15, 0
	v_add_f32_dpp v38, v38, v38 row_ror:8 row_mask:0xf bank_mask:0x3 bound_ctrl:1
	v_add_f32_dpp v38, v39, v39 row_ror:8 row_mask:0xf bank_mask:0xc bound_ctrl:1
	ds_read_b64 v[104:105], v3 offset:46080
	ds_read_b128 v[80:83], v2 offset:27904
	v_add_f32_dpp v38, v38, v38 row_half_mirror row_mask:0xf bank_mask:0xf bound_ctrl:1
	ds_read_b128 v[96:99], v2 offset:42752
	ds_read_b128 v[84:87], v2 offset:28160
	v_add_f32_dpp v38, v38, v38 quad_perm:[1,0,3,2] row_mask:0xf bank_mask:0xf bound_ctrl:1
	ds_read_b128 v[88:91], v2 offset:28416
	ds_read_b128 v[100:103], v2 offset:43008
	v_add_f32_dpp v38, v38, v38 quad_perm:[2,3,0,1] row_mask:0xf bank_mask:0xf bound_ctrl:1
	ds_read_b128 v[92:95], v2 offset:28672
	s_nop 0
	v_mov_b32_dpp v39, v38 row_ror:8 row_mask:0xf bank_mask:0xf bound_ctrl:1
	v_cvt_pk_bf16_f32 v47, v38, v39
	s_mov_b64 exec, s[2:3]
	global_store_dword v46, v47, s[14:15] offset:-4096
	s_mov_b64 exec, -1
	s_waitcnt lgkmcnt(4)
	v_pk_mul_f32 v[42:43], v[104:105], v[80:81] op_sel_hi:[1,0]
	v_pk_fma_f32 v[6:7], v[6:7], v[96:97], v[42:43] op_sel:[0,0,0] op_sel_hi:[1,0,1]
	v_pk_mul_f32 v[38:39], v[6:7], v[80:81] op_sel:[0,1] op_sel_hi:[1,1]
	v_pk_mul_f32 v[44:45], v[104:105], v[82:83] op_sel_hi:[1,0]
	v_pk_fma_f32 v[8:9], v[8:9], v[96:97], v[44:45] op_sel:[0,1,0] op_sel_hi:[1,1,1]
	v_pk_fma_f32 v[38:39], v[8:9], v[82:83], v[38:39] op_sel:[0,1,0] op_sel_hi:[1,1,1]
	s_waitcnt lgkmcnt(3)
	v_pk_mul_f32 v[42:43], v[104:105], v[84:85] op_sel_hi:[1,0]
	v_pk_fma_f32 v[10:11], v[10:11], v[98:99], v[42:43] op_sel:[0,0,0] op_sel_hi:[1,0,1]
	v_pk_fma_f32 v[38:39], v[10:11], v[84:85], v[38:39] op_sel:[0,1,0] op_sel_hi:[1,1,1]
	v_pk_mul_f32 v[44:45], v[104:105], v[86:87] op_sel_hi:[1,0]
	v_pk_fma_f32 v[12:13], v[12:13], v[98:99], v[44:45] op_sel:[0,1,0] op_sel_hi:[1,1,1]
	v_pk_fma_f32 v[38:39], v[12:13], v[86:87], v[38:39] op_sel:[0,1,0] op_sel_hi:[1,1,1]
	s_waitcnt lgkmcnt(1)
	v_pk_mul_f32 v[42:43], v[104:105], v[88:89] op_sel_hi:[1,0]
	v_pk_fma_f32 v[14:15], v[14:15], v[100:101], v[42:43] op_sel:[0,0,0] op_sel_hi:[1,0,1]
	v_pk_fma_f32 v[38:39], v[14:15], v[88:89], v[38:39] op_sel:[0,1,0] op_sel_hi:[1,1,1]
	v_pk_mul_f32 v[44:45], v[104:105], v[90:91] op_sel_hi:[1,0]
	v_pk_fma_f32 v[16:17], v[16:17], v[100:101], v[44:45] op_sel:[0,1,0] op_sel_hi:[1,1,1]
	v_pk_fma_f32 v[38:39], v[16:17], v[90:91], v[38:39] op_sel:[0,1,0] op_sel_hi:[1,1,1]
	s_waitcnt lgkmcnt(0)
	v_pk_mul_f32 v[42:43], v[104:105], v[92:93] op_sel_hi:[1,0]
	v_pk_fma_f32 v[18:19], v[18:19], v[102:103], v[42:43] op_sel:[0,0,0] op_sel_hi:[1,0,1]
	v_pk_fma_f32 v[38:39], v[18:19], v[92:93], v[38:39] op_sel:[0,1,0] op_sel_hi:[1,1,1]
	v_pk_mul_f32 v[44:45], v[104:105], v[94:95] op_sel_hi:[1,0]
	v_pk_fma_f32 v[20:21], v[20:21], v[102:103], v[44:45] op_sel:[0,1,0] op_sel_hi:[1,1,1]
	v_pk_fma_f32 v[38:39], v[20:21], v[94:95], v[38:39] op_sel:[0,1,0] op_sel_hi:[1,1,1]
	s_add_u32 s14, s14, 0x1000
	s_addc_u32 s15, s15, 0
	v_add_f32_dpp v38, v38, v38 row_ror:8 row_mask:0xf bank_mask:0x3 bound_ctrl:1
	v_add_f32_dpp v38, v39, v39 row_ror:8 row_mask:0xf bank_mask:0xc bound_ctrl:1
	ds_read_b64 v[72:73], v3 offset:46336
	ds_read_b128 v[48:51], v2 offset:28928
	v_add_f32_dpp v38, v38, v38 row_half_mirror row_mask:0xf bank_mask:0xf bound_ctrl:1
	ds_read_b128 v[64:67], v2 offset:43264
	ds_read_b128 v[52:55], v2 offset:29184
	v_add_f32_dpp v38, v38, v38 quad_perm:[1,0,3,2] row_mask:0xf bank_mask:0xf bound_ctrl:1
	ds_read_b128 v[56:59], v2 offset:29440
	ds_read_b128 v[68:71], v2 offset:43520
	v_add_f32_dpp v38, v38, v38 quad_perm:[2,3,0,1] row_mask:0xf bank_mask:0xf bound_ctrl:1
	ds_read_b128 v[60:63], v2 offset:29696
	s_nop 0
	v_mov_b32_dpp v39, v38 row_ror:8 row_mask:0xf bank_mask:0xf bound_ctrl:1
	v_cvt_pk_bf16_f32 v47, v38, v39
	s_mov_b64 exec, s[2:3]
	global_store_dword v46, v47, s[14:15] offset:-4096
	s_mov_b64 exec, -1
	s_waitcnt lgkmcnt(4)
	v_pk_mul_f32 v[42:43], v[72:73], v[48:49] op_sel_hi:[1,0]
	v_pk_fma_f32 v[6:7], v[6:7], v[64:65], v[42:43] op_sel:[0,0,0] op_sel_hi:[1,0,1]
	v_pk_mul_f32 v[38:39], v[6:7], v[48:49] op_sel:[0,1] op_sel_hi:[1,1]
	v_pk_mul_f32 v[44:45], v[72:73], v[50:51] op_sel_hi:[1,0]
	v_pk_fma_f32 v[8:9], v[8:9], v[64:65], v[44:45] op_sel:[0,1,0] op_sel_hi:[1,1,1]
	v_pk_fma_f32 v[38:39], v[8:9], v[50:51], v[38:39] op_sel:[0,1,0] op_sel_hi:[1,1,1]
	s_waitcnt lgkmcnt(3)
	v_pk_mul_f32 v[42:43], v[72:73], v[52:53] op_sel_hi:[1,0]
	v_pk_fma_f32 v[10:11], v[10:11], v[66:67], v[42:43] op_sel:[0,0,0] op_sel_hi:[1,0,1]
	v_pk_fma_f32 v[38:39], v[10:11], v[52:53], v[38:39] op_sel:[0,1,0] op_sel_hi:[1,1,1]
	v_pk_mul_f32 v[44:45], v[72:73], v[54:55] op_sel_hi:[1,0]
	v_pk_fma_f32 v[12:13], v[12:13], v[66:67], v[44:45] op_sel:[0,1,0] op_sel_hi:[1,1,1]
	v_pk_fma_f32 v[38:39], v[12:13], v[54:55], v[38:39] op_sel:[0,1,0] op_sel_hi:[1,1,1]
	s_waitcnt lgkmcnt(1)
	v_pk_mul_f32 v[42:43], v[72:73], v[56:57] op_sel_hi:[1,0]
	v_pk_fma_f32 v[14:15], v[14:15], v[68:69], v[42:43] op_sel:[0,0,0] op_sel_hi:[1,0,1]
	v_pk_fma_f32 v[38:39], v[14:15], v[56:57], v[38:39] op_sel:[0,1,0] op_sel_hi:[1,1,1]
	v_pk_mul_f32 v[44:45], v[72:73], v[58:59] op_sel_hi:[1,0]
	v_pk_fma_f32 v[16:17], v[16:17], v[68:69], v[44:45] op_sel:[0,1,0] op_sel_hi:[1,1,1]
	v_pk_fma_f32 v[38:39], v[16:17], v[58:59], v[38:39] op_sel:[0,1,0] op_sel_hi:[1,1,1]
	s_waitcnt lgkmcnt(0)
	v_pk_mul_f32 v[42:43], v[72:73], v[60:61] op_sel_hi:[1,0]
	v_pk_fma_f32 v[18:19], v[18:19], v[70:71], v[42:43] op_sel:[0,0,0] op_sel_hi:[1,0,1]
	v_pk_fma_f32 v[38:39], v[18:19], v[60:61], v[38:39] op_sel:[0,1,0] op_sel_hi:[1,1,1]
	v_pk_mul_f32 v[44:45], v[72:73], v[62:63] op_sel_hi:[1,0]
	v_pk_fma_f32 v[20:21], v[20:21], v[70:71], v[44:45] op_sel:[0,1,0] op_sel_hi:[1,1,1]
	v_pk_fma_f32 v[38:39], v[20:21], v[62:63], v[38:39] op_sel:[0,1,0] op_sel_hi:[1,1,1]
	s_add_u32 s14, s14, 0x1000
	s_addc_u32 s15, s15, 0
	v_add_f32_dpp v38, v38, v38 row_ror:8 row_mask:0xf bank_mask:0x3 bound_ctrl:1
	v_add_f32_dpp v38, v39, v39 row_ror:8 row_mask:0xf bank_mask:0xc bound_ctrl:1
	ds_read_b64 v[104:105], v3 offset:46592
	ds_read_b128 v[80:83], v2 offset:29952
	v_add_f32_dpp v38, v38, v38 row_half_mirror row_mask:0xf bank_mask:0xf bound_ctrl:1
	ds_read_b128 v[96:99], v2 offset:43776
	ds_read_b128 v[84:87], v2 offset:30208
	v_add_f32_dpp v38, v38, v38 quad_perm:[1,0,3,2] row_mask:0xf bank_mask:0xf bound_ctrl:1
	ds_read_b128 v[88:91], v2 offset:30464
	ds_read_b128 v[100:103], v2 offset:44032
	v_add_f32_dpp v38, v38, v38 quad_perm:[2,3,0,1] row_mask:0xf bank_mask:0xf bound_ctrl:1
	ds_read_b128 v[92:95], v2 offset:30720
	s_nop 0
	v_mov_b32_dpp v39, v38 row_ror:8 row_mask:0xf bank_mask:0xf bound_ctrl:1
	v_cvt_pk_bf16_f32 v47, v38, v39
	s_mov_b64 exec, s[2:3]
	global_store_dword v46, v47, s[14:15] offset:-4096
	s_mov_b64 exec, -1
	s_waitcnt lgkmcnt(4)
	v_pk_mul_f32 v[42:43], v[104:105], v[80:81] op_sel_hi:[1,0]
	v_pk_fma_f32 v[6:7], v[6:7], v[96:97], v[42:43] op_sel:[0,0,0] op_sel_hi:[1,0,1]
	v_pk_mul_f32 v[38:39], v[6:7], v[80:81] op_sel:[0,1] op_sel_hi:[1,1]
	v_pk_mul_f32 v[44:45], v[104:105], v[82:83] op_sel_hi:[1,0]
	v_pk_fma_f32 v[8:9], v[8:9], v[96:97], v[44:45] op_sel:[0,1,0] op_sel_hi:[1,1,1]
	v_pk_fma_f32 v[38:39], v[8:9], v[82:83], v[38:39] op_sel:[0,1,0] op_sel_hi:[1,1,1]
	s_waitcnt lgkmcnt(3)
	v_pk_mul_f32 v[42:43], v[104:105], v[84:85] op_sel_hi:[1,0]
	v_pk_fma_f32 v[10:11], v[10:11], v[98:99], v[42:43] op_sel:[0,0,0] op_sel_hi:[1,0,1]
	v_pk_fma_f32 v[38:39], v[10:11], v[84:85], v[38:39] op_sel:[0,1,0] op_sel_hi:[1,1,1]
	v_pk_mul_f32 v[44:45], v[104:105], v[86:87] op_sel_hi:[1,0]
	v_pk_fma_f32 v[12:13], v[12:13], v[98:99], v[44:45] op_sel:[0,1,0] op_sel_hi:[1,1,1]
	v_pk_fma_f32 v[38:39], v[12:13], v[86:87], v[38:39] op_sel:[0,1,0] op_sel_hi:[1,1,1]
	s_waitcnt lgkmcnt(1)
	v_pk_mul_f32 v[42:43], v[104:105], v[88:89] op_sel_hi:[1,0]
	v_pk_fma_f32 v[14:15], v[14:15], v[100:101], v[42:43] op_sel:[0,0,0] op_sel_hi:[1,0,1]
	v_pk_fma_f32 v[38:39], v[14:15], v[88:89], v[38:39] op_sel:[0,1,0] op_sel_hi:[1,1,1]
	v_pk_mul_f32 v[44:45], v[104:105], v[90:91] op_sel_hi:[1,0]
	v_pk_fma_f32 v[16:17], v[16:17], v[100:101], v[44:45] op_sel:[0,1,0] op_sel_hi:[1,1,1]
	v_pk_fma_f32 v[38:39], v[16:17], v[90:91], v[38:39] op_sel:[0,1,0] op_sel_hi:[1,1,1]
	s_waitcnt lgkmcnt(0)
	v_pk_mul_f32 v[42:43], v[104:105], v[92:93] op_sel_hi:[1,0]
	v_pk_fma_f32 v[18:19], v[18:19], v[102:103], v[42:43] op_sel:[0,0,0] op_sel_hi:[1,0,1]
	v_pk_fma_f32 v[38:39], v[18:19], v[92:93], v[38:39] op_sel:[0,1,0] op_sel_hi:[1,1,1]
	v_pk_mul_f32 v[44:45], v[104:105], v[94:95] op_sel_hi:[1,0]
	v_pk_fma_f32 v[20:21], v[20:21], v[102:103], v[44:45] op_sel:[0,1,0] op_sel_hi:[1,1,1]
	v_pk_fma_f32 v[38:39], v[20:21], v[94:95], v[38:39] op_sel:[0,1,0] op_sel_hi:[1,1,1]
	s_add_u32 s14, s14, 0x1000
	s_addc_u32 s15, s15, 0
	v_add_f32_dpp v38, v38, v38 row_ror:8 row_mask:0xf bank_mask:0x3 bound_ctrl:1
	v_add_f32_dpp v38, v39, v39 row_ror:8 row_mask:0xf bank_mask:0xc bound_ctrl:1
	ds_read_b64 v[72:73], v3 offset:46848
	ds_read_b128 v[48:51], v2 offset:30976
	v_add_f32_dpp v38, v38, v38 row_half_mirror row_mask:0xf bank_mask:0xf bound_ctrl:1
	ds_read_b128 v[64:67], v2 offset:44288
	ds_read_b128 v[52:55], v2 offset:31232
	v_add_f32_dpp v38, v38, v38 quad_perm:[1,0,3,2] row_mask:0xf bank_mask:0xf bound_ctrl:1
	ds_read_b128 v[56:59], v2 offset:31488
	ds_read_b128 v[68:71], v2 offset:44544
	v_add_f32_dpp v38, v38, v38 quad_perm:[2,3,0,1] row_mask:0xf bank_mask:0xf bound_ctrl:1
	ds_read_b128 v[60:63], v2 offset:31744
	s_nop 0
	v_mov_b32_dpp v39, v38 row_ror:8 row_mask:0xf bank_mask:0xf bound_ctrl:1
	v_cvt_pk_bf16_f32 v47, v38, v39
	s_mov_b64 exec, s[2:3]
	global_store_dword v46, v47, s[14:15] offset:-4096
	s_mov_b64 exec, -1
	s_waitcnt lgkmcnt(4)
	v_pk_mul_f32 v[42:43], v[72:73], v[48:49] op_sel_hi:[1,0]
	v_pk_fma_f32 v[6:7], v[6:7], v[64:65], v[42:43] op_sel:[0,0,0] op_sel_hi:[1,0,1]
	v_pk_mul_f32 v[38:39], v[6:7], v[48:49] op_sel:[0,1] op_sel_hi:[1,1]
	v_pk_mul_f32 v[44:45], v[72:73], v[50:51] op_sel_hi:[1,0]
	v_pk_fma_f32 v[8:9], v[8:9], v[64:65], v[44:45] op_sel:[0,1,0] op_sel_hi:[1,1,1]
	v_pk_fma_f32 v[38:39], v[8:9], v[50:51], v[38:39] op_sel:[0,1,0] op_sel_hi:[1,1,1]
	s_waitcnt lgkmcnt(3)
	v_pk_mul_f32 v[42:43], v[72:73], v[52:53] op_sel_hi:[1,0]
	v_pk_fma_f32 v[10:11], v[10:11], v[66:67], v[42:43] op_sel:[0,0,0] op_sel_hi:[1,0,1]
	v_pk_fma_f32 v[38:39], v[10:11], v[52:53], v[38:39] op_sel:[0,1,0] op_sel_hi:[1,1,1]
	v_pk_mul_f32 v[44:45], v[72:73], v[54:55] op_sel_hi:[1,0]
	v_pk_fma_f32 v[12:13], v[12:13], v[66:67], v[44:45] op_sel:[0,1,0] op_sel_hi:[1,1,1]
	v_pk_fma_f32 v[38:39], v[12:13], v[54:55], v[38:39] op_sel:[0,1,0] op_sel_hi:[1,1,1]
	s_waitcnt lgkmcnt(1)
	v_pk_mul_f32 v[42:43], v[72:73], v[56:57] op_sel_hi:[1,0]
	v_pk_fma_f32 v[14:15], v[14:15], v[68:69], v[42:43] op_sel:[0,0,0] op_sel_hi:[1,0,1]
	v_pk_fma_f32 v[38:39], v[14:15], v[56:57], v[38:39] op_sel:[0,1,0] op_sel_hi:[1,1,1]
	v_pk_mul_f32 v[44:45], v[72:73], v[58:59] op_sel_hi:[1,0]
	v_pk_fma_f32 v[16:17], v[16:17], v[68:69], v[44:45] op_sel:[0,1,0] op_sel_hi:[1,1,1]
	v_pk_fma_f32 v[38:39], v[16:17], v[58:59], v[38:39] op_sel:[0,1,0] op_sel_hi:[1,1,1]
	s_waitcnt lgkmcnt(0)
	v_pk_mul_f32 v[42:43], v[72:73], v[60:61] op_sel_hi:[1,0]
	v_pk_fma_f32 v[18:19], v[18:19], v[70:71], v[42:43] op_sel:[0,0,0] op_sel_hi:[1,0,1]
	v_pk_fma_f32 v[38:39], v[18:19], v[60:61], v[38:39] op_sel:[0,1,0] op_sel_hi:[1,1,1]
	v_pk_mul_f32 v[44:45], v[72:73], v[62:63] op_sel_hi:[1,0]
	v_pk_fma_f32 v[20:21], v[20:21], v[70:71], v[44:45] op_sel:[0,1,0] op_sel_hi:[1,1,1]
	v_pk_fma_f32 v[38:39], v[20:21], v[62:63], v[38:39] op_sel:[0,1,0] op_sel_hi:[1,1,1]
	s_add_u32 s14, s14, 0x1000
	s_addc_u32 s15, s15, 0
	v_add_f32_dpp v38, v38, v38 row_ror:8 row_mask:0xf bank_mask:0x3 bound_ctrl:1
	v_add_f32_dpp v38, v39, v39 row_ror:8 row_mask:0xf bank_mask:0xc bound_ctrl:1
	ds_read_b64 v[104:105], v3 offset:47104
	ds_read_b128 v[80:83], v2 offset:32000
	v_add_f32_dpp v38, v38, v38 row_half_mirror row_mask:0xf bank_mask:0xf bound_ctrl:1
	ds_read_b128 v[96:99], v2 offset:44800
	ds_read_b128 v[84:87], v2 offset:32256
	v_add_f32_dpp v38, v38, v38 quad_perm:[1,0,3,2] row_mask:0xf bank_mask:0xf bound_ctrl:1
	ds_read_b128 v[88:91], v2 offset:32512
	ds_read_b128 v[100:103], v2 offset:45056
	v_add_f32_dpp v38, v38, v38 quad_perm:[2,3,0,1] row_mask:0xf bank_mask:0xf bound_ctrl:1
	ds_read_b128 v[92:95], v2 offset:32768
	s_nop 0
	v_mov_b32_dpp v39, v38 row_ror:8 row_mask:0xf bank_mask:0xf bound_ctrl:1
	v_cvt_pk_bf16_f32 v47, v38, v39
	s_mov_b64 exec, s[2:3]
	global_store_dword v46, v47, s[14:15] offset:-4096
	s_mov_b64 exec, -1
	s_waitcnt lgkmcnt(4)
	v_pk_mul_f32 v[42:43], v[104:105], v[80:81] op_sel_hi:[1,0]
	v_pk_fma_f32 v[6:7], v[6:7], v[96:97], v[42:43] op_sel:[0,0,0] op_sel_hi:[1,0,1]
	v_pk_mul_f32 v[38:39], v[6:7], v[80:81] op_sel:[0,1] op_sel_hi:[1,1]
	v_pk_mul_f32 v[44:45], v[104:105], v[82:83] op_sel_hi:[1,0]
	v_pk_fma_f32 v[8:9], v[8:9], v[96:97], v[44:45] op_sel:[0,1,0] op_sel_hi:[1,1,1]
	v_pk_fma_f32 v[38:39], v[8:9], v[82:83], v[38:39] op_sel:[0,1,0] op_sel_hi:[1,1,1]
	s_waitcnt lgkmcnt(3)
	v_pk_mul_f32 v[42:43], v[104:105], v[84:85] op_sel_hi:[1,0]
	v_pk_fma_f32 v[10:11], v[10:11], v[98:99], v[42:43] op_sel:[0,0,0] op_sel_hi:[1,0,1]
	v_pk_fma_f32 v[38:39], v[10:11], v[84:85], v[38:39] op_sel:[0,1,0] op_sel_hi:[1,1,1]
	v_pk_mul_f32 v[44:45], v[104:105], v[86:87] op_sel_hi:[1,0]
	v_pk_fma_f32 v[12:13], v[12:13], v[98:99], v[44:45] op_sel:[0,1,0] op_sel_hi:[1,1,1]
	v_pk_fma_f32 v[38:39], v[12:13], v[86:87], v[38:39] op_sel:[0,1,0] op_sel_hi:[1,1,1]
	s_waitcnt lgkmcnt(1)
	v_pk_mul_f32 v[42:43], v[104:105], v[88:89] op_sel_hi:[1,0]
	v_pk_fma_f32 v[14:15], v[14:15], v[100:101], v[42:43] op_sel:[0,0,0] op_sel_hi:[1,0,1]
	v_pk_fma_f32 v[38:39], v[14:15], v[88:89], v[38:39] op_sel:[0,1,0] op_sel_hi:[1,1,1]
	v_pk_mul_f32 v[44:45], v[104:105], v[90:91] op_sel_hi:[1,0]
	v_pk_fma_f32 v[16:17], v[16:17], v[100:101], v[44:45] op_sel:[0,1,0] op_sel_hi:[1,1,1]
	v_pk_fma_f32 v[38:39], v[16:17], v[90:91], v[38:39] op_sel:[0,1,0] op_sel_hi:[1,1,1]
	s_waitcnt lgkmcnt(0)
	v_pk_mul_f32 v[42:43], v[104:105], v[92:93] op_sel_hi:[1,0]
	v_pk_fma_f32 v[18:19], v[18:19], v[102:103], v[42:43] op_sel:[0,0,0] op_sel_hi:[1,0,1]
	v_pk_fma_f32 v[38:39], v[18:19], v[92:93], v[38:39] op_sel:[0,1,0] op_sel_hi:[1,1,1]
	v_pk_mul_f32 v[44:45], v[104:105], v[94:95] op_sel_hi:[1,0]
	v_pk_fma_f32 v[20:21], v[20:21], v[102:103], v[44:45] op_sel:[0,1,0] op_sel_hi:[1,1,1]
	v_pk_fma_f32 v[38:39], v[20:21], v[94:95], v[38:39] op_sel:[0,1,0] op_sel_hi:[1,1,1]
	s_add_u32 s14, s14, 0x1000
	s_addc_u32 s15, s15, 0
	v_add_f32_dpp v38, v38, v38 row_ror:8 row_mask:0xf bank_mask:0x3 bound_ctrl:1
	v_add_f32_dpp v38, v39, v39 row_ror:8 row_mask:0xf bank_mask:0xc bound_ctrl:1
	ds_read_b64 v[72:73], v23 offset:37120
	ds_read_b128 v[48:51], v2 offset:49408
	v_add_f32_dpp v38, v38, v38 row_half_mirror row_mask:0xf bank_mask:0xf bound_ctrl:1
	ds_read_b128 v[64:67], v22 offset:33024
	ds_read_b128 v[52:55], v2 offset:49664
	v_add_f32_dpp v38, v38, v38 quad_perm:[1,0,3,2] row_mask:0xf bank_mask:0xf bound_ctrl:1
	ds_read_b128 v[56:59], v2 offset:49920
	ds_read_b128 v[68:71], v22 offset:33280
	v_add_f32_dpp v38, v38, v38 quad_perm:[2,3,0,1] row_mask:0xf bank_mask:0xf bound_ctrl:1
	ds_read_b128 v[60:63], v2 offset:50176
	s_nop 0
	v_mov_b32_dpp v39, v38 row_ror:8 row_mask:0xf bank_mask:0xf bound_ctrl:1
	v_cvt_pk_bf16_f32 v47, v38, v39
	s_mov_b64 exec, s[2:3]
	global_store_dword v46, v47, s[14:15] offset:-4096
	s_mov_b64 exec, -1
	s_waitcnt vmcnt(8)
	v_lshlrev_b32_e32 v144, 16, v110
	v_lshlrev_b32_e32 v145, 16, v111
	v_and_b32_e32 v146, s17, v110
	v_and_b32_e32 v147, s17, v111
	v_lshlrev_b32_e32 v148, 16, v112
	v_lshlrev_b32_e32 v149, 16, v113
	v_and_b32_e32 v150, s17, v112
	v_and_b32_e32 v151, s17, v113
	v_lshlrev_b32_e32 v152, 16, v114
	v_and_b32_e32 v153, s17, v114
	v_rcp_f32_e32 v25, v24
	v_mul_f32_e32 v149, v24, v149
	v_mul_f32_e32 v151, v24, v151
	v_mul_f32_e32 v145, 0x3db504f3, v145
	v_mul_f32_e32 v147, 0x3db504f3, v147
	v_cndmask_b32_e64 v27, 1.0, v25, s[20:21]
	v_mul_f32_e32 v24, v24, v26
	v_mul_f32_e32 v152, v27, v152
	v_mul_f32_e32 v153, v27, v153
	ds_write_b128 v29, v[144:147] offset:256
	ds_write_b128 v29, v[148:151] offset:8448
	ds_write_b64 v30, v[116:117] offset:256
	ds_write_b64 v31, v[152:153] offset:256
	s_add_i32 s16, s16, 8
	s_waitcnt lgkmcnt(0)
	s_barrier
	s_cmpk_lt_u32 s16, 0x800
	s_cbranch_scc0 .Lgla2_done
	global_load_dword v110, v32, s[10:11]
	global_load_dword v111, v32, s[10:11] offset:-1024
	global_load_dword v112, v33, s[10:11]
	global_load_dword v113, v33, s[10:11] offset:-1024
	global_load_dword v114, v34, s[10:11]
	global_load_dword v116, v35, s[12:13]
	global_load_dword v117, v35, s[12:13] offset:4
	s_add_u32 s10, s10, 0x18000
	s_addc_u32 s11, s11, 0
	s_add_u32 s12, s12, 0x4000
	s_addc_u32 s13, s13, 0
	s_waitcnt lgkmcnt(4)
	v_pk_mul_f32 v[42:43], v[72:73], v[48:49] op_sel_hi:[1,0]
	v_pk_fma_f32 v[6:7], v[6:7], v[64:65], v[42:43] op_sel:[0,0,0] op_sel_hi:[1,0,1]
	v_pk_mul_f32 v[38:39], v[6:7], v[48:49] op_sel:[0,1] op_sel_hi:[1,1]
	v_pk_mul_f32 v[44:45], v[72:73], v[50:51] op_sel_hi:[1,0]
	v_pk_fma_f32 v[8:9], v[8:9], v[64:65], v[44:45] op_sel:[0,1,0] op_sel_hi:[1,1,1]
	v_pk_fma_f32 v[38:39], v[8:9], v[50:51], v[38:39] op_sel:[0,1,0] op_sel_hi:[1,1,1]
	s_waitcnt lgkmcnt(3)
	v_pk_mul_f32 v[42:43], v[72:73], v[52:53] op_sel_hi:[1,0]
	v_pk_fma_f32 v[10:11], v[10:11], v[66:67], v[42:43] op_sel:[0,0,0] op_sel_hi:[1,0,1]
	v_pk_fma_f32 v[38:39], v[10:11], v[52:53], v[38:39] op_sel:[0,1,0] op_sel_hi:[1,1,1]
	v_pk_mul_f32 v[44:45], v[72:73], v[54:55] op_sel_hi:[1,0]
	v_pk_fma_f32 v[12:13], v[12:13], v[66:67], v[44:45] op_sel:[0,1,0] op_sel_hi:[1,1,1]
	v_pk_fma_f32 v[38:39], v[12:13], v[54:55], v[38:39] op_sel:[0,1,0] op_sel_hi:[1,1,1]
	s_waitcnt lgkmcnt(1)
	v_pk_mul_f32 v[42:43], v[72:73], v[56:57] op_sel_hi:[1,0]
	v_pk_fma_f32 v[14:15], v[14:15], v[68:69], v[42:43] op_sel:[0,0,0] op_sel_hi:[1,0,1]
	v_pk_fma_f32 v[38:39], v[14:15], v[56:57], v[38:39] op_sel:[0,1,0] op_sel_hi:[1,1,1]
	v_pk_mul_f32 v[44:45], v[72:73], v[58:59] op_sel_hi:[1,0]
	v_pk_fma_f32 v[16:17], v[16:17], v[68:69], v[44:45] op_sel:[0,1,0] op_sel_hi:[1,1,1]
	v_pk_fma_f32 v[38:39], v[16:17], v[58:59], v[38:39] op_sel:[0,1,0] op_sel_hi:[1,1,1]
	s_waitcnt lgkmcnt(0)
	v_pk_mul_f32 v[42:43], v[72:73], v[60:61] op_sel_hi:[1,0]
	v_pk_fma_f32 v[18:19], v[18:19], v[70:71], v[42:43] op_sel:[0,0,0] op_sel_hi:[1,0,1]
	v_pk_fma_f32 v[38:39], v[18:19], v[60:61], v[38:39] op_sel:[0,1,0] op_sel_hi:[1,1,1]
	v_pk_mul_f32 v[44:45], v[72:73], v[62:63] op_sel_hi:[1,0]
	v_pk_fma_f32 v[20:21], v[20:21], v[70:71], v[44:45] op_sel:[0,1,0] op_sel_hi:[1,1,1]
	v_pk_fma_f32 v[38:39], v[20:21], v[62:63], v[38:39] op_sel:[0,1,0] op_sel_hi:[1,1,1]
	s_add_u32 s14, s14, 0x1000
	s_addc_u32 s15, s15, 0
	v_add_f32_dpp v38, v38, v38 row_ror:8 row_mask:0xf bank_mask:0x3 bound_ctrl:1
	v_add_f32_dpp v38, v39, v39 row_ror:8 row_mask:0xf bank_mask:0xc bound_ctrl:1
	ds_read_b64 v[104:105], v23 offset:37376
	ds_read_b128 v[80:83], v2 offset:50432
	v_add_f32_dpp v38, v38, v38 row_half_mirror row_mask:0xf bank_mask:0xf bound_ctrl:1
	ds_read_b128 v[96:99], v22 offset:33536
	ds_read_b128 v[84:87], v2 offset:50688
	v_add_f32_dpp v38, v38, v38 quad_perm:[1,0,3,2] row_mask:0xf bank_mask:0xf bound_ctrl:1
	ds_read_b128 v[88:91], v2 offset:50944
	ds_read_b128 v[100:103], v22 offset:33792
	v_add_f32_dpp v38, v38, v38 quad_perm:[2,3,0,1] row_mask:0xf bank_mask:0xf bound_ctrl:1
	ds_read_b128 v[92:95], v2 offset:51200
	s_nop 0
	v_mov_b32_dpp v39, v38 row_ror:8 row_mask:0xf bank_mask:0xf bound_ctrl:1
	v_cvt_pk_bf16_f32 v47, v38, v39
	s_mov_b64 exec, s[2:3]
	global_store_dword v46, v47, s[14:15] offset:-4096
	s_mov_b64 exec, -1
	s_waitcnt lgkmcnt(4)
	v_pk_mul_f32 v[42:43], v[104:105], v[80:81] op_sel_hi:[1,0]
	v_pk_fma_f32 v[6:7], v[6:7], v[96:97], v[42:43] op_sel:[0,0,0] op_sel_hi:[1,0,1]
	v_pk_mul_f32 v[38:39], v[6:7], v[80:81] op_sel:[0,1] op_sel_hi:[1,1]
	v_pk_mul_f32 v[44:45], v[104:105], v[82:83] op_sel_hi:[1,0]
	v_pk_fma_f32 v[8:9], v[8:9], v[96:97], v[44:45] op_sel:[0,1,0] op_sel_hi:[1,1,1]
	v_pk_fma_f32 v[38:39], v[8:9], v[82:83], v[38:39] op_sel:[0,1,0] op_sel_hi:[1,1,1]
	s_waitcnt lgkmcnt(3)
	v_pk_mul_f32 v[42:43], v[104:105], v[84:85] op_sel_hi:[1,0]
	v_pk_fma_f32 v[10:11], v[10:11], v[98:99], v[42:43] op_sel:[0,0,0] op_sel_hi:[1,0,1]
	v_pk_fma_f32 v[38:39], v[10:11], v[84:85], v[38:39] op_sel:[0,1,0] op_sel_hi:[1,1,1]
	v_pk_mul_f32 v[44:45], v[104:105], v[86:87] op_sel_hi:[1,0]
	v_pk_fma_f32 v[12:13], v[12:13], v[98:99], v[44:45] op_sel:[0,1,0] op_sel_hi:[1,1,1]
	v_pk_fma_f32 v[38:39], v[12:13], v[86:87], v[38:39] op_sel:[0,1,0] op_sel_hi:[1,1,1]
	s_waitcnt lgkmcnt(1)
	v_pk_mul_f32 v[42:43], v[104:105], v[88:89] op_sel_hi:[1,0]
	v_pk_fma_f32 v[14:15], v[14:15], v[100:101], v[42:43] op_sel:[0,0,0] op_sel_hi:[1,0,1]
	v_pk_fma_f32 v[38:39], v[14:15], v[88:89], v[38:39] op_sel:[0,1,0] op_sel_hi:[1,1,1]
	v_pk_mul_f32 v[44:45], v[104:105], v[90:91] op_sel_hi:[1,0]
	v_pk_fma_f32 v[16:17], v[16:17], v[100:101], v[44:45] op_sel:[0,1,0] op_sel_hi:[1,1,1]
	v_pk_fma_f32 v[38:39], v[16:17], v[90:91], v[38:39] op_sel:[0,1,0] op_sel_hi:[1,1,1]
	s_waitcnt lgkmcnt(0)
	v_pk_mul_f32 v[42:43], v[104:105], v[92:93] op_sel_hi:[1,0]
	v_pk_fma_f32 v[18:19], v[18:19], v[102:103], v[42:43] op_sel:[0,0,0] op_sel_hi:[1,0,1]
	v_pk_fma_f32 v[38:39], v[18:19], v[92:93], v[38:39] op_sel:[0,1,0] op_sel_hi:[1,1,1]
	v_pk_mul_f32 v[44:45], v[104:105], v[94:95] op_sel_hi:[1,0]
	v_pk_fma_f32 v[20:21], v[20:21], v[102:103], v[44:45] op_sel:[0,1,0] op_sel_hi:[1,1,1]
	v_pk_fma_f32 v[38:39], v[20:21], v[94:95], v[38:39] op_sel:[0,1,0] op_sel_hi:[1,1,1]
	s_add_u32 s14, s14, 0x1000
	s_addc_u32 s15, s15, 0
	v_add_f32_dpp v38, v38, v38 row_ror:8 row_mask:0xf bank_mask:0x3 bound_ctrl:1
	v_add_f32_dpp v38, v39, v39 row_ror:8 row_mask:0xf bank_mask:0xc bound_ctrl:1
	ds_read_b64 v[72:73], v23 offset:37632
	ds_read_b128 v[48:51], v2 offset:51456
	v_add_f32_dpp v38, v38, v38 row_half_mirror row_mask:0xf bank_mask:0xf bound_ctrl:1
	ds_read_b128 v[64:67], v22 offset:34048
	ds_read_b128 v[52:55], v2 offset:51712
	v_add_f32_dpp v38, v38, v38 quad_perm:[1,0,3,2] row_mask:0xf bank_mask:0xf bound_ctrl:1
	ds_read_b128 v[56:59], v2 offset:51968
	ds_read_b128 v[68:71], v22 offset:34304
	v_add_f32_dpp v38, v38, v38 quad_perm:[2,3,0,1] row_mask:0xf bank_mask:0xf bound_ctrl:1
	ds_read_b128 v[60:63], v2 offset:52224
	s_nop 0
	v_mov_b32_dpp v39, v38 row_ror:8 row_mask:0xf bank_mask:0xf bound_ctrl:1
	v_cvt_pk_bf16_f32 v47, v38, v39
	s_mov_b64 exec, s[2:3]
	global_store_dword v46, v47, s[14:15] offset:-4096
	s_mov_b64 exec, -1
	s_waitcnt lgkmcnt(4)
	v_pk_mul_f32 v[42:43], v[72:73], v[48:49] op_sel_hi:[1,0]
	v_pk_fma_f32 v[6:7], v[6:7], v[64:65], v[42:43] op_sel:[0,0,0] op_sel_hi:[1,0,1]
	v_pk_mul_f32 v[38:39], v[6:7], v[48:49] op_sel:[0,1] op_sel_hi:[1,1]
	v_pk_mul_f32 v[44:45], v[72:73], v[50:51] op_sel_hi:[1,0]
	v_pk_fma_f32 v[8:9], v[8:9], v[64:65], v[44:45] op_sel:[0,1,0] op_sel_hi:[1,1,1]
	v_pk_fma_f32 v[38:39], v[8:9], v[50:51], v[38:39] op_sel:[0,1,0] op_sel_hi:[1,1,1]
	s_waitcnt lgkmcnt(3)
	v_pk_mul_f32 v[42:43], v[72:73], v[52:53] op_sel_hi:[1,0]
	v_pk_fma_f32 v[10:11], v[10:11], v[66:67], v[42:43] op_sel:[0,0,0] op_sel_hi:[1,0,1]
	v_pk_fma_f32 v[38:39], v[10:11], v[52:53], v[38:39] op_sel:[0,1,0] op_sel_hi:[1,1,1]
	v_pk_mul_f32 v[44:45], v[72:73], v[54:55] op_sel_hi:[1,0]
	v_pk_fma_f32 v[12:13], v[12:13], v[66:67], v[44:45] op_sel:[0,1,0] op_sel_hi:[1,1,1]
	v_pk_fma_f32 v[38:39], v[12:13], v[54:55], v[38:39] op_sel:[0,1,0] op_sel_hi:[1,1,1]
	s_waitcnt lgkmcnt(1)
	v_pk_mul_f32 v[42:43], v[72:73], v[56:57] op_sel_hi:[1,0]
	v_pk_fma_f32 v[14:15], v[14:15], v[68:69], v[42:43] op_sel:[0,0,0] op_sel_hi:[1,0,1]
	v_pk_fma_f32 v[38:39], v[14:15], v[56:57], v[38:39] op_sel:[0,1,0] op_sel_hi:[1,1,1]
	v_pk_mul_f32 v[44:45], v[72:73], v[58:59] op_sel_hi:[1,0]
	v_pk_fma_f32 v[16:17], v[16:17], v[68:69], v[44:45] op_sel:[0,1,0] op_sel_hi:[1,1,1]
	v_pk_fma_f32 v[38:39], v[16:17], v[58:59], v[38:39] op_sel:[0,1,0] op_sel_hi:[1,1,1]
	s_waitcnt lgkmcnt(0)
	v_pk_mul_f32 v[42:43], v[72:73], v[60:61] op_sel_hi:[1,0]
	v_pk_fma_f32 v[18:19], v[18:19], v[70:71], v[42:43] op_sel:[0,0,0] op_sel_hi:[1,0,1]
	v_pk_fma_f32 v[38:39], v[18:19], v[60:61], v[38:39] op_sel:[0,1,0] op_sel_hi:[1,1,1]
	v_pk_mul_f32 v[44:45], v[72:73], v[62:63] op_sel_hi:[1,0]
	v_pk_fma_f32 v[20:21], v[20:21], v[70:71], v[44:45] op_sel:[0,1,0] op_sel_hi:[1,1,1]
	v_pk_fma_f32 v[38:39], v[20:21], v[62:63], v[38:39] op_sel:[0,1,0] op_sel_hi:[1,1,1]
	s_add_u32 s14, s14, 0x1000
	s_addc_u32 s15, s15, 0
	v_add_f32_dpp v38, v38, v38 row_ror:8 row_mask:0xf bank_mask:0x3 bound_ctrl:1
	v_add_f32_dpp v38, v39, v39 row_ror:8 row_mask:0xf bank_mask:0xc bound_ctrl:1
	ds_read_b64 v[104:105], v23 offset:37888
	ds_read_b128 v[80:83], v2 offset:52480
	v_add_f32_dpp v38, v38, v38 row_half_mirror row_mask:0xf bank_mask:0xf bound_ctrl:1
	ds_read_b128 v[96:99], v22 offset:34560
	ds_read_b128 v[84:87], v2 offset:52736
	v_add_f32_dpp v38, v38, v38 quad_perm:[1,0,3,2] row_mask:0xf bank_mask:0xf bound_ctrl:1
	ds_read_b128 v[88:91], v2 offset:52992
	ds_read_b128 v[100:103], v22 offset:34816
	v_add_f32_dpp v38, v38, v38 quad_perm:[2,3,0,1] row_mask:0xf bank_mask:0xf bound_ctrl:1
	ds_read_b128 v[92:95], v2 offset:53248
	s_nop 0
	v_mov_b32_dpp v39, v38 row_ror:8 row_mask:0xf bank_mask:0xf bound_ctrl:1
	v_cvt_pk_bf16_f32 v47, v38, v39
	s_mov_b64 exec, s[2:3]
	global_store_dword v46, v47, s[14:15] offset:-4096
	s_mov_b64 exec, -1
	s_waitcnt lgkmcnt(4)
	v_pk_mul_f32 v[42:43], v[104:105], v[80:81] op_sel_hi:[1,0]
	v_pk_fma_f32 v[6:7], v[6:7], v[96:97], v[42:43] op_sel:[0,0,0] op_sel_hi:[1,0,1]
	v_pk_mul_f32 v[38:39], v[6:7], v[80:81] op_sel:[0,1] op_sel_hi:[1,1]
	v_pk_mul_f32 v[44:45], v[104:105], v[82:83] op_sel_hi:[1,0]
	v_pk_fma_f32 v[8:9], v[8:9], v[96:97], v[44:45] op_sel:[0,1,0] op_sel_hi:[1,1,1]
	v_pk_fma_f32 v[38:39], v[8:9], v[82:83], v[38:39] op_sel:[0,1,0] op_sel_hi:[1,1,1]
	s_waitcnt lgkmcnt(3)
	v_pk_mul_f32 v[42:43], v[104:105], v[84:85] op_sel_hi:[1,0]
	v_pk_fma_f32 v[10:11], v[10:11], v[98:99], v[42:43] op_sel:[0,0,0] op_sel_hi:[1,0,1]
	v_pk_fma_f32 v[38:39], v[10:11], v[84:85], v[38:39] op_sel:[0,1,0] op_sel_hi:[1,1,1]
	v_pk_mul_f32 v[44:45], v[104:105], v[86:87] op_sel_hi:[1,0]
	v_pk_fma_f32 v[12:13], v[12:13], v[98:99], v[44:45] op_sel:[0,1,0] op_sel_hi:[1,1,1]
	v_pk_fma_f32 v[38:39], v[12:13], v[86:87], v[38:39] op_sel:[0,1,0] op_sel_hi:[1,1,1]
	s_waitcnt lgkmcnt(1)
	v_pk_mul_f32 v[42:43], v[104:105], v[88:89] op_sel_hi:[1,0]
	v_pk_fma_f32 v[14:15], v[14:15], v[100:101], v[42:43] op_sel:[0,0,0] op_sel_hi:[1,0,1]
	v_pk_fma_f32 v[38:39], v[14:15], v[88:89], v[38:39] op_sel:[0,1,0] op_sel_hi:[1,1,1]
	v_pk_mul_f32 v[44:45], v[104:105], v[90:91] op_sel_hi:[1,0]
	v_pk_fma_f32 v[16:17], v[16:17], v[100:101], v[44:45] op_sel:[0,1,0] op_sel_hi:[1,1,1]
	v_pk_fma_f32 v[38:39], v[16:17], v[90:91], v[38:39] op_sel:[0,1,0] op_sel_hi:[1,1,1]
	s_waitcnt lgkmcnt(0)
	v_pk_mul_f32 v[42:43], v[104:105], v[92:93] op_sel_hi:[1,0]
	v_pk_fma_f32 v[18:19], v[18:19], v[102:103], v[42:43] op_sel:[0,0,0] op_sel_hi:[1,0,1]
	v_pk_fma_f32 v[38:39], v[18:19], v[92:93], v[38:39] op_sel:[0,1,0] op_sel_hi:[1,1,1]
	v_pk_mul_f32 v[44:45], v[104:105], v[94:95] op_sel_hi:[1,0]
	v_pk_fma_f32 v[20:21], v[20:21], v[102:103], v[44:45] op_sel:[0,1,0] op_sel_hi:[1,1,1]
	v_pk_fma_f32 v[38:39], v[20:21], v[94:95], v[38:39] op_sel:[0,1,0] op_sel_hi:[1,1,1]
	s_add_u32 s14, s14, 0x1000
	s_addc_u32 s15, s15, 0
	v_add_f32_dpp v38, v38, v38 row_ror:8 row_mask:0xf bank_mask:0x3 bound_ctrl:1
	v_add_f32_dpp v38, v39, v39 row_ror:8 row_mask:0xf bank_mask:0xc bound_ctrl:1
	ds_read_b64 v[72:73], v23 offset:38144
	ds_read_b128 v[48:51], v2 offset:53504
	v_add_f32_dpp v38, v38, v38 row_half_mirror row_mask:0xf bank_mask:0xf bound_ctrl:1
	ds_read_b128 v[64:67], v22 offset:35072
	ds_read_b128 v[52:55], v2 offset:53760
	v_add_f32_dpp v38, v38, v38 quad_perm:[1,0,3,2] row_mask:0xf bank_mask:0xf bound_ctrl:1
	ds_read_b128 v[56:59], v2 offset:54016
	ds_read_b128 v[68:71], v22 offset:35328
	v_add_f32_dpp v38, v38, v38 quad_perm:[2,3,0,1] row_mask:0xf bank_mask:0xf bound_ctrl:1
	ds_read_b128 v[60:63], v2 offset:54272
	s_nop 0
	v_mov_b32_dpp v39, v38 row_ror:8 row_mask:0xf bank_mask:0xf bound_ctrl:1
	v_cvt_pk_bf16_f32 v47, v38, v39
	s_mov_b64 exec, s[2:3]
	global_store_dword v46, v47, s[14:15] offset:-4096
	s_mov_b64 exec, -1
	s_waitcnt lgkmcnt(4)
	v_pk_mul_f32 v[42:43], v[72:73], v[48:49] op_sel_hi:[1,0]
	v_pk_fma_f32 v[6:7], v[6:7], v[64:65], v[42:43] op_sel:[0,0,0] op_sel_hi:[1,0,1]
	v_pk_mul_f32 v[38:39], v[6:7], v[48:49] op_sel:[0,1] op_sel_hi:[1,1]
	v_pk_mul_f32 v[44:45], v[72:73], v[50:51] op_sel_hi:[1,0]
	v_pk_fma_f32 v[8:9], v[8:9], v[64:65], v[44:45] op_sel:[0,1,0] op_sel_hi:[1,1,1]
	v_pk_fma_f32 v[38:39], v[8:9], v[50:51], v[38:39] op_sel:[0,1,0] op_sel_hi:[1,1,1]
	s_waitcnt lgkmcnt(3)
	v_pk_mul_f32 v[42:43], v[72:73], v[52:53] op_sel_hi:[1,0]
	v_pk_fma_f32 v[10:11], v[10:11], v[66:67], v[42:43] op_sel:[0,0,0] op_sel_hi:[1,0,1]
	v_pk_fma_f32 v[38:39], v[10:11], v[52:53], v[38:39] op_sel:[0,1,0] op_sel_hi:[1,1,1]
	v_pk_mul_f32 v[44:45], v[72:73], v[54:55] op_sel_hi:[1,0]
	v_pk_fma_f32 v[12:13], v[12:13], v[66:67], v[44:45] op_sel:[0,1,0] op_sel_hi:[1,1,1]
	v_pk_fma_f32 v[38:39], v[12:13], v[54:55], v[38:39] op_sel:[0,1,0] op_sel_hi:[1,1,1]
	s_waitcnt lgkmcnt(1)
	v_pk_mul_f32 v[42:43], v[72:73], v[56:57] op_sel_hi:[1,0]
	v_pk_fma_f32 v[14:15], v[14:15], v[68:69], v[42:43] op_sel:[0,0,0] op_sel_hi:[1,0,1]
	v_pk_fma_f32 v[38:39], v[14:15], v[56:57], v[38:39] op_sel:[0,1,0] op_sel_hi:[1,1,1]
	v_pk_mul_f32 v[44:45], v[72:73], v[58:59] op_sel_hi:[1,0]
	v_pk_fma_f32 v[16:17], v[16:17], v[68:69], v[44:45] op_sel:[0,1,0] op_sel_hi:[1,1,1]
	v_pk_fma_f32 v[38:39], v[16:17], v[58:59], v[38:39] op_sel:[0,1,0] op_sel_hi:[1,1,1]
	s_waitcnt lgkmcnt(0)
	v_pk_mul_f32 v[42:43], v[72:73], v[60:61] op_sel_hi:[1,0]
	v_pk_fma_f32 v[18:19], v[18:19], v[70:71], v[42:43] op_sel:[0,0,0] op_sel_hi:[1,0,1]
	v_pk_fma_f32 v[38:39], v[18:19], v[60:61], v[38:39] op_sel:[0,1,0] op_sel_hi:[1,1,1]
	v_pk_mul_f32 v[44:45], v[72:73], v[62:63] op_sel_hi:[1,0]
	v_pk_fma_f32 v[20:21], v[20:21], v[70:71], v[44:45] op_sel:[0,1,0] op_sel_hi:[1,1,1]
	v_pk_fma_f32 v[38:39], v[20:21], v[62:63], v[38:39] op_sel:[0,1,0] op_sel_hi:[1,1,1]
	s_add_u32 s14, s14, 0x1000
	s_addc_u32 s15, s15, 0
	v_add_f32_dpp v38, v38, v38 row_ror:8 row_mask:0xf bank_mask:0x3 bound_ctrl:1
	v_add_f32_dpp v38, v39, v39 row_ror:8 row_mask:0xf bank_mask:0xc bound_ctrl:1
	ds_read_b64 v[104:105], v23 offset:38400
	ds_read_b128 v[80:83], v2 offset:54528
	v_add_f32_dpp v38, v38, v38 row_half_mirror row_mask:0xf bank_mask:0xf bound_ctrl:1
	ds_read_b128 v[96:99], v22 offset:35584
	ds_read_b128 v[84:87], v2 offset:54784
	v_add_f32_dpp v38, v38, v38 quad_perm:[1,0,3,2] row_mask:0xf bank_mask:0xf bound_ctrl:1
	ds_read_b128 v[88:91], v2 offset:55040
	ds_read_b128 v[100:103], v22 offset:35840
	v_add_f32_dpp v38, v38, v38 quad_perm:[2,3,0,1] row_mask:0xf bank_mask:0xf bound_ctrl:1
	ds_read_b128 v[92:95], v2 offset:55296
	s_nop 0
	v_mov_b32_dpp v39, v38 row_ror:8 row_mask:0xf bank_mask:0xf bound_ctrl:1
	v_cvt_pk_bf16_f32 v47, v38, v39
	s_mov_b64 exec, s[2:3]
	global_store_dword v46, v47, s[14:15] offset:-4096
	s_mov_b64 exec, -1
	s_waitcnt lgkmcnt(4)
	v_pk_mul_f32 v[42:43], v[104:105], v[80:81] op_sel_hi:[1,0]
	v_pk_fma_f32 v[6:7], v[6:7], v[96:97], v[42:43] op_sel:[0,0,0] op_sel_hi:[1,0,1]
	v_pk_mul_f32 v[38:39], v[6:7], v[80:81] op_sel:[0,1] op_sel_hi:[1,1]
	v_pk_mul_f32 v[44:45], v[104:105], v[82:83] op_sel_hi:[1,0]
	v_pk_fma_f32 v[8:9], v[8:9], v[96:97], v[44:45] op_sel:[0,1,0] op_sel_hi:[1,1,1]
	v_pk_fma_f32 v[38:39], v[8:9], v[82:83], v[38:39] op_sel:[0,1,0] op_sel_hi:[1,1,1]
	s_waitcnt lgkmcnt(3)
	v_pk_mul_f32 v[42:43], v[104:105], v[84:85] op_sel_hi:[1,0]
	v_pk_fma_f32 v[10:11], v[10:11], v[98:99], v[42:43] op_sel:[0,0,0] op_sel_hi:[1,0,1]
	v_pk_fma_f32 v[38:39], v[10:11], v[84:85], v[38:39] op_sel:[0,1,0] op_sel_hi:[1,1,1]
	v_pk_mul_f32 v[44:45], v[104:105], v[86:87] op_sel_hi:[1,0]
	v_pk_fma_f32 v[12:13], v[12:13], v[98:99], v[44:45] op_sel:[0,1,0] op_sel_hi:[1,1,1]
	v_pk_fma_f32 v[38:39], v[12:13], v[86:87], v[38:39] op_sel:[0,1,0] op_sel_hi:[1,1,1]
	s_waitcnt lgkmcnt(1)
	v_pk_mul_f32 v[42:43], v[104:105], v[88:89] op_sel_hi:[1,0]
	v_pk_fma_f32 v[14:15], v[14:15], v[100:101], v[42:43] op_sel:[0,0,0] op_sel_hi:[1,0,1]
	v_pk_fma_f32 v[38:39], v[14:15], v[88:89], v[38:39] op_sel:[0,1,0] op_sel_hi:[1,1,1]
	v_pk_mul_f32 v[44:45], v[104:105], v[90:91] op_sel_hi:[1,0]
	v_pk_fma_f32 v[16:17], v[16:17], v[100:101], v[44:45] op_sel:[0,1,0] op_sel_hi:[1,1,1]
	v_pk_fma_f32 v[38:39], v[16:17], v[90:91], v[38:39] op_sel:[0,1,0] op_sel_hi:[1,1,1]
	s_waitcnt lgkmcnt(0)
	v_pk_mul_f32 v[42:43], v[104:105], v[92:93] op_sel_hi:[1,0]
	v_pk_fma_f32 v[18:19], v[18:19], v[102:103], v[42:43] op_sel:[0,0,0] op_sel_hi:[1,0,1]
	v_pk_fma_f32 v[38:39], v[18:19], v[92:93], v[38:39] op_sel:[0,1,0] op_sel_hi:[1,1,1]
	v_pk_mul_f32 v[44:45], v[104:105], v[94:95] op_sel_hi:[1,0]
	v_pk_fma_f32 v[20:21], v[20:21], v[102:103], v[44:45] op_sel:[0,1,0] op_sel_hi:[1,1,1]
	v_pk_fma_f32 v[38:39], v[20:21], v[94:95], v[38:39] op_sel:[0,1,0] op_sel_hi:[1,1,1]
	s_add_u32 s14, s14, 0x1000
	s_addc_u32 s15, s15, 0
	v_add_f32_dpp v38, v38, v38 row_ror:8 row_mask:0xf bank_mask:0x3 bound_ctrl:1
	v_add_f32_dpp v38, v39, v39 row_ror:8 row_mask:0xf bank_mask:0xc bound_ctrl:1
	ds_read_b64 v[72:73], v23 offset:38656
	ds_read_b128 v[48:51], v2 offset:55552
	v_add_f32_dpp v38, v38, v38 row_half_mirror row_mask:0xf bank_mask:0xf bound_ctrl:1
	ds_read_b128 v[64:67], v22 offset:36096
	ds_read_b128 v[52:55], v2 offset:55808
	v_add_f32_dpp v38, v38, v38 quad_perm:[1,0,3,2] row_mask:0xf bank_mask:0xf bound_ctrl:1
	ds_read_b128 v[56:59], v2 offset:56064
	ds_read_b128 v[68:71], v22 offset:36352
	v_add_f32_dpp v38, v38, v38 quad_perm:[2,3,0,1] row_mask:0xf bank_mask:0xf bound_ctrl:1
	ds_read_b128 v[60:63], v2 offset:56320
	s_nop 0
	v_mov_b32_dpp v39, v38 row_ror:8 row_mask:0xf bank_mask:0xf bound_ctrl:1
	v_cvt_pk_bf16_f32 v47, v38, v39
	s_mov_b64 exec, s[2:3]
	global_store_dword v46, v47, s[14:15] offset:-4096
	s_mov_b64 exec, -1
	s_waitcnt lgkmcnt(4)
	v_pk_mul_f32 v[42:43], v[72:73], v[48:49] op_sel_hi:[1,0]
	v_pk_fma_f32 v[6:7], v[6:7], v[64:65], v[42:43] op_sel:[0,0,0] op_sel_hi:[1,0,1]
	v_pk_mul_f32 v[38:39], v[6:7], v[48:49] op_sel:[0,1] op_sel_hi:[1,1]
	v_pk_mul_f32 v[44:45], v[72:73], v[50:51] op_sel_hi:[1,0]
	v_pk_fma_f32 v[8:9], v[8:9], v[64:65], v[44:45] op_sel:[0,1,0] op_sel_hi:[1,1,1]
	v_pk_fma_f32 v[38:39], v[8:9], v[50:51], v[38:39] op_sel:[0,1,0] op_sel_hi:[1,1,1]
	s_waitcnt lgkmcnt(3)
	v_pk_mul_f32 v[42:43], v[72:73], v[52:53] op_sel_hi:[1,0]
	v_pk_fma_f32 v[10:11], v[10:11], v[66:67], v[42:43] op_sel:[0,0,0] op_sel_hi:[1,0,1]
	v_pk_fma_f32 v[38:39], v[10:11], v[52:53], v[38:39] op_sel:[0,1,0] op_sel_hi:[1,1,1]
	v_pk_mul_f32 v[44:45], v[72:73], v[54:55] op_sel_hi:[1,0]
	v_pk_fma_f32 v[12:13], v[12:13], v[66:67], v[44:45] op_sel:[0,1,0] op_sel_hi:[1,1,1]
	v_pk_fma_f32 v[38:39], v[12:13], v[54:55], v[38:39] op_sel:[0,1,0] op_sel_hi:[1,1,1]
	s_waitcnt lgkmcnt(1)
	v_pk_mul_f32 v[42:43], v[72:73], v[56:57] op_sel_hi:[1,0]
	v_pk_fma_f32 v[14:15], v[14:15], v[68:69], v[42:43] op_sel:[0,0,0] op_sel_hi:[1,0,1]
	v_pk_fma_f32 v[38:39], v[14:15], v[56:57], v[38:39] op_sel:[0,1,0] op_sel_hi:[1,1,1]
	v_pk_mul_f32 v[44:45], v[72:73], v[58:59] op_sel_hi:[1,0]
	v_pk_fma_f32 v[16:17], v[16:17], v[68:69], v[44:45] op_sel:[0,1,0] op_sel_hi:[1,1,1]
	v_pk_fma_f32 v[38:39], v[16:17], v[58:59], v[38:39] op_sel:[0,1,0] op_sel_hi:[1,1,1]
	s_waitcnt lgkmcnt(0)
	v_pk_mul_f32 v[42:43], v[72:73], v[60:61] op_sel_hi:[1,0]
	v_pk_fma_f32 v[18:19], v[18:19], v[70:71], v[42:43] op_sel:[0,0,0] op_sel_hi:[1,0,1]
	v_pk_fma_f32 v[38:39], v[18:19], v[60:61], v[38:39] op_sel:[0,1,0] op_sel_hi:[1,1,1]
	v_pk_mul_f32 v[44:45], v[72:73], v[62:63] op_sel_hi:[1,0]
	v_pk_fma_f32 v[20:21], v[20:21], v[70:71], v[44:45] op_sel:[0,1,0] op_sel_hi:[1,1,1]
	v_pk_fma_f32 v[38:39], v[20:21], v[62:63], v[38:39] op_sel:[0,1,0] op_sel_hi:[1,1,1]
	s_add_u32 s14, s14, 0x1000
	s_addc_u32 s15, s15, 0
	v_add_f32_dpp v38, v38, v38 row_ror:8 row_mask:0xf bank_mask:0x3 bound_ctrl:1
	v_add_f32_dpp v38, v39, v39 row_ror:8 row_mask:0xf bank_mask:0xc bound_ctrl:1
	ds_read_b64 v[104:105], v23 offset:38912
	ds_read_b128 v[80:83], v2 offset:56576
	v_add_f32_dpp v38, v38, v38 row_half_mirror row_mask:0xf bank_mask:0xf bound_ctrl:1
	ds_read_b128 v[96:99], v22 offset:36608
	ds_read_b128 v[84:87], v2 offset:56832
	v_add_f32_dpp v38, v38, v38 quad_perm:[1,0,3,2] row_mask:0xf bank_mask:0xf bound_ctrl:1
	ds_read_b128 v[88:91], v2 offset:57088
	ds_read_b128 v[100:103], v22 offset:36864
	v_add_f32_dpp v38, v38, v38 quad_perm:[2,3,0,1] row_mask:0xf bank_mask:0xf bound_ctrl:1
	ds_read_b128 v[92:95], v2 offset:57344
	s_nop 0
	v_mov_b32_dpp v39, v38 row_ror:8 row_mask:0xf bank_mask:0xf bound_ctrl:1
	v_cvt_pk_bf16_f32 v47, v38, v39
	s_mov_b64 exec, s[2:3]
	global_store_dword v46, v47, s[14:15] offset:-4096
	s_mov_b64 exec, -1
	s_waitcnt lgkmcnt(4)
	v_pk_mul_f32 v[42:43], v[104:105], v[80:81] op_sel_hi:[1,0]
	v_pk_fma_f32 v[6:7], v[6:7], v[96:97], v[42:43] op_sel:[0,0,0] op_sel_hi:[1,0,1]
	v_pk_mul_f32 v[38:39], v[6:7], v[80:81] op_sel:[0,1] op_sel_hi:[1,1]
	v_pk_mul_f32 v[44:45], v[104:105], v[82:83] op_sel_hi:[1,0]
	v_pk_fma_f32 v[8:9], v[8:9], v[96:97], v[44:45] op_sel:[0,1,0] op_sel_hi:[1,1,1]
	v_pk_fma_f32 v[38:39], v[8:9], v[82:83], v[38:39] op_sel:[0,1,0] op_sel_hi:[1,1,1]
	s_waitcnt lgkmcnt(3)
	v_pk_mul_f32 v[42:43], v[104:105], v[84:85] op_sel_hi:[1,0]
	v_pk_fma_f32 v[10:11], v[10:11], v[98:99], v[42:43] op_sel:[0,0,0] op_sel_hi:[1,0,1]
	v_pk_fma_f32 v[38:39], v[10:11], v[84:85], v[38:39] op_sel:[0,1,0] op_sel_hi:[1,1,1]
	v_pk_mul_f32 v[44:45], v[104:105], v[86:87] op_sel_hi:[1,0]
	v_pk_fma_f32 v[12:13], v[12:13], v[98:99], v[44:45] op_sel:[0,1,0] op_sel_hi:[1,1,1]
	v_pk_fma_f32 v[38:39], v[12:13], v[86:87], v[38:39] op_sel:[0,1,0] op_sel_hi:[1,1,1]
	s_waitcnt lgkmcnt(1)
	v_pk_mul_f32 v[42:43], v[104:105], v[88:89] op_sel_hi:[1,0]
	v_pk_fma_f32 v[14:15], v[14:15], v[100:101], v[42:43] op_sel:[0,0,0] op_sel_hi:[1,0,1]
	v_pk_fma_f32 v[38:39], v[14:15], v[88:89], v[38:39] op_sel:[0,1,0] op_sel_hi:[1,1,1]
	v_pk_mul_f32 v[44:45], v[104:105], v[90:91] op_sel_hi:[1,0]
	v_pk_fma_f32 v[16:17], v[16:17], v[100:101], v[44:45] op_sel:[0,1,0] op_sel_hi:[1,1,1]
	v_pk_fma_f32 v[38:39], v[16:17], v[90:91], v[38:39] op_sel:[0,1,0] op_sel_hi:[1,1,1]
	s_waitcnt lgkmcnt(0)
	v_pk_mul_f32 v[42:43], v[104:105], v[92:93] op_sel_hi:[1,0]
	v_pk_fma_f32 v[18:19], v[18:19], v[102:103], v[42:43] op_sel:[0,0,0] op_sel_hi:[1,0,1]
	v_pk_fma_f32 v[38:39], v[18:19], v[92:93], v[38:39] op_sel:[0,1,0] op_sel_hi:[1,1,1]
	v_pk_mul_f32 v[44:45], v[104:105], v[94:95] op_sel_hi:[1,0]
	v_pk_fma_f32 v[20:21], v[20:21], v[102:103], v[44:45] op_sel:[0,1,0] op_sel_hi:[1,1,1]
	v_pk_fma_f32 v[38:39], v[20:21], v[94:95], v[38:39] op_sel:[0,1,0] op_sel_hi:[1,1,1]
	s_add_u32 s14, s14, 0x1000
	s_addc_u32 s15, s15, 0
	v_add_f32_dpp v38, v38, v38 row_ror:8 row_mask:0xf bank_mask:0x3 bound_ctrl:1
	v_add_f32_dpp v38, v39, v39 row_ror:8 row_mask:0xf bank_mask:0xc bound_ctrl:1
	ds_read_b64 v[72:73], v3 offset:20736
	ds_read_b128 v[48:51], v2 offset:256
	v_add_f32_dpp v38, v38, v38 row_half_mirror row_mask:0xf bank_mask:0xf bound_ctrl:1
	ds_read_b128 v[64:67], v2 offset:16640
	ds_read_b128 v[52:55], v2 offset:512
	v_add_f32_dpp v38, v38, v38 quad_perm:[1,0,3,2] row_mask:0xf bank_mask:0xf bound_ctrl:1
	ds_read_b128 v[56:59], v2 offset:768
	ds_read_b128 v[68:71], v2 offset:16896
	v_add_f32_dpp v38, v38, v38 quad_perm:[2,3,0,1] row_mask:0xf bank_mask:0xf bound_ctrl:1
	ds_read_b128 v[60:63], v2 offset:1024
	s_nop 0
	v_mov_b32_dpp v39, v38 row_ror:8 row_mask:0xf bank_mask:0xf bound_ctrl:1
	v_cvt_pk_bf16_f32 v47, v38, v39
	s_mov_b64 exec, s[2:3]
	global_store_dword v46, v47, s[14:15] offset:-4096
	s_mov_b64 exec, -1
	s_waitcnt vmcnt(8)
	v_lshlrev_b32_e32 v144, 16, v110
	v_lshlrev_b32_e32 v145, 16, v111
	v_and_b32_e32 v146, s17, v110
	v_and_b32_e32 v147, s17, v111
	v_lshlrev_b32_e32 v148, 16, v112
	v_lshlrev_b32_e32 v149, 16, v113
	v_and_b32_e32 v150, s17, v112
	v_and_b32_e32 v151, s17, v113
	v_lshlrev_b32_e32 v152, 16, v114
	v_and_b32_e32 v153, s17, v114
	v_rcp_f32_e32 v25, v24
	v_mul_f32_e32 v149, v24, v149
	v_mul_f32_e32 v151, v24, v151
	v_mul_f32_e32 v145, 0x3db504f3, v145
	v_mul_f32_e32 v147, 0x3db504f3, v147
	v_cndmask_b32_e64 v27, 1.0, v25, s[20:21]
	v_mul_f32_e32 v24, v24, v26
	v_mul_f32_e32 v152, v27, v152
	v_mul_f32_e32 v153, v27, v153
	ds_write_b128 v29, v[144:147] offset:24832
	ds_write_b128 v29, v[148:151] offset:33024
	ds_write_b64 v30, v[116:117] offset:24832
	ds_write_b64 v31, v[152:153] offset:24832
	s_add_i32 s16, s16, 8
	s_waitcnt lgkmcnt(0)
	s_barrier
	s_cmpk_lt_u32 s16, 0x800
	s_cbranch_scc1 .Lgla2_loop
